# GEMM K-loops: remaining M0->DMA wait-state nops replaced by the segment's last ds_read
# baseline (speedup 1.0000x reference)
.LBB0_34:
	ds_read_b128 v[164:167], v151
	ds_read_b128 v[168:171], v151 offset:1024
	ds_read_b128 v[172:175], v151 offset:2048
	ds_read_b128 v[176:179], v151 offset:3072
	v_lshl_add_u64 v[204:205], v[138:139], 0, s[12:13]
	v_lshl_add_u64 v[228:229], v[204:205], 0, s[60:61]
	s_add_i32 m0, s1, 0xc000
	ds_read_b128 v[180:183], v0
	ds_read_b128 v[184:187], v0 offset:1024
	ds_read_b128 v[188:191], v0 offset:2048
	ds_read_b128 v[192:195], v0 offset:3072
	ds_read_b128 v[196:199], v0 offset:4096
	ds_read_b128 v[200:203], v0 offset:5120
	ds_read_b128 v[222:225], v0 offset:6144
	ds_read_b128 v[232:235], v0 offset:7168
	global_load_lds_dwordx4 v[228:229], off
	v_lshl_add_u64 v[210:211], v[140:141], 0, s[12:13]
	s_add_i32 m0, s1, 0xe000
	v_lshl_add_u64 v[152:153], v[210:211], 0, s[60:61]
	global_load_lds_dwordx4 v[152:153], off
	s_waitcnt lgkmcnt(8)
	s_barrier
	s_waitcnt lgkmcnt(0)
	v_mfma_f32_16x16x32_bf16 v[126:129], v[164:167], v[180:183], v[126:129]
	v_mfma_f32_16x16x32_bf16 v[122:125], v[172:175], v[180:183], v[122:125]
	v_mfma_f32_16x16x32_bf16 v[118:121], v[164:167], v[188:191], v[118:121]
	v_mfma_f32_16x16x32_bf16 v[114:117], v[172:175], v[188:191], v[114:117]
	v_mfma_f32_16x16x32_bf16 v[110:113], v[164:167], v[196:199], v[110:113]
	v_mfma_f32_16x16x32_bf16 v[106:109], v[172:175], v[196:199], v[106:109]
	v_mfma_f32_16x16x32_bf16 v[102:105], v[164:167], v[222:225], v[102:105]
	v_mfma_f32_16x16x32_bf16 v[98:101], v[172:175], v[222:225], v[98:101]
	v_mfma_f32_16x16x32_bf16 v[126:129], v[168:171], v[184:187], v[126:129]
	v_mfma_f32_16x16x32_bf16 v[122:125], v[176:179], v[184:187], v[122:125]
	v_mfma_f32_16x16x32_bf16 v[118:121], v[168:171], v[192:195], v[118:121]
	v_mfma_f32_16x16x32_bf16 v[114:117], v[176:179], v[192:195], v[114:117]
	v_mfma_f32_16x16x32_bf16 v[110:113], v[168:171], v[200:203], v[110:113]
	v_mfma_f32_16x16x32_bf16 v[106:109], v[176:179], v[200:203], v[106:109]
	v_mfma_f32_16x16x32_bf16 v[102:105], v[168:171], v[232:235], v[102:105]
	v_mfma_f32_16x16x32_bf16 v[98:101], v[176:179], v[232:235], v[98:101]
	s_barrier
	v_lshl_add_u64 v[216:217], v[134:135], 0, s[12:13]
	s_add_i32 m0, s1, 0xff00
	ds_read_b128 v[236:239], v151 offset:16384
	ds_read_b128 v[240:243], v151 offset:17408
	ds_read_b128 v[244:247], v151 offset:18432
	ds_read_b128 v[248:251], v151 offset:19456
	global_load_lds_dwordx4 v[216:217], off offset:256
	s_add_i32 m0, s1, 0x11f00
	v_lshl_add_u64 v[218:219], v[136:137], 0, s[12:13]
	global_load_lds_dwordx4 v[218:219], off offset:256
	s_barrier
	s_waitcnt lgkmcnt(0)
	v_mfma_f32_16x16x32_bf16 v[94:97], v[236:239], v[180:183], v[94:97]
	v_mfma_f32_16x16x32_bf16 v[90:93], v[244:247], v[180:183], v[90:93]
	v_mfma_f32_16x16x32_bf16 v[86:89], v[236:239], v[188:191], v[86:89]
	v_mfma_f32_16x16x32_bf16 v[70:73], v[244:247], v[188:191], v[70:73]
	v_mfma_f32_16x16x32_bf16 v[62:65], v[236:239], v[196:199], v[62:65]
	v_mfma_f32_16x16x32_bf16 v[58:61], v[244:247], v[196:199], v[58:61]
	v_mfma_f32_16x16x32_bf16 v[54:57], v[236:239], v[222:225], v[54:57]
	v_mfma_f32_16x16x32_bf16 v[50:53], v[244:247], v[222:225], v[50:53]
	v_mfma_f32_16x16x32_bf16 v[94:97], v[240:243], v[184:187], v[94:97]
	v_mfma_f32_16x16x32_bf16 v[90:93], v[248:251], v[184:187], v[90:93]
	v_mfma_f32_16x16x32_bf16 v[86:89], v[240:243], v[192:195], v[86:89]
	v_mfma_f32_16x16x32_bf16 v[70:73], v[248:251], v[192:195], v[70:73]
	v_mfma_f32_16x16x32_bf16 v[62:65], v[240:243], v[200:203], v[62:65]
	v_mfma_f32_16x16x32_bf16 v[58:61], v[248:251], v[200:203], v[58:61]
	v_mfma_f32_16x16x32_bf16 v[54:57], v[240:243], v[232:235], v[54:57]
	v_mfma_f32_16x16x32_bf16 v[50:53], v[248:251], v[232:235], v[50:53]
	v_lshl_add_u64 v[158:159], v[204:205], 0, s[74:75]
	s_mov_b32 m0, s1
	s_barrier
	ds_read_b128 v[180:183], v0 offset:16384
	ds_read_b128 v[184:187], v0 offset:17408
	ds_read_b128 v[188:191], v0 offset:18432
	ds_read_b128 v[192:195], v0 offset:19456
	ds_read_b128 v[196:199], v0 offset:20480
	ds_read_b128 v[200:203], v0 offset:21504
	ds_read_b128 v[222:225], v0 offset:22528
	global_load_lds_dwordx4 v[158:159], off
	s_add_i32 m0, s1, 0x1f00
	ds_read_b128 v[232:235], v0 offset:23552
	global_load_lds_dwordx4 v[210:211], off offset:256
	s_barrier
	s_waitcnt lgkmcnt(0)
	v_mfma_f32_16x16x32_bf16 v[46:49], v[164:167], v[180:183], v[46:49]
	v_mfma_f32_16x16x32_bf16 v[42:45], v[172:175], v[180:183], v[42:45]
	v_mfma_f32_16x16x32_bf16 v[38:41], v[164:167], v[188:191], v[38:41]
	v_mfma_f32_16x16x32_bf16 v[34:37], v[172:175], v[188:191], v[34:37]
	v_mfma_f32_16x16x32_bf16 v[30:33], v[164:167], v[196:199], v[30:33]
	v_mfma_f32_16x16x32_bf16 v[26:29], v[172:175], v[196:199], v[26:29]
	v_mfma_f32_16x16x32_bf16 v[22:25], v[164:167], v[222:225], v[22:25]
	v_mfma_f32_16x16x32_bf16 v[18:21], v[172:175], v[222:225], v[18:21]
	v_mfma_f32_16x16x32_bf16 v[46:49], v[168:171], v[184:187], v[46:49]
	v_mfma_f32_16x16x32_bf16 v[42:45], v[176:179], v[184:187], v[42:45]
	v_mfma_f32_16x16x32_bf16 v[38:41], v[168:171], v[192:195], v[38:41]
	v_mfma_f32_16x16x32_bf16 v[34:37], v[176:179], v[192:195], v[34:37]
	v_mfma_f32_16x16x32_bf16 v[30:33], v[168:171], v[200:203], v[30:33]
	v_mfma_f32_16x16x32_bf16 v[26:29], v[176:179], v[200:203], v[26:29]
	v_mfma_f32_16x16x32_bf16 v[22:25], v[168:171], v[232:235], v[22:25]
	v_mfma_f32_16x16x32_bf16 v[18:21], v[176:179], v[232:235], v[18:21]
	s_barrier
	s_add_i32 m0, s1, 0x14000
	v_lshl_add_u64 v[154:155], v[216:217], 0, s[18:19]
	global_load_lds_dwordx4 v[154:155], off
	s_add_i32 m0, s1, 0x16000
	v_lshl_add_u64 v[156:157], v[218:219], 0, s[18:19]
	global_load_lds_dwordx4 v[156:157], off
	s_waitcnt vmcnt(6)
	s_barrier
	v_mfma_f32_16x16x32_bf16 v[14:17], v[236:239], v[180:183], v[14:17]
	v_mfma_f32_16x16x32_bf16 v[10:13], v[244:247], v[180:183], v[10:13]
	v_mfma_f32_16x16x32_bf16 v[6:9], v[236:239], v[188:191], v[6:9]
	v_mfma_f32_16x16x32_bf16 v[2:5], v[244:247], v[188:191], v[2:5]
	v_mfma_f32_16x16x32_bf16 v[66:69], v[236:239], v[196:199], v[66:69]
	v_mfma_f32_16x16x32_bf16 v[74:77], v[244:247], v[196:199], v[74:77]
	v_mfma_f32_16x16x32_bf16 v[78:81], v[236:239], v[222:225], v[78:81]
	v_mfma_f32_16x16x32_bf16 v[82:85], v[244:247], v[222:225], v[82:85]
	v_mfma_f32_16x16x32_bf16 v[14:17], v[240:243], v[184:187], v[14:17]
	v_mfma_f32_16x16x32_bf16 v[10:13], v[248:251], v[184:187], v[10:13]
	v_mfma_f32_16x16x32_bf16 v[6:9], v[240:243], v[192:195], v[6:9]
	v_mfma_f32_16x16x32_bf16 v[2:5], v[248:251], v[192:195], v[2:5]
	v_mfma_f32_16x16x32_bf16 v[66:69], v[240:243], v[200:203], v[66:69]
	v_mfma_f32_16x16x32_bf16 v[74:77], v[248:251], v[200:203], v[74:77]
	v_mfma_f32_16x16x32_bf16 v[78:81], v[240:243], v[232:235], v[78:81]
	v_mfma_f32_16x16x32_bf16 v[82:85], v[248:251], v[232:235], v[82:85]
	s_barrier
	ds_read_b128 v[164:167], v151 offset:32768
	ds_read_b128 v[168:171], v151 offset:33792
	ds_read_b128 v[172:175], v151 offset:34816
	ds_read_b128 v[176:179], v151 offset:35840
	s_add_i32 m0, s1, 0x3f80
	ds_read_b128 v[180:183], v0 offset:32768
	ds_read_b128 v[184:187], v0 offset:33792
	ds_read_b128 v[188:191], v0 offset:34816
	ds_read_b128 v[192:195], v0 offset:35840
	ds_read_b128 v[196:199], v0 offset:36864
	ds_read_b128 v[200:203], v0 offset:37888
	ds_read_b128 v[222:225], v0 offset:38912
	global_load_lds_dwordx4 v[228:229], off offset:128
	s_add_i32 m0, s1, 0x5f80
	ds_read_b128 v[232:235], v0 offset:39936
	global_load_lds_dwordx4 v[152:153], off offset:128
	s_waitcnt lgkmcnt(8)
	s_barrier
	s_waitcnt lgkmcnt(0)
	v_mfma_f32_16x16x32_bf16 v[126:129], v[164:167], v[180:183], v[126:129]
	v_mfma_f32_16x16x32_bf16 v[122:125], v[172:175], v[180:183], v[122:125]
	v_mfma_f32_16x16x32_bf16 v[118:121], v[164:167], v[188:191], v[118:121]
	v_mfma_f32_16x16x32_bf16 v[114:117], v[172:175], v[188:191], v[114:117]
	v_mfma_f32_16x16x32_bf16 v[110:113], v[164:167], v[196:199], v[110:113]
	v_mfma_f32_16x16x32_bf16 v[106:109], v[172:175], v[196:199], v[106:109]
	v_mfma_f32_16x16x32_bf16 v[102:105], v[164:167], v[222:225], v[102:105]
	v_mfma_f32_16x16x32_bf16 v[98:101], v[172:175], v[222:225], v[98:101]
	v_mfma_f32_16x16x32_bf16 v[126:129], v[168:171], v[184:187], v[126:129]
	v_mfma_f32_16x16x32_bf16 v[122:125], v[176:179], v[184:187], v[122:125]
	v_mfma_f32_16x16x32_bf16 v[118:121], v[168:171], v[192:195], v[118:121]
	v_mfma_f32_16x16x32_bf16 v[114:117], v[176:179], v[192:195], v[114:117]
	v_mfma_f32_16x16x32_bf16 v[110:113], v[168:171], v[200:203], v[110:113]
	v_mfma_f32_16x16x32_bf16 v[106:109], v[176:179], v[200:203], v[106:109]
	v_mfma_f32_16x16x32_bf16 v[102:105], v[168:171], v[232:235], v[102:105]
	v_mfma_f32_16x16x32_bf16 v[98:101], v[176:179], v[232:235], v[98:101]
	s_barrier
	s_add_i32 m0, s1, 0x17e80
	ds_read_b128 v[236:239], v151 offset:49152
	ds_read_b128 v[240:243], v151 offset:50176
	ds_read_b128 v[244:247], v151 offset:51200
	global_load_lds_dwordx4 v[216:217], off offset:384
	s_add_i32 m0, s1, 0x19e80
	ds_read_b128 v[248:251], v151 offset:52224
	global_load_lds_dwordx4 v[218:219], off offset:384
	s_barrier
	s_waitcnt lgkmcnt(0)
	v_mfma_f32_16x16x32_bf16 v[94:97], v[236:239], v[180:183], v[94:97]
	v_mfma_f32_16x16x32_bf16 v[90:93], v[244:247], v[180:183], v[90:93]
	v_mfma_f32_16x16x32_bf16 v[86:89], v[236:239], v[188:191], v[86:89]
	v_mfma_f32_16x16x32_bf16 v[70:73], v[244:247], v[188:191], v[70:73]
	v_mfma_f32_16x16x32_bf16 v[62:65], v[236:239], v[196:199], v[62:65]
	v_mfma_f32_16x16x32_bf16 v[58:61], v[244:247], v[196:199], v[58:61]
	v_mfma_f32_16x16x32_bf16 v[54:57], v[236:239], v[222:225], v[54:57]
	v_mfma_f32_16x16x32_bf16 v[50:53], v[244:247], v[222:225], v[50:53]
	v_mfma_f32_16x16x32_bf16 v[94:97], v[240:243], v[184:187], v[94:97]
	v_mfma_f32_16x16x32_bf16 v[90:93], v[248:251], v[184:187], v[90:93]
	v_mfma_f32_16x16x32_bf16 v[86:89], v[240:243], v[192:195], v[86:89]
	v_mfma_f32_16x16x32_bf16 v[70:73], v[248:251], v[192:195], v[70:73]
	v_mfma_f32_16x16x32_bf16 v[62:65], v[240:243], v[200:203], v[62:65]
	v_mfma_f32_16x16x32_bf16 v[58:61], v[248:251], v[200:203], v[58:61]
	v_mfma_f32_16x16x32_bf16 v[54:57], v[240:243], v[232:235], v[54:57]
	v_mfma_f32_16x16x32_bf16 v[50:53], v[248:251], v[232:235], v[50:53]
	s_add_i32 m0, s1, 0x7e80
	s_barrier
	ds_read_b128 v[180:183], v0 offset:49152
	ds_read_b128 v[184:187], v0 offset:50176
	ds_read_b128 v[188:191], v0 offset:51200
	ds_read_b128 v[192:195], v0 offset:52224
	ds_read_b128 v[196:199], v0 offset:53248
	ds_read_b128 v[200:203], v0 offset:54272
	ds_read_b128 v[222:225], v0 offset:55296
	global_load_lds_dwordx4 v[204:205], off offset:384
	s_add_i32 m0, s1, 0x9e80
	ds_read_b128 v[232:235], v0 offset:56320
	global_load_lds_dwordx4 v[210:211], off offset:384
	s_barrier
	s_waitcnt lgkmcnt(0)
	v_mfma_f32_16x16x32_bf16 v[46:49], v[164:167], v[180:183], v[46:49]
	v_mfma_f32_16x16x32_bf16 v[42:45], v[172:175], v[180:183], v[42:45]
	v_mfma_f32_16x16x32_bf16 v[38:41], v[164:167], v[188:191], v[38:41]
	v_mfma_f32_16x16x32_bf16 v[34:37], v[172:175], v[188:191], v[34:37]
	v_mfma_f32_16x16x32_bf16 v[30:33], v[164:167], v[196:199], v[30:33]
	v_mfma_f32_16x16x32_bf16 v[26:29], v[172:175], v[196:199], v[26:29]
	v_mfma_f32_16x16x32_bf16 v[22:25], v[164:167], v[222:225], v[22:25]
	v_mfma_f32_16x16x32_bf16 v[18:21], v[172:175], v[222:225], v[18:21]
	v_mfma_f32_16x16x32_bf16 v[46:49], v[168:171], v[184:187], v[46:49]
	v_mfma_f32_16x16x32_bf16 v[42:45], v[176:179], v[184:187], v[42:45]
	v_mfma_f32_16x16x32_bf16 v[38:41], v[168:171], v[192:195], v[38:41]
	v_mfma_f32_16x16x32_bf16 v[34:37], v[176:179], v[192:195], v[34:37]
	v_mfma_f32_16x16x32_bf16 v[30:33], v[168:171], v[200:203], v[30:33]
	v_mfma_f32_16x16x32_bf16 v[26:29], v[176:179], v[200:203], v[26:29]
	v_mfma_f32_16x16x32_bf16 v[22:25], v[168:171], v[232:235], v[22:25]
	v_mfma_f32_16x16x32_bf16 v[18:21], v[176:179], v[232:235], v[18:21]
	s_barrier
	s_add_i32 m0, s1, 0x1bf80
	s_nop 0
	global_load_lds_dwordx4 v[154:155], off offset:128
	s_add_i32 m0, s1, 0x1df80
	s_nop 0
	global_load_lds_dwordx4 v[156:157], off offset:128
	s_waitcnt vmcnt(6)
	s_barrier
	v_mfma_f32_16x16x32_bf16 v[14:17], v[236:239], v[180:183], v[14:17]
	v_mfma_f32_16x16x32_bf16 v[10:13], v[244:247], v[180:183], v[10:13]
	v_mfma_f32_16x16x32_bf16 v[6:9], v[236:239], v[188:191], v[6:9]
	v_mfma_f32_16x16x32_bf16 v[2:5], v[244:247], v[188:191], v[2:5]
	v_mfma_f32_16x16x32_bf16 v[66:69], v[236:239], v[196:199], v[66:69]
	v_mfma_f32_16x16x32_bf16 v[74:77], v[244:247], v[196:199], v[74:77]
	v_mfma_f32_16x16x32_bf16 v[78:81], v[236:239], v[222:225], v[78:81]
	v_mfma_f32_16x16x32_bf16 v[82:85], v[244:247], v[222:225], v[82:85]
	v_mfma_f32_16x16x32_bf16 v[14:17], v[240:243], v[184:187], v[14:17]
	v_mfma_f32_16x16x32_bf16 v[10:13], v[248:251], v[184:187], v[10:13]
	v_mfma_f32_16x16x32_bf16 v[6:9], v[240:243], v[192:195], v[6:9]
	v_mfma_f32_16x16x32_bf16 v[2:5], v[248:251], v[192:195], v[2:5]
	v_mfma_f32_16x16x32_bf16 v[66:69], v[240:243], v[200:203], v[66:69]
	v_mfma_f32_16x16x32_bf16 v[74:77], v[248:251], v[200:203], v[74:77]
	v_mfma_f32_16x16x32_bf16 v[78:81], v[240:243], v[232:235], v[78:81]
	v_mfma_f32_16x16x32_bf16 v[82:85], v[248:251], v[232:235], v[82:85]
	s_add_i32 s0, s0, 2
	s_add_u32 s12, s12, 0x100
	s_addc_u32 s13, s13, 0
	s_cmp_lt_u32 s0, 28
	s_barrier
	s_cbranch_scc1 .LBB0_34
	s_add_i32 s1, s1, 0x1e000
	s_mov_b64 s[12:13], 0xf80
	v_readfirstlane_b32 s0, v162
	v_lshl_add_u64 v[132:133], v[132:133], 0, s[12:13]
	s_mov_b32 m0, s0
	v_readfirstlane_b32 s0, v163
	ds_read_b128 v[134:137], v151
	ds_read_b128 v[138:141], v151 offset:1024
	ds_read_b128 v[152:155], v151 offset:2048
	ds_read_b128 v[156:159], v151 offset:3072
	ds_read_b128 v[164:167], v0
	ds_read_b128 v[168:171], v0 offset:1024
	ds_read_b128 v[172:175], v0 offset:2048
	ds_read_b128 v[176:179], v0 offset:3072
	ds_read_b128 v[180:183], v0 offset:4096
	ds_read_b128 v[184:187], v0 offset:5120
	ds_read_b128 v[188:191], v0 offset:6144
	ds_read_b128 v[192:195], v0 offset:7168
	global_load_lds_dwordx4 v[132:133], off
	v_lshl_add_u64 v[130:131], v[130:131], 0, s[12:13]
	s_mov_b32 m0, s0
	s_nop 0
	global_load_lds_dwordx4 v[130:131], off
	s_barrier
	s_waitcnt lgkmcnt(0)
	s_setprio 1
	s_waitcnt lgkmcnt(0)
	v_mfma_f32_16x16x32_bf16 v[122:125], v[152:155], v[164:167], v[122:125]
	v_mfma_f32_16x16x32_bf16 v[118:121], v[134:137], v[172:175], v[118:121]
	v_mfma_f32_16x16x32_bf16 v[114:117], v[152:155], v[172:175], v[114:117]
	v_mfma_f32_16x16x32_bf16 v[102:105], v[134:137], v[188:191], v[102:105]
	v_mfma_f32_16x16x32_bf16 v[98:101], v[152:155], v[188:191], v[98:101]
	v_mfma_f32_16x16x32_bf16 v[126:129], v[134:137], v[164:167], v[126:129]
	v_mfma_f32_16x16x32_bf16 v[122:125], v[156:159], v[168:171], v[122:125]
	v_mfma_f32_16x16x32_bf16 v[118:121], v[138:141], v[176:179], v[118:121]
	v_mfma_f32_16x16x32_bf16 v[114:117], v[156:159], v[176:179], v[114:117]
	v_mfma_f32_16x16x32_bf16 v[110:113], v[134:137], v[180:183], v[110:113]
	v_mfma_f32_16x16x32_bf16 v[106:109], v[152:155], v[180:183], v[106:109]
	v_mfma_f32_16x16x32_bf16 v[102:105], v[138:141], v[192:195], v[102:105]
	v_mfma_f32_16x16x32_bf16 v[98:101], v[156:159], v[192:195], v[98:101]
	v_mfma_f32_16x16x32_bf16 v[126:129], v[138:141], v[168:171], v[126:129]
	v_mfma_f32_16x16x32_bf16 v[130:133], v[138:141], v[184:187], v[110:113]
	v_mfma_f32_16x16x32_bf16 v[160:163], v[156:159], v[184:187], v[106:109]
	s_setprio 0
	s_barrier
	ds_read_b128 v[106:109], v151 offset:16384
	ds_read_b128 v[110:113], v151 offset:17408
	ds_read_b128 v[196:199], v151 offset:18432
	ds_read_b128 v[200:203], v151 offset:19456
	s_barrier
	s_waitcnt lgkmcnt(0)
	s_setprio 1
	s_waitcnt lgkmcnt(3)
	v_mfma_f32_16x16x32_bf16 v[86:89], v[106:109], v[172:175], v[86:89]
	s_waitcnt lgkmcnt(1)
	v_mfma_f32_16x16x32_bf16 v[70:73], v[196:199], v[172:175], v[70:73]
	v_mfma_f32_16x16x32_bf16 v[62:65], v[106:109], v[180:183], v[62:65]
	v_mfma_f32_16x16x32_bf16 v[58:61], v[196:199], v[180:183], v[58:61]
	v_mfma_f32_16x16x32_bf16 v[54:57], v[106:109], v[188:191], v[54:57]
	v_mfma_f32_16x16x32_bf16 v[50:53], v[196:199], v[188:191], v[50:53]
	v_mfma_f32_16x16x32_bf16 v[94:97], v[106:109], v[164:167], v[94:97]
	v_mfma_f32_16x16x32_bf16 v[90:93], v[196:199], v[164:167], v[90:93]
	v_mfma_f32_16x16x32_bf16 v[86:89], v[110:113], v[176:179], v[86:89]
	s_waitcnt lgkmcnt(0)
	v_mfma_f32_16x16x32_bf16 v[70:73], v[200:203], v[176:179], v[70:73]
	v_mfma_f32_16x16x32_bf16 v[62:65], v[110:113], v[184:187], v[62:65]
	v_mfma_f32_16x16x32_bf16 v[58:61], v[200:203], v[184:187], v[58:61]
	v_mfma_f32_16x16x32_bf16 v[54:57], v[110:113], v[192:195], v[54:57]
	v_mfma_f32_16x16x32_bf16 v[50:53], v[200:203], v[192:195], v[50:53]
	v_mfma_f32_16x16x32_bf16 v[222:225], v[110:113], v[168:171], v[94:97]
	v_mfma_f32_16x16x32_bf16 v[164:167], v[200:203], v[168:171], v[90:93]
	s_setprio 0
	s_barrier
	s_nop 0
	ds_read_b128 v[90:93], v0 offset:16384
	ds_read_b128 v[94:97], v0 offset:17408
	ds_read_b128 v[168:171], v0 offset:18432
	ds_read_b128 v[172:175], v0 offset:19456
	ds_read_b128 v[176:179], v0 offset:20480
	ds_read_b128 v[180:183], v0 offset:21504
	ds_read_b128 v[184:187], v0 offset:22528
	ds_read_b128 v[188:191], v0 offset:23552
	s_waitcnt vmcnt(4)
	s_barrier
	s_waitcnt lgkmcnt(0)
	s_setprio 1
	s_waitcnt lgkmcnt(7)
	v_mfma_f32_16x16x32_bf16 v[46:49], v[134:137], v[90:93], v[46:49]
	v_mfma_f32_16x16x32_bf16 v[42:45], v[152:155], v[90:93], v[42:45]
	s_waitcnt lgkmcnt(5)
	v_mfma_f32_16x16x32_bf16 v[38:41], v[134:137], v[168:171], v[38:41]
	v_mfma_f32_16x16x32_bf16 v[34:37], v[152:155], v[168:171], v[34:37]
	s_waitcnt lgkmcnt(3)
	v_mfma_f32_16x16x32_bf16 v[30:33], v[134:137], v[176:179], v[30:33]
	v_mfma_f32_16x16x32_bf16 v[26:29], v[152:155], v[176:179], v[26:29]
	s_waitcnt lgkmcnt(1)
	v_mfma_f32_16x16x32_bf16 v[22:25], v[134:137], v[184:187], v[22:25]
	v_mfma_f32_16x16x32_bf16 v[18:21], v[152:155], v[184:187], v[18:21]
	v_mfma_f32_16x16x32_bf16 v[46:49], v[138:141], v[94:97], v[46:49]
	v_mfma_f32_16x16x32_bf16 v[42:45], v[156:159], v[94:97], v[42:45]
	v_mfma_f32_16x16x32_bf16 v[38:41], v[138:141], v[172:175], v[38:41]
	v_mfma_f32_16x16x32_bf16 v[34:37], v[156:159], v[172:175], v[34:37]
	v_mfma_f32_16x16x32_bf16 v[30:33], v[138:141], v[180:183], v[30:33]
	v_mfma_f32_16x16x32_bf16 v[26:29], v[156:159], v[180:183], v[26:29]
	s_waitcnt lgkmcnt(0)
	v_mfma_f32_16x16x32_bf16 v[22:25], v[138:141], v[188:191], v[22:25]
	v_mfma_f32_16x16x32_bf16 v[18:21], v[156:159], v[188:191], v[18:21]
	s_setprio 0
	s_setprio 1
	v_mfma_f32_16x16x32_bf16 v[10:13], v[196:199], v[90:93], v[10:13]
	v_mfma_f32_16x16x32_bf16 v[152:155], v[200:203], v[94:97], v[10:13]
	v_mfma_f32_16x16x32_bf16 v[10:13], v[106:109], v[176:179], v[66:69]
	v_mfma_f32_16x16x32_bf16 v[156:159], v[110:113], v[180:183], v[10:13]
	v_mfma_f32_16x16x32_bf16 v[10:13], v[196:199], v[176:179], v[74:77]
	v_mfma_f32_16x16x32_bf16 v[6:9], v[106:109], v[168:171], v[6:9]
	v_mfma_f32_16x16x32_bf16 v[2:5], v[196:199], v[168:171], v[2:5]
	v_mfma_f32_16x16x32_bf16 v[168:171], v[200:203], v[180:183], v[10:13]
	v_mfma_f32_16x16x32_bf16 v[10:13], v[106:109], v[184:187], v[78:81]
	v_mfma_f32_16x16x32_bf16 v[14:17], v[106:109], v[90:93], v[14:17]
	v_mfma_f32_16x16x32_bf16 v[6:9], v[110:113], v[172:175], v[6:9]
	v_mfma_f32_16x16x32_bf16 v[2:5], v[200:203], v[172:175], v[2:5]
	v_mfma_f32_16x16x32_bf16 v[172:175], v[110:113], v[188:191], v[10:13]
	v_mfma_f32_16x16x32_bf16 v[10:13], v[196:199], v[184:187], v[82:85]
	v_mfma_f32_16x16x32_bf16 v[134:137], v[110:113], v[94:97], v[14:17]
	v_mfma_f32_16x16x32_bf16 v[176:179], v[200:203], v[188:191], v[10:13]
	s_setprio 0
	s_barrier
	s_nop 3
	ds_read_b128 v[10:13], v151 offset:32768
	ds_read_b128 v[14:17], v151 offset:33792
	ds_read_b128 v[180:183], v151 offset:34816
	ds_read_b128 v[184:187], v151 offset:35840
	ds_read_b128 v[66:69], v0 offset:32768
	ds_read_b128 v[82:85], v0 offset:33792
	ds_read_b128 v[188:191], v0 offset:34816
	ds_read_b128 v[192:195], v0 offset:35840
	ds_read_b128 v[196:199], v0 offset:36864
	ds_read_b128 v[200:203], v0 offset:37888
	ds_read_b128 v[232:235], v0 offset:38912
	ds_read_b128 v[236:239], v0 offset:39936
	s_waitcnt vmcnt(2)
	s_barrier
	s_waitcnt lgkmcnt(0)
	s_setprio 1
	s_waitcnt lgkmcnt(7)
	v_mfma_f32_16x16x32_bf16 v[74:77], v[10:13], v[66:69], v[126:129]
	s_waitcnt lgkmcnt(6)
	v_mfma_f32_16x16x32_bf16 v[138:141], v[14:17], v[82:85], v[74:77]
	v_mfma_f32_16x16x32_bf16 v[74:77], v[180:183], v[66:69], v[122:125]
	v_mfma_f32_16x16x32_bf16 v[122:125], v[184:187], v[82:85], v[74:77]
	s_waitcnt lgkmcnt(5)
	v_mfma_f32_16x16x32_bf16 v[74:77], v[10:13], v[188:191], v[118:121]
	s_waitcnt lgkmcnt(4)
	v_mfma_f32_16x16x32_bf16 v[110:113], v[14:17], v[192:195], v[74:77]
	v_mfma_f32_16x16x32_bf16 v[74:77], v[180:183], v[188:191], v[114:117]
	v_mfma_f32_16x16x32_bf16 v[106:109], v[184:187], v[192:195], v[74:77]
	s_waitcnt lgkmcnt(3)
	v_mfma_f32_16x16x32_bf16 v[74:77], v[10:13], v[196:199], v[130:133]
	s_waitcnt lgkmcnt(2)
	v_mfma_f32_16x16x32_bf16 v[94:97], v[14:17], v[200:203], v[74:77]
	v_mfma_f32_16x16x32_bf16 v[74:77], v[180:183], v[196:199], v[160:163]
	v_mfma_f32_16x16x32_bf16 v[90:93], v[184:187], v[200:203], v[74:77]
	s_waitcnt lgkmcnt(1)
	v_mfma_f32_16x16x32_bf16 v[74:77], v[10:13], v[232:235], v[102:105]
	s_waitcnt lgkmcnt(0)
	v_mfma_f32_16x16x32_bf16 v[78:81], v[14:17], v[236:239], v[74:77]
	v_mfma_f32_16x16x32_bf16 v[74:77], v[180:183], v[232:235], v[98:101]
	v_mfma_f32_16x16x32_bf16 v[74:77], v[184:187], v[236:239], v[74:77]
	s_setprio 0
	s_barrier
	ds_read_b128 v[126:129], v151 offset:49152
	ds_read_b128 v[130:133], v151 offset:50176
	ds_read_b128 v[160:163], v151 offset:51200
	ds_read_b128 v[148:151], v151 offset:52224
	s_waitcnt vmcnt(0)
	s_barrier
	s_waitcnt lgkmcnt(0)
	s_setprio 1
	s_waitcnt lgkmcnt(3)
	v_mfma_f32_16x16x32_bf16 v[98:101], v[126:129], v[66:69], v[222:225]
	s_waitcnt lgkmcnt(1)
	v_mfma_f32_16x16x32_bf16 v[66:69], v[160:163], v[66:69], v[164:167]
	s_waitcnt lgkmcnt(0)
	v_mfma_f32_16x16x32_bf16 v[114:117], v[148:151], v[82:85], v[66:69]
	v_mfma_f32_16x16x32_bf16 v[66:69], v[126:129], v[188:191], v[86:89]
	v_mfma_f32_16x16x32_bf16 v[102:105], v[130:133], v[192:195], v[66:69]
	v_mfma_f32_16x16x32_bf16 v[66:69], v[160:163], v[188:191], v[70:73]
	v_mfma_f32_16x16x32_bf16 v[62:65], v[126:129], v[196:199], v[62:65]
	v_mfma_f32_16x16x32_bf16 v[58:61], v[160:163], v[196:199], v[58:61]
	v_mfma_f32_16x16x32_bf16 v[54:57], v[126:129], v[232:235], v[54:57]
	v_mfma_f32_16x16x32_bf16 v[50:53], v[160:163], v[232:235], v[50:53]
	v_mfma_f32_16x16x32_bf16 v[118:121], v[130:133], v[82:85], v[98:101]
	v_mfma_f32_16x16x32_bf16 v[98:101], v[148:151], v[192:195], v[66:69]
	v_mfma_f32_16x16x32_bf16 v[86:89], v[130:133], v[200:203], v[62:65]
	v_mfma_f32_16x16x32_bf16 v[82:85], v[148:151], v[200:203], v[58:61]
	v_mfma_f32_16x16x32_bf16 v[70:73], v[130:133], v[236:239], v[54:57]
	v_mfma_f32_16x16x32_bf16 v[66:69], v[148:151], v[236:239], v[50:53]
	s_setprio 0
	s_barrier
	s_nop 0
	ds_read_b128 v[50:53], v0 offset:49152
	ds_read_b128 v[164:167], v0 offset:50176
	ds_read_b128 v[188:191], v0 offset:51200
	ds_read_b128 v[192:195], v0 offset:52224
	ds_read_b128 v[196:199], v0 offset:53248
	ds_read_b128 v[200:203], v0 offset:54272
	ds_read_b128 v[222:225], v0 offset:55296
	ds_read_b128 v[232:235], v0 offset:56320
	s_barrier
	s_waitcnt lgkmcnt(0)
	s_setprio 1
	s_waitcnt lgkmcnt(7)
	v_mfma_f32_16x16x32_bf16 v[46:49], v[10:13], v[50:53], v[46:49]
	s_waitcnt lgkmcnt(5)
	v_mfma_f32_16x16x32_bf16 v[38:41], v[10:13], v[188:191], v[38:41]
	s_waitcnt lgkmcnt(3)
	v_mfma_f32_16x16x32_bf16 v[30:33], v[10:13], v[196:199], v[30:33]
	s_waitcnt lgkmcnt(1)
	v_mfma_f32_16x16x32_bf16 v[10:13], v[10:13], v[222:225], v[22:25]
	v_mfma_f32_16x16x32_bf16 v[62:65], v[14:17], v[164:167], v[46:49]
	v_mfma_f32_16x16x32_bf16 v[42:45], v[180:183], v[50:53], v[42:45]
	v_mfma_f32_16x16x32_bf16 v[46:49], v[14:17], v[192:195], v[38:41]
	v_mfma_f32_16x16x32_bf16 v[34:37], v[180:183], v[188:191], v[34:37]
	v_mfma_f32_16x16x32_bf16 v[30:33], v[14:17], v[200:203], v[30:33]
	v_mfma_f32_16x16x32_bf16 v[26:29], v[180:183], v[196:199], v[26:29]
	s_waitcnt lgkmcnt(0)
	v_mfma_f32_16x16x32_bf16 v[14:17], v[14:17], v[232:235], v[10:13]
	v_mfma_f32_16x16x32_bf16 v[10:13], v[180:183], v[222:225], v[18:21]
	v_mfma_f32_16x16x32_bf16 v[58:61], v[184:187], v[164:167], v[42:45]
	v_mfma_f32_16x16x32_bf16 v[42:45], v[184:187], v[192:195], v[34:37]
	v_mfma_f32_16x16x32_bf16 v[26:29], v[184:187], v[200:203], v[26:29]
	v_mfma_f32_16x16x32_bf16 v[10:13], v[184:187], v[232:235], v[10:13]
	s_setprio 0
	s_setprio 1
	v_mfma_f32_16x16x32_bf16 v[2:5], v[160:163], v[188:191], v[2:5]
	v_mfma_f32_16x16x32_bf16 v[18:21], v[126:129], v[50:53], v[134:137]
	v_mfma_f32_16x16x32_bf16 v[34:37], v[148:151], v[192:195], v[2:5]
	v_mfma_f32_16x16x32_bf16 v[2:5], v[126:129], v[196:199], v[156:159]
	v_mfma_f32_16x16x32_bf16 v[54:57], v[130:133], v[164:167], v[18:21]
	v_mfma_f32_16x16x32_bf16 v[18:21], v[160:163], v[50:53], v[152:155]
	v_mfma_f32_16x16x32_bf16 v[22:25], v[130:133], v[200:203], v[2:5]
	v_mfma_f32_16x16x32_bf16 v[2:5], v[160:163], v[196:199], v[168:171]
	v_mfma_f32_16x16x32_bf16 v[50:53], v[148:151], v[164:167], v[18:21]
	v_mfma_f32_16x16x32_bf16 v[6:9], v[126:129], v[188:191], v[6:9]
	v_mfma_f32_16x16x32_bf16 v[18:21], v[148:151], v[200:203], v[2:5]
	v_mfma_f32_16x16x32_bf16 v[2:5], v[126:129], v[222:225], v[172:175]
	v_mfma_f32_16x16x32_bf16 v[38:41], v[130:133], v[192:195], v[6:9]
	v_mfma_f32_16x16x32_bf16 v[6:9], v[130:133], v[232:235], v[2:5]
	v_mfma_f32_16x16x32_bf16 v[2:5], v[160:163], v[222:225], v[176:179]
	v_mfma_f32_16x16x32_bf16 v[2:5], v[148:151], v[232:235], v[2:5]
	s_setprio 0
	s_movk_i32 s0, 0x100
	v_cmp_gt_u32_e32 vcc, s0, v142
	s_barrier
	s_and_saveexec_b64 s[0:1], vcc
	s_cbranch_execz .LBB0_37
	s_barrier

.LBB0_85:
	ds_read_b128 v[164:167], v151
	ds_read_b128 v[168:171], v151 offset:1024
	ds_read_b128 v[172:175], v151 offset:2048
	ds_read_b128 v[176:179], v151 offset:3072
	v_lshl_add_u64 v[204:205], v[138:139], 0, s[10:11]
	v_lshl_add_u64 v[228:229], v[204:205], 0, s[60:61]
	s_add_i32 m0, s1, 0xc000
	ds_read_b128 v[180:183], v0
	ds_read_b128 v[184:187], v0 offset:1024
	ds_read_b128 v[188:191], v0 offset:2048
	ds_read_b128 v[192:195], v0 offset:3072
	ds_read_b128 v[196:199], v0 offset:4096
	ds_read_b128 v[200:203], v0 offset:5120
	ds_read_b128 v[222:225], v0 offset:6144
	ds_read_b128 v[232:235], v0 offset:7168
	global_load_lds_dwordx4 v[228:229], off
	v_lshl_add_u64 v[210:211], v[140:141], 0, s[10:11]
	s_add_i32 m0, s1, 0xe000
	v_lshl_add_u64 v[152:153], v[210:211], 0, s[60:61]
	global_load_lds_dwordx4 v[152:153], off
	s_waitcnt lgkmcnt(8)
	s_barrier
	s_waitcnt lgkmcnt(0)
	v_mfma_f32_16x16x32_bf16 v[126:129], v[164:167], v[180:183], v[126:129]
	v_mfma_f32_16x16x32_bf16 v[122:125], v[172:175], v[180:183], v[122:125]
	v_mfma_f32_16x16x32_bf16 v[118:121], v[164:167], v[188:191], v[118:121]
	v_mfma_f32_16x16x32_bf16 v[114:117], v[172:175], v[188:191], v[114:117]
	v_mfma_f32_16x16x32_bf16 v[110:113], v[164:167], v[196:199], v[110:113]
	v_mfma_f32_16x16x32_bf16 v[106:109], v[172:175], v[196:199], v[106:109]
	v_mfma_f32_16x16x32_bf16 v[102:105], v[164:167], v[222:225], v[102:105]
	v_mfma_f32_16x16x32_bf16 v[98:101], v[172:175], v[222:225], v[98:101]
	v_mfma_f32_16x16x32_bf16 v[126:129], v[168:171], v[184:187], v[126:129]
	v_mfma_f32_16x16x32_bf16 v[122:125], v[176:179], v[184:187], v[122:125]
	v_mfma_f32_16x16x32_bf16 v[118:121], v[168:171], v[192:195], v[118:121]
	v_mfma_f32_16x16x32_bf16 v[114:117], v[176:179], v[192:195], v[114:117]
	v_mfma_f32_16x16x32_bf16 v[110:113], v[168:171], v[200:203], v[110:113]
	v_mfma_f32_16x16x32_bf16 v[106:109], v[176:179], v[200:203], v[106:109]
	v_mfma_f32_16x16x32_bf16 v[102:105], v[168:171], v[232:235], v[102:105]
	v_mfma_f32_16x16x32_bf16 v[98:101], v[176:179], v[232:235], v[98:101]
	s_barrier
	v_lshl_add_u64 v[216:217], v[134:135], 0, s[10:11]
	s_add_i32 m0, s1, 0xff00
	ds_read_b128 v[236:239], v151 offset:16384
	ds_read_b128 v[240:243], v151 offset:17408
	ds_read_b128 v[244:247], v151 offset:18432
	ds_read_b128 v[248:251], v151 offset:19456
	global_load_lds_dwordx4 v[216:217], off offset:256
	s_add_i32 m0, s1, 0x11f00
	v_lshl_add_u64 v[218:219], v[136:137], 0, s[10:11]
	global_load_lds_dwordx4 v[218:219], off offset:256
	s_barrier
	s_waitcnt lgkmcnt(0)
	v_mfma_f32_16x16x32_bf16 v[94:97], v[236:239], v[180:183], v[94:97]
	v_mfma_f32_16x16x32_bf16 v[90:93], v[244:247], v[180:183], v[90:93]
	v_mfma_f32_16x16x32_bf16 v[86:89], v[236:239], v[188:191], v[86:89]
	v_mfma_f32_16x16x32_bf16 v[82:85], v[244:247], v[188:191], v[82:85]
	v_mfma_f32_16x16x32_bf16 v[78:81], v[236:239], v[196:199], v[78:81]
	v_mfma_f32_16x16x32_bf16 v[74:77], v[244:247], v[196:199], v[74:77]
	v_mfma_f32_16x16x32_bf16 v[70:73], v[236:239], v[222:225], v[70:73]
	v_mfma_f32_16x16x32_bf16 v[66:69], v[244:247], v[222:225], v[66:69]
	v_mfma_f32_16x16x32_bf16 v[94:97], v[240:243], v[184:187], v[94:97]
	v_mfma_f32_16x16x32_bf16 v[90:93], v[248:251], v[184:187], v[90:93]
	v_mfma_f32_16x16x32_bf16 v[86:89], v[240:243], v[192:195], v[86:89]
	v_mfma_f32_16x16x32_bf16 v[82:85], v[248:251], v[192:195], v[82:85]
	v_mfma_f32_16x16x32_bf16 v[78:81], v[240:243], v[200:203], v[78:81]
	v_mfma_f32_16x16x32_bf16 v[74:77], v[248:251], v[200:203], v[74:77]
	v_mfma_f32_16x16x32_bf16 v[70:73], v[240:243], v[232:235], v[70:73]
	v_mfma_f32_16x16x32_bf16 v[66:69], v[248:251], v[232:235], v[66:69]
	v_lshl_add_u64 v[158:159], v[204:205], 0, s[74:75]
	s_mov_b32 m0, s1
	s_barrier
	ds_read_b128 v[180:183], v0 offset:16384
	ds_read_b128 v[184:187], v0 offset:17408
	ds_read_b128 v[188:191], v0 offset:18432
	ds_read_b128 v[192:195], v0 offset:19456
	ds_read_b128 v[196:199], v0 offset:20480
	ds_read_b128 v[200:203], v0 offset:21504
	ds_read_b128 v[222:225], v0 offset:22528
	global_load_lds_dwordx4 v[158:159], off
	s_add_i32 m0, s1, 0x1f00
	ds_read_b128 v[232:235], v0 offset:23552
	global_load_lds_dwordx4 v[210:211], off offset:256
	s_barrier
	s_waitcnt lgkmcnt(0)
	v_mfma_f32_16x16x32_bf16 v[62:65], v[164:167], v[180:183], v[62:65]
	v_mfma_f32_16x16x32_bf16 v[58:61], v[172:175], v[180:183], v[58:61]
	v_mfma_f32_16x16x32_bf16 v[54:57], v[164:167], v[188:191], v[54:57]
	v_mfma_f32_16x16x32_bf16 v[50:53], v[172:175], v[188:191], v[50:53]
	v_mfma_f32_16x16x32_bf16 v[46:49], v[164:167], v[196:199], v[46:49]
	v_mfma_f32_16x16x32_bf16 v[42:45], v[172:175], v[196:199], v[42:45]
	v_mfma_f32_16x16x32_bf16 v[38:41], v[164:167], v[222:225], v[38:41]
	v_mfma_f32_16x16x32_bf16 v[34:37], v[172:175], v[222:225], v[34:37]
	v_mfma_f32_16x16x32_bf16 v[62:65], v[168:171], v[184:187], v[62:65]
	v_mfma_f32_16x16x32_bf16 v[58:61], v[176:179], v[184:187], v[58:61]
	v_mfma_f32_16x16x32_bf16 v[54:57], v[168:171], v[192:195], v[54:57]
	v_mfma_f32_16x16x32_bf16 v[50:53], v[176:179], v[192:195], v[50:53]
	v_mfma_f32_16x16x32_bf16 v[46:49], v[168:171], v[200:203], v[46:49]
	v_mfma_f32_16x16x32_bf16 v[42:45], v[176:179], v[200:203], v[42:45]
	v_mfma_f32_16x16x32_bf16 v[38:41], v[168:171], v[232:235], v[38:41]
	v_mfma_f32_16x16x32_bf16 v[34:37], v[176:179], v[232:235], v[34:37]
	s_barrier
	s_add_i32 m0, s1, 0x14000
	v_lshl_add_u64 v[154:155], v[216:217], 0, s[18:19]
	global_load_lds_dwordx4 v[154:155], off
	s_add_i32 m0, s1, 0x16000
	v_lshl_add_u64 v[156:157], v[218:219], 0, s[18:19]
	global_load_lds_dwordx4 v[156:157], off
	s_waitcnt vmcnt(6)
	s_barrier
	v_mfma_f32_16x16x32_bf16 v[30:33], v[236:239], v[180:183], v[30:33]
	v_mfma_f32_16x16x32_bf16 v[26:29], v[244:247], v[180:183], v[26:29]
	v_mfma_f32_16x16x32_bf16 v[22:25], v[236:239], v[188:191], v[22:25]
	v_mfma_f32_16x16x32_bf16 v[18:21], v[244:247], v[188:191], v[18:21]
	v_mfma_f32_16x16x32_bf16 v[14:17], v[236:239], v[196:199], v[14:17]
	v_mfma_f32_16x16x32_bf16 v[10:13], v[244:247], v[196:199], v[10:13]
	v_mfma_f32_16x16x32_bf16 v[6:9], v[236:239], v[222:225], v[6:9]
	v_mfma_f32_16x16x32_bf16 v[2:5], v[244:247], v[222:225], v[2:5]
	v_mfma_f32_16x16x32_bf16 v[30:33], v[240:243], v[184:187], v[30:33]
	v_mfma_f32_16x16x32_bf16 v[26:29], v[248:251], v[184:187], v[26:29]
	v_mfma_f32_16x16x32_bf16 v[22:25], v[240:243], v[192:195], v[22:25]
	v_mfma_f32_16x16x32_bf16 v[18:21], v[248:251], v[192:195], v[18:21]
	v_mfma_f32_16x16x32_bf16 v[14:17], v[240:243], v[200:203], v[14:17]
	v_mfma_f32_16x16x32_bf16 v[10:13], v[248:251], v[200:203], v[10:13]
	v_mfma_f32_16x16x32_bf16 v[6:9], v[240:243], v[232:235], v[6:9]
	v_mfma_f32_16x16x32_bf16 v[2:5], v[248:251], v[232:235], v[2:5]
	s_barrier
	ds_read_b128 v[164:167], v151 offset:32768
	ds_read_b128 v[168:171], v151 offset:33792
	ds_read_b128 v[172:175], v151 offset:34816
	ds_read_b128 v[176:179], v151 offset:35840
	s_add_i32 m0, s1, 0x3f80
	ds_read_b128 v[180:183], v0 offset:32768
	ds_read_b128 v[184:187], v0 offset:33792
	ds_read_b128 v[188:191], v0 offset:34816
	ds_read_b128 v[192:195], v0 offset:35840
	ds_read_b128 v[196:199], v0 offset:36864
	ds_read_b128 v[200:203], v0 offset:37888
	ds_read_b128 v[222:225], v0 offset:38912
	global_load_lds_dwordx4 v[228:229], off offset:128
	s_add_i32 m0, s1, 0x5f80
	ds_read_b128 v[232:235], v0 offset:39936
	global_load_lds_dwordx4 v[152:153], off offset:128
	s_waitcnt lgkmcnt(8)
	s_barrier
	s_waitcnt lgkmcnt(0)
	v_mfma_f32_16x16x32_bf16 v[126:129], v[164:167], v[180:183], v[126:129]
	v_mfma_f32_16x16x32_bf16 v[122:125], v[172:175], v[180:183], v[122:125]
	v_mfma_f32_16x16x32_bf16 v[118:121], v[164:167], v[188:191], v[118:121]
	v_mfma_f32_16x16x32_bf16 v[114:117], v[172:175], v[188:191], v[114:117]
	v_mfma_f32_16x16x32_bf16 v[110:113], v[164:167], v[196:199], v[110:113]
	v_mfma_f32_16x16x32_bf16 v[106:109], v[172:175], v[196:199], v[106:109]
	v_mfma_f32_16x16x32_bf16 v[102:105], v[164:167], v[222:225], v[102:105]
	v_mfma_f32_16x16x32_bf16 v[98:101], v[172:175], v[222:225], v[98:101]
	v_mfma_f32_16x16x32_bf16 v[126:129], v[168:171], v[184:187], v[126:129]
	v_mfma_f32_16x16x32_bf16 v[122:125], v[176:179], v[184:187], v[122:125]
	v_mfma_f32_16x16x32_bf16 v[118:121], v[168:171], v[192:195], v[118:121]
	v_mfma_f32_16x16x32_bf16 v[114:117], v[176:179], v[192:195], v[114:117]
	v_mfma_f32_16x16x32_bf16 v[110:113], v[168:171], v[200:203], v[110:113]
	v_mfma_f32_16x16x32_bf16 v[106:109], v[176:179], v[200:203], v[106:109]
	v_mfma_f32_16x16x32_bf16 v[102:105], v[168:171], v[232:235], v[102:105]
	v_mfma_f32_16x16x32_bf16 v[98:101], v[176:179], v[232:235], v[98:101]
	s_barrier
	s_add_i32 m0, s1, 0x17e80
	ds_read_b128 v[236:239], v151 offset:49152
	ds_read_b128 v[240:243], v151 offset:50176
	ds_read_b128 v[244:247], v151 offset:51200
	global_load_lds_dwordx4 v[216:217], off offset:384
	s_add_i32 m0, s1, 0x19e80
	ds_read_b128 v[248:251], v151 offset:52224
	global_load_lds_dwordx4 v[218:219], off offset:384
	s_barrier
	s_waitcnt lgkmcnt(0)
	v_mfma_f32_16x16x32_bf16 v[94:97], v[236:239], v[180:183], v[94:97]
	v_mfma_f32_16x16x32_bf16 v[90:93], v[244:247], v[180:183], v[90:93]
	v_mfma_f32_16x16x32_bf16 v[86:89], v[236:239], v[188:191], v[86:89]
	v_mfma_f32_16x16x32_bf16 v[82:85], v[244:247], v[188:191], v[82:85]
	v_mfma_f32_16x16x32_bf16 v[78:81], v[236:239], v[196:199], v[78:81]
	v_mfma_f32_16x16x32_bf16 v[74:77], v[244:247], v[196:199], v[74:77]
	v_mfma_f32_16x16x32_bf16 v[70:73], v[236:239], v[222:225], v[70:73]
	v_mfma_f32_16x16x32_bf16 v[66:69], v[244:247], v[222:225], v[66:69]
	v_mfma_f32_16x16x32_bf16 v[94:97], v[240:243], v[184:187], v[94:97]
	v_mfma_f32_16x16x32_bf16 v[90:93], v[248:251], v[184:187], v[90:93]
	v_mfma_f32_16x16x32_bf16 v[86:89], v[240:243], v[192:195], v[86:89]
	v_mfma_f32_16x16x32_bf16 v[82:85], v[248:251], v[192:195], v[82:85]
	v_mfma_f32_16x16x32_bf16 v[78:81], v[240:243], v[200:203], v[78:81]
	v_mfma_f32_16x16x32_bf16 v[74:77], v[248:251], v[200:203], v[74:77]
	v_mfma_f32_16x16x32_bf16 v[70:73], v[240:243], v[232:235], v[70:73]
	v_mfma_f32_16x16x32_bf16 v[66:69], v[248:251], v[232:235], v[66:69]
	s_add_i32 m0, s1, 0x7e80
	s_barrier
	ds_read_b128 v[180:183], v0 offset:49152
	ds_read_b128 v[184:187], v0 offset:50176
	ds_read_b128 v[188:191], v0 offset:51200
	ds_read_b128 v[192:195], v0 offset:52224
	ds_read_b128 v[196:199], v0 offset:53248
	ds_read_b128 v[200:203], v0 offset:54272
	ds_read_b128 v[222:225], v0 offset:55296
	global_load_lds_dwordx4 v[204:205], off offset:384
	s_add_i32 m0, s1, 0x9e80
	ds_read_b128 v[232:235], v0 offset:56320
	global_load_lds_dwordx4 v[210:211], off offset:384
	s_barrier
	s_waitcnt lgkmcnt(0)
	v_mfma_f32_16x16x32_bf16 v[62:65], v[164:167], v[180:183], v[62:65]
	v_mfma_f32_16x16x32_bf16 v[58:61], v[172:175], v[180:183], v[58:61]
	v_mfma_f32_16x16x32_bf16 v[54:57], v[164:167], v[188:191], v[54:57]
	v_mfma_f32_16x16x32_bf16 v[50:53], v[172:175], v[188:191], v[50:53]
	v_mfma_f32_16x16x32_bf16 v[46:49], v[164:167], v[196:199], v[46:49]
	v_mfma_f32_16x16x32_bf16 v[42:45], v[172:175], v[196:199], v[42:45]
	v_mfma_f32_16x16x32_bf16 v[38:41], v[164:167], v[222:225], v[38:41]
	v_mfma_f32_16x16x32_bf16 v[34:37], v[172:175], v[222:225], v[34:37]
	v_mfma_f32_16x16x32_bf16 v[62:65], v[168:171], v[184:187], v[62:65]
	v_mfma_f32_16x16x32_bf16 v[58:61], v[176:179], v[184:187], v[58:61]
	v_mfma_f32_16x16x32_bf16 v[54:57], v[168:171], v[192:195], v[54:57]
	v_mfma_f32_16x16x32_bf16 v[50:53], v[176:179], v[192:195], v[50:53]
	v_mfma_f32_16x16x32_bf16 v[46:49], v[168:171], v[200:203], v[46:49]
	v_mfma_f32_16x16x32_bf16 v[42:45], v[176:179], v[200:203], v[42:45]
	v_mfma_f32_16x16x32_bf16 v[38:41], v[168:171], v[232:235], v[38:41]
	v_mfma_f32_16x16x32_bf16 v[34:37], v[176:179], v[232:235], v[34:37]
	s_barrier
	s_add_i32 m0, s1, 0x1bf80
	s_nop 0
	global_load_lds_dwordx4 v[154:155], off offset:128
	s_add_i32 m0, s1, 0x1df80
	s_nop 0
	global_load_lds_dwordx4 v[156:157], off offset:128
	s_waitcnt vmcnt(6)
	s_barrier
	v_mfma_f32_16x16x32_bf16 v[30:33], v[236:239], v[180:183], v[30:33]
	v_mfma_f32_16x16x32_bf16 v[26:29], v[244:247], v[180:183], v[26:29]
	v_mfma_f32_16x16x32_bf16 v[22:25], v[236:239], v[188:191], v[22:25]
	v_mfma_f32_16x16x32_bf16 v[18:21], v[244:247], v[188:191], v[18:21]
	v_mfma_f32_16x16x32_bf16 v[14:17], v[236:239], v[196:199], v[14:17]
	v_mfma_f32_16x16x32_bf16 v[10:13], v[244:247], v[196:199], v[10:13]
	v_mfma_f32_16x16x32_bf16 v[6:9], v[236:239], v[222:225], v[6:9]
	v_mfma_f32_16x16x32_bf16 v[2:5], v[244:247], v[222:225], v[2:5]
	v_mfma_f32_16x16x32_bf16 v[30:33], v[240:243], v[184:187], v[30:33]
	v_mfma_f32_16x16x32_bf16 v[26:29], v[248:251], v[184:187], v[26:29]
	v_mfma_f32_16x16x32_bf16 v[22:25], v[240:243], v[192:195], v[22:25]
	v_mfma_f32_16x16x32_bf16 v[18:21], v[248:251], v[192:195], v[18:21]
	v_mfma_f32_16x16x32_bf16 v[14:17], v[240:243], v[200:203], v[14:17]
	v_mfma_f32_16x16x32_bf16 v[10:13], v[248:251], v[200:203], v[10:13]
	v_mfma_f32_16x16x32_bf16 v[6:9], v[240:243], v[232:235], v[6:9]
	v_mfma_f32_16x16x32_bf16 v[2:5], v[248:251], v[232:235], v[2:5]
	s_add_i32 s0, s0, 2
	s_add_u32 s10, s10, 0x100
	s_addc_u32 s11, s11, 0
	s_cmp_lt_u32 s0, 28
	s_barrier
	s_cbranch_scc1 .LBB0_85
	s_add_i32 s1, s1, 0x1e000
	s_mov_b64 s[10:11], 0xf80
	v_readfirstlane_b32 s0, v162
	v_lshl_add_u64 v[132:133], v[132:133], 0, s[10:11]
	s_mov_b32 m0, s0
	v_readfirstlane_b32 s0, v163
	ds_read_b128 v[134:137], v151
	ds_read_b128 v[138:141], v151 offset:1024
	ds_read_b128 v[152:155], v151 offset:2048
	ds_read_b128 v[156:159], v151 offset:3072
	ds_read_b128 v[164:167], v0
	ds_read_b128 v[168:171], v0 offset:1024
	ds_read_b128 v[172:175], v0 offset:2048
	ds_read_b128 v[176:179], v0 offset:3072
	ds_read_b128 v[180:183], v0 offset:4096
	ds_read_b128 v[184:187], v0 offset:5120
	ds_read_b128 v[188:191], v0 offset:6144
	ds_read_b128 v[192:195], v0 offset:7168
	global_load_lds_dwordx4 v[132:133], off
	v_lshl_add_u64 v[130:131], v[130:131], 0, s[10:11]
	s_mov_b32 m0, s0
	s_nop 0
	global_load_lds_dwordx4 v[130:131], off
	s_barrier
	s_waitcnt lgkmcnt(0)
	s_setprio 1
	s_waitcnt lgkmcnt(0)
	v_mfma_f32_16x16x32_bf16 v[126:129], v[134:137], v[164:167], v[126:129]
	v_mfma_f32_16x16x32_bf16 v[122:125], v[152:155], v[164:167], v[122:125]
	v_mfma_f32_16x16x32_bf16 v[114:117], v[152:155], v[172:175], v[114:117]
	v_mfma_f32_16x16x32_bf16 v[106:109], v[152:155], v[180:183], v[106:109]
	v_mfma_f32_16x16x32_bf16 v[98:101], v[152:155], v[188:191], v[98:101]
	v_mfma_f32_16x16x32_bf16 v[126:129], v[138:141], v[168:171], v[126:129]
	v_mfma_f32_16x16x32_bf16 v[122:125], v[156:159], v[168:171], v[122:125]
	v_mfma_f32_16x16x32_bf16 v[118:121], v[134:137], v[172:175], v[118:121]
	v_mfma_f32_16x16x32_bf16 v[114:117], v[156:159], v[176:179], v[114:117]
	v_mfma_f32_16x16x32_bf16 v[110:113], v[134:137], v[180:183], v[110:113]
	v_mfma_f32_16x16x32_bf16 v[106:109], v[156:159], v[184:187], v[106:109]
	v_mfma_f32_16x16x32_bf16 v[102:105], v[134:137], v[188:191], v[102:105]
	v_mfma_f32_16x16x32_bf16 v[98:101], v[156:159], v[192:195], v[98:101]
	v_mfma_f32_16x16x32_bf16 v[130:133], v[138:141], v[176:179], v[118:121]
	v_mfma_f32_16x16x32_bf16 v[160:163], v[138:141], v[184:187], v[110:113]
	v_mfma_f32_16x16x32_bf16 v[196:199], v[138:141], v[192:195], v[102:105]
	s_setprio 0
	s_barrier
	s_nop 0
	ds_read_b128 v[102:105], v151 offset:16384
	ds_read_b128 v[110:113], v151 offset:17408
	ds_read_b128 v[118:121], v151 offset:18432
	ds_read_b128 v[200:203], v151 offset:19456
	s_barrier
	s_waitcnt lgkmcnt(0)
	s_setprio 1
	s_waitcnt lgkmcnt(1)
	v_mfma_f32_16x16x32_bf16 v[90:93], v[118:121], v[164:167], v[90:93]
	v_mfma_f32_16x16x32_bf16 v[86:89], v[102:105], v[172:175], v[86:89]
	v_mfma_f32_16x16x32_bf16 v[82:85], v[118:121], v[172:175], v[82:85]
	v_mfma_f32_16x16x32_bf16 v[78:81], v[102:105], v[180:183], v[78:81]
	v_mfma_f32_16x16x32_bf16 v[70:73], v[102:105], v[188:191], v[70:73]
	v_mfma_f32_16x16x32_bf16 v[94:97], v[102:105], v[164:167], v[94:97]
	s_waitcnt lgkmcnt(0)
	v_mfma_f32_16x16x32_bf16 v[90:93], v[200:203], v[168:171], v[90:93]
	v_mfma_f32_16x16x32_bf16 v[86:89], v[110:113], v[176:179], v[86:89]
	v_mfma_f32_16x16x32_bf16 v[82:85], v[200:203], v[176:179], v[82:85]
	v_mfma_f32_16x16x32_bf16 v[78:81], v[110:113], v[184:187], v[78:81]
	v_mfma_f32_16x16x32_bf16 v[74:77], v[118:121], v[180:183], v[74:77]
	v_mfma_f32_16x16x32_bf16 v[70:73], v[110:113], v[192:195], v[70:73]
	v_mfma_f32_16x16x32_bf16 v[66:69], v[118:121], v[188:191], v[66:69]
	v_mfma_f32_16x16x32_bf16 v[222:225], v[110:113], v[168:171], v[94:97]
	v_mfma_f32_16x16x32_bf16 v[164:167], v[200:203], v[184:187], v[74:77]
	v_mfma_f32_16x16x32_bf16 v[168:171], v[200:203], v[192:195], v[66:69]
	s_setprio 0
	s_barrier
	s_nop 2
	ds_read_b128 v[66:69], v0 offset:16384
	ds_read_b128 v[74:77], v0 offset:17408
	ds_read_b128 v[94:97], v0 offset:18432
	ds_read_b128 v[172:175], v0 offset:19456
	ds_read_b128 v[176:179], v0 offset:20480
	ds_read_b128 v[180:183], v0 offset:21504
	ds_read_b128 v[184:187], v0 offset:22528
	ds_read_b128 v[188:191], v0 offset:23552
	s_waitcnt vmcnt(4)
	s_barrier
	s_waitcnt lgkmcnt(0)
	s_setprio 1
	s_waitcnt lgkmcnt(5)
	v_mfma_f32_16x16x32_bf16 v[54:57], v[134:137], v[94:97], v[54:57]
	v_mfma_f32_16x16x32_bf16 v[50:53], v[152:155], v[94:97], v[50:53]
	v_mfma_f32_16x16x32_bf16 v[62:65], v[134:137], v[66:69], v[62:65]
	v_mfma_f32_16x16x32_bf16 v[58:61], v[152:155], v[66:69], v[58:61]
	s_waitcnt lgkmcnt(4)
	v_mfma_f32_16x16x32_bf16 v[54:57], v[138:141], v[172:175], v[54:57]
	v_mfma_f32_16x16x32_bf16 v[50:53], v[156:159], v[172:175], v[50:53]
	s_waitcnt lgkmcnt(3)
	v_mfma_f32_16x16x32_bf16 v[46:49], v[134:137], v[176:179], v[46:49]
	v_mfma_f32_16x16x32_bf16 v[42:45], v[152:155], v[176:179], v[42:45]
	s_waitcnt lgkmcnt(1)
	v_mfma_f32_16x16x32_bf16 v[38:41], v[134:137], v[184:187], v[38:41]
	v_mfma_f32_16x16x32_bf16 v[34:37], v[152:155], v[184:187], v[34:37]
	v_mfma_f32_16x16x32_bf16 v[192:195], v[138:141], v[74:77], v[62:65]
	v_mfma_f32_16x16x32_bf16 v[232:235], v[156:159], v[74:77], v[58:61]
	v_mfma_f32_16x16x32_bf16 v[236:239], v[138:141], v[180:183], v[46:49]
	v_mfma_f32_16x16x32_bf16 v[240:243], v[156:159], v[180:183], v[42:45]
	s_waitcnt lgkmcnt(0)
	v_mfma_f32_16x16x32_bf16 v[134:137], v[138:141], v[188:191], v[38:41]
	v_mfma_f32_16x16x32_bf16 v[138:141], v[156:159], v[188:191], v[34:37]
	s_setprio 0
	s_setprio 1
	v_mfma_f32_16x16x32_bf16 v[30:33], v[102:105], v[66:69], v[30:33]
	v_mfma_f32_16x16x32_bf16 v[26:29], v[118:121], v[66:69], v[26:29]
	v_mfma_f32_16x16x32_bf16 v[14:17], v[102:105], v[176:179], v[14:17]
	v_mfma_f32_16x16x32_bf16 v[10:13], v[118:121], v[176:179], v[10:13]
	v_mfma_f32_16x16x32_bf16 v[30:33], v[110:113], v[74:77], v[30:33]
	v_mfma_f32_16x16x32_bf16 v[26:29], v[200:203], v[74:77], v[26:29]
	v_mfma_f32_16x16x32_bf16 v[22:25], v[102:105], v[94:97], v[22:25]
	v_mfma_f32_16x16x32_bf16 v[18:21], v[118:121], v[94:97], v[18:21]
	v_mfma_f32_16x16x32_bf16 v[14:17], v[110:113], v[180:183], v[14:17]
	v_mfma_f32_16x16x32_bf16 v[10:13], v[200:203], v[180:183], v[10:13]
	v_mfma_f32_16x16x32_bf16 v[6:9], v[102:105], v[184:187], v[6:9]
	v_mfma_f32_16x16x32_bf16 v[2:5], v[118:121], v[184:187], v[2:5]
	v_mfma_f32_16x16x32_bf16 v[152:155], v[110:113], v[172:175], v[22:25]
	v_mfma_f32_16x16x32_bf16 v[156:159], v[200:203], v[172:175], v[18:21]
	v_mfma_f32_16x16x32_bf16 v[172:175], v[110:113], v[188:191], v[6:9]
	v_mfma_f32_16x16x32_bf16 v[176:179], v[200:203], v[188:191], v[2:5]
	s_setprio 0
	s_barrier
	s_nop 1
	ds_read_b128 v[2:5], v151 offset:32768
	ds_read_b128 v[6:9], v151 offset:33792
	ds_read_b128 v[180:183], v151 offset:34816
	ds_read_b128 v[184:187], v151 offset:35840
	ds_read_b128 v[18:21], v0 offset:32768
	ds_read_b128 v[22:25], v0 offset:33792
	ds_read_b128 v[38:41], v0 offset:34816
	ds_read_b128 v[46:49], v0 offset:35840
	ds_read_b128 v[58:61], v0 offset:36864
	ds_read_b128 v[66:69], v0 offset:37888
	ds_read_b128 v[188:191], v0 offset:38912
	ds_read_b128 v[200:203], v0 offset:39936
	s_waitcnt vmcnt(2)
	s_barrier
	s_waitcnt lgkmcnt(0)
	s_setprio 1
	s_waitcnt lgkmcnt(7)
	v_mfma_f32_16x16x32_bf16 v[34:37], v[2:5], v[18:21], v[126:129]
	s_waitcnt lgkmcnt(6)
	v_mfma_f32_16x16x32_bf16 v[118:121], v[6:9], v[22:25], v[34:37]
	v_mfma_f32_16x16x32_bf16 v[34:37], v[180:183], v[18:21], v[122:125]
	v_mfma_f32_16x16x32_bf16 v[110:113], v[184:187], v[22:25], v[34:37]
	s_waitcnt lgkmcnt(5)
	v_mfma_f32_16x16x32_bf16 v[34:37], v[2:5], v[38:41], v[130:133]
	s_waitcnt lgkmcnt(4)
	v_mfma_f32_16x16x32_bf16 v[102:105], v[6:9], v[46:49], v[34:37]
	v_mfma_f32_16x16x32_bf16 v[34:37], v[180:183], v[38:41], v[114:117]
	v_mfma_f32_16x16x32_bf16 v[94:97], v[184:187], v[46:49], v[34:37]
	s_waitcnt lgkmcnt(3)
	v_mfma_f32_16x16x32_bf16 v[34:37], v[2:5], v[58:61], v[160:163]
	s_waitcnt lgkmcnt(2)
	v_mfma_f32_16x16x32_bf16 v[74:77], v[6:9], v[66:69], v[34:37]
	v_mfma_f32_16x16x32_bf16 v[34:37], v[180:183], v[58:61], v[106:109]
	v_mfma_f32_16x16x32_bf16 v[62:65], v[184:187], v[66:69], v[34:37]
	s_waitcnt lgkmcnt(1)
	v_mfma_f32_16x16x32_bf16 v[34:37], v[2:5], v[188:191], v[196:199]
	s_waitcnt lgkmcnt(0)
	v_mfma_f32_16x16x32_bf16 v[42:45], v[6:9], v[200:203], v[34:37]
	v_mfma_f32_16x16x32_bf16 v[34:37], v[180:183], v[188:191], v[98:101]
	v_mfma_f32_16x16x32_bf16 v[34:37], v[184:187], v[200:203], v[34:37]
	s_setprio 0
	s_barrier
	ds_read_b128 v[130:133], v151 offset:49152
	ds_read_b128 v[160:163], v151 offset:50176
	ds_read_b128 v[196:199], v151 offset:51200
	ds_read_b128 v[148:151], v151 offset:52224
	s_waitcnt vmcnt(0)
	s_barrier
	s_waitcnt lgkmcnt(0)
	s_setprio 1
	s_waitcnt lgkmcnt(3)
	v_mfma_f32_16x16x32_bf16 v[98:101], v[130:133], v[18:21], v[222:225]
	s_waitcnt lgkmcnt(1)
	v_mfma_f32_16x16x32_bf16 v[18:21], v[196:199], v[18:21], v[90:93]
	s_waitcnt lgkmcnt(0)
	v_mfma_f32_16x16x32_bf16 v[122:125], v[148:151], v[22:25], v[18:21]
	v_mfma_f32_16x16x32_bf16 v[18:21], v[130:133], v[38:41], v[86:89]
	v_mfma_f32_16x16x32_bf16 v[114:117], v[160:163], v[46:49], v[18:21]
	v_mfma_f32_16x16x32_bf16 v[18:21], v[196:199], v[38:41], v[82:85]
	v_mfma_f32_16x16x32_bf16 v[106:109], v[148:151], v[46:49], v[18:21]
	v_mfma_f32_16x16x32_bf16 v[18:21], v[130:133], v[58:61], v[78:81]
	v_mfma_f32_16x16x32_bf16 v[126:129], v[160:163], v[22:25], v[98:101]
	v_mfma_f32_16x16x32_bf16 v[98:101], v[160:163], v[66:69], v[18:21]
	v_mfma_f32_16x16x32_bf16 v[18:21], v[196:199], v[58:61], v[164:167]
	v_mfma_f32_16x16x32_bf16 v[90:93], v[148:151], v[66:69], v[18:21]
	v_mfma_f32_16x16x32_bf16 v[18:21], v[130:133], v[188:191], v[70:73]
	v_mfma_f32_16x16x32_bf16 v[66:69], v[160:163], v[200:203], v[18:21]
	v_mfma_f32_16x16x32_bf16 v[18:21], v[196:199], v[188:191], v[168:171]
	v_mfma_f32_16x16x32_bf16 v[58:61], v[148:151], v[200:203], v[18:21]
	s_setprio 0
	s_barrier
	ds_read_b128 v[82:85], v0 offset:49152
	ds_read_b128 v[164:167], v0 offset:50176
	ds_read_b128 v[168:171], v0 offset:51200
	ds_read_b128 v[188:191], v0 offset:52224
	ds_read_b128 v[200:203], v0 offset:53248
	ds_read_b128 v[222:225], v0 offset:54272
	ds_read_b128 v[244:247], v0 offset:55296
	ds_read_b128 v[248:251], v0 offset:56320
	s_barrier
	s_waitcnt lgkmcnt(0)
	s_setprio 1
	s_waitcnt lgkmcnt(7)
	v_mfma_f32_16x16x32_bf16 v[18:21], v[2:5], v[82:85], v[192:195]
	s_waitcnt lgkmcnt(6)
	v_mfma_f32_16x16x32_bf16 v[78:81], v[6:9], v[164:167], v[18:21]
	v_mfma_f32_16x16x32_bf16 v[18:21], v[180:183], v[82:85], v[232:235]
	v_mfma_f32_16x16x32_bf16 v[70:73], v[184:187], v[164:167], v[18:21]
	s_waitcnt lgkmcnt(5)
	v_mfma_f32_16x16x32_bf16 v[18:21], v[2:5], v[168:171], v[54:57]
	s_waitcnt lgkmcnt(4)
	v_mfma_f32_16x16x32_bf16 v[46:49], v[6:9], v[188:191], v[18:21]
	v_mfma_f32_16x16x32_bf16 v[18:21], v[180:183], v[168:171], v[50:53]
	v_mfma_f32_16x16x32_bf16 v[38:41], v[184:187], v[188:191], v[18:21]
	s_waitcnt lgkmcnt(3)
	v_mfma_f32_16x16x32_bf16 v[18:21], v[2:5], v[200:203], v[236:239]
	s_waitcnt lgkmcnt(1)
	v_mfma_f32_16x16x32_bf16 v[2:5], v[2:5], v[244:247], v[134:137]
	v_mfma_f32_16x16x32_bf16 v[22:25], v[6:9], v[222:225], v[18:21]
	v_mfma_f32_16x16x32_bf16 v[18:21], v[180:183], v[200:203], v[240:243]
	s_waitcnt lgkmcnt(0)
	v_mfma_f32_16x16x32_bf16 v[6:9], v[6:9], v[248:251], v[2:5]
	v_mfma_f32_16x16x32_bf16 v[2:5], v[180:183], v[244:247], v[138:141]
	v_mfma_f32_16x16x32_bf16 v[18:21], v[184:187], v[222:225], v[18:21]
	v_mfma_f32_16x16x32_bf16 v[2:5], v[184:187], v[248:251], v[2:5]
	s_setprio 0
	s_setprio 1
	v_mfma_f32_16x16x32_bf16 v[26:29], v[196:199], v[82:85], v[26:29]
	v_mfma_f32_16x16x32_bf16 v[30:33], v[130:133], v[82:85], v[30:33]
	v_mfma_f32_16x16x32_bf16 v[82:85], v[148:151], v[164:167], v[26:29]
	v_mfma_f32_16x16x32_bf16 v[26:29], v[130:133], v[168:171], v[152:155]
	v_mfma_f32_16x16x32_bf16 v[54:57], v[160:163], v[188:191], v[26:29]
	v_mfma_f32_16x16x32_bf16 v[26:29], v[196:199], v[168:171], v[156:159]
	v_mfma_f32_16x16x32_bf16 v[10:13], v[196:199], v[200:203], v[10:13]
	v_mfma_f32_16x16x32_bf16 v[50:53], v[148:151], v[188:191], v[26:29]
	v_mfma_f32_16x16x32_bf16 v[14:17], v[130:133], v[200:203], v[14:17]
	v_mfma_f32_16x16x32_bf16 v[26:29], v[148:151], v[222:225], v[10:13]
	v_mfma_f32_16x16x32_bf16 v[10:13], v[130:133], v[244:247], v[172:175]
	v_mfma_f32_16x16x32_bf16 v[86:89], v[160:163], v[164:167], v[30:33]
	v_mfma_f32_16x16x32_bf16 v[30:33], v[160:163], v[222:225], v[14:17]
	v_mfma_f32_16x16x32_bf16 v[14:17], v[160:163], v[248:251], v[10:13]
	v_mfma_f32_16x16x32_bf16 v[10:13], v[196:199], v[244:247], v[176:179]
	v_mfma_f32_16x16x32_bf16 v[10:13], v[148:151], v[248:251], v[10:13]
	s_setprio 0
	s_movk_i32 s0, 0x100
	v_cmp_gt_u32_e32 vcc, s0, v142
	s_barrier
	s_and_saveexec_b64 s[0:1], vcc
	s_cbranch_execz .LBB0_81
	s_barrier
	s_branch .LBB0_81

.LBB0_108:
	ds_read_b128 v[104:107], v99
	ds_read_b128 v[108:111], v99 offset:1024
	ds_read_b128 v[112:115], v99 offset:2048
	ds_read_b128 v[116:119], v99 offset:3072
	v_lshl_add_u64 v[152:153], v[74:75], 0, s[10:11]
	v_lshl_add_u64 v[164:165], v[152:153], 0, s[60:61]
	s_add_i32 m0, s1, 0xc000
	ds_read_b128 v[120:123], v0
	ds_read_b128 v[124:127], v0 offset:1024
	ds_read_b128 v[128:131], v0 offset:2048
	ds_read_b128 v[132:135], v0 offset:3072
	ds_read_b128 v[136:139], v0 offset:4096
	ds_read_b128 v[140:143], v0 offset:5120
	ds_read_b128 v[144:147], v0 offset:6144
	ds_read_b128 v[148:151], v0 offset:7168
	global_load_lds_dwordx4 v[164:165], off
	v_lshl_add_u64 v[154:155], v[76:77], 0, s[10:11]
	s_add_i32 m0, s1, 0xe000
	v_lshl_add_u64 v[88:89], v[154:155], 0, s[60:61]
	global_load_lds_dwordx4 v[88:89], off
	s_waitcnt lgkmcnt(8)
	s_barrier
	s_waitcnt lgkmcnt(0)
	v_mfma_f32_16x16x32_bf16 v[62:65], v[104:107], v[120:123], v[62:65]
	v_mfma_f32_16x16x32_bf16 v[58:61], v[112:115], v[120:123], v[58:61]
	v_mfma_f32_16x16x32_bf16 v[54:57], v[104:107], v[128:131], v[54:57]
	v_mfma_f32_16x16x32_bf16 v[50:53], v[112:115], v[128:131], v[50:53]
	v_mfma_f32_16x16x32_bf16 v[46:49], v[104:107], v[136:139], v[46:49]
	v_mfma_f32_16x16x32_bf16 v[42:45], v[112:115], v[136:139], v[42:45]
	v_mfma_f32_16x16x32_bf16 v[38:41], v[104:107], v[144:147], v[38:41]
	v_mfma_f32_16x16x32_bf16 v[34:37], v[112:115], v[144:147], v[34:37]
	v_mfma_f32_16x16x32_bf16 v[62:65], v[108:111], v[124:127], v[62:65]
	v_mfma_f32_16x16x32_bf16 v[58:61], v[116:119], v[124:127], v[58:61]
	v_mfma_f32_16x16x32_bf16 v[54:57], v[108:111], v[132:135], v[54:57]
	v_mfma_f32_16x16x32_bf16 v[50:53], v[116:119], v[132:135], v[50:53]
	v_mfma_f32_16x16x32_bf16 v[46:49], v[108:111], v[140:143], v[46:49]
	v_mfma_f32_16x16x32_bf16 v[42:45], v[116:119], v[140:143], v[42:45]
	v_mfma_f32_16x16x32_bf16 v[38:41], v[108:111], v[148:151], v[38:41]
	v_mfma_f32_16x16x32_bf16 v[34:37], v[116:119], v[148:151], v[34:37]
	s_barrier
	v_lshl_add_u64 v[156:157], v[70:71], 0, s[10:11]
	s_add_i32 m0, s1, 0xff00
	s_nop 0
	global_load_lds_dwordx4 v[156:157], off offset:256
	s_add_i32 m0, s1, 0x11f00
	v_lshl_add_u64 v[158:159], v[72:73], 0, s[10:11]
	global_load_lds_dwordx4 v[158:159], off offset:256
	v_lshl_add_u64 v[90:91], v[152:153], 0, s[74:75]
	s_mov_b32 m0, s1
	s_barrier
	s_waitcnt lgkmcnt(0)
	s_barrier
	ds_read_b128 v[120:123], v0 offset:16384
	ds_read_b128 v[124:127], v0 offset:17408
	ds_read_b128 v[128:131], v0 offset:18432
	ds_read_b128 v[132:135], v0 offset:19456
	ds_read_b128 v[136:139], v0 offset:20480
	ds_read_b128 v[140:143], v0 offset:21504
	ds_read_b128 v[144:147], v0 offset:22528
	global_load_lds_dwordx4 v[90:91], off
	s_add_i32 m0, s1, 0x1f00
	ds_read_b128 v[148:151], v0 offset:23552
	global_load_lds_dwordx4 v[154:155], off offset:256
	s_barrier
	s_waitcnt lgkmcnt(0)
	v_mfma_f32_16x16x32_bf16 v[2:5], v[104:107], v[120:123], v[2:5]
	v_mfma_f32_16x16x32_bf16 v[6:9], v[112:115], v[120:123], v[6:9]
	v_mfma_f32_16x16x32_bf16 v[10:13], v[104:107], v[128:131], v[10:13]
	v_mfma_f32_16x16x32_bf16 v[14:17], v[112:115], v[128:131], v[14:17]
	v_mfma_f32_16x16x32_bf16 v[18:21], v[104:107], v[136:139], v[18:21]
	v_mfma_f32_16x16x32_bf16 v[22:25], v[112:115], v[136:139], v[22:25]
	v_mfma_f32_16x16x32_bf16 v[26:29], v[104:107], v[144:147], v[26:29]
	v_mfma_f32_16x16x32_bf16 v[30:33], v[112:115], v[144:147], v[30:33]
	v_mfma_f32_16x16x32_bf16 v[2:5], v[108:111], v[124:127], v[2:5]
	v_mfma_f32_16x16x32_bf16 v[6:9], v[116:119], v[124:127], v[6:9]
	v_mfma_f32_16x16x32_bf16 v[10:13], v[108:111], v[132:135], v[10:13]
	v_mfma_f32_16x16x32_bf16 v[14:17], v[116:119], v[132:135], v[14:17]
	v_mfma_f32_16x16x32_bf16 v[18:21], v[108:111], v[140:143], v[18:21]
	v_mfma_f32_16x16x32_bf16 v[22:25], v[116:119], v[140:143], v[22:25]
	v_mfma_f32_16x16x32_bf16 v[26:29], v[108:111], v[148:151], v[26:29]
	v_mfma_f32_16x16x32_bf16 v[30:33], v[116:119], v[148:151], v[30:33]
	s_barrier
	v_lshl_add_u64 v[160:161], v[78:79], 0, s[10:11]
	s_add_i32 m0, s1, 0x13f00
	s_nop 0
	global_load_lds_dwordx4 v[160:161], off offset:256
	s_add_i32 m0, s1, 0x15f00
	v_lshl_add_u64 v[162:163], v[80:81], 0, s[10:11]
	global_load_lds_dwordx4 v[162:163], off offset:256
	s_waitcnt vmcnt(6)
	s_barrier
	s_barrier
	ds_read_b128 v[104:107], v99 offset:32768
	ds_read_b128 v[108:111], v99 offset:33792
	ds_read_b128 v[112:115], v99 offset:34816
	ds_read_b128 v[116:119], v99 offset:35840
	s_add_i32 m0, s1, 0x3f80
	ds_read_b128 v[120:123], v0 offset:32768
	ds_read_b128 v[124:127], v0 offset:33792
	ds_read_b128 v[128:131], v0 offset:34816
	ds_read_b128 v[132:135], v0 offset:35840
	ds_read_b128 v[136:139], v0 offset:36864
	ds_read_b128 v[140:143], v0 offset:37888
	ds_read_b128 v[144:147], v0 offset:38912
	global_load_lds_dwordx4 v[164:165], off offset:128
	s_add_i32 m0, s1, 0x5f80
	ds_read_b128 v[148:151], v0 offset:39936
	global_load_lds_dwordx4 v[88:89], off offset:128
	s_waitcnt lgkmcnt(8)
	s_barrier
	s_waitcnt lgkmcnt(0)
	v_mfma_f32_16x16x32_bf16 v[62:65], v[104:107], v[120:123], v[62:65]
	v_mfma_f32_16x16x32_bf16 v[58:61], v[112:115], v[120:123], v[58:61]
	v_mfma_f32_16x16x32_bf16 v[54:57], v[104:107], v[128:131], v[54:57]
	v_mfma_f32_16x16x32_bf16 v[50:53], v[112:115], v[128:131], v[50:53]
	v_mfma_f32_16x16x32_bf16 v[46:49], v[104:107], v[136:139], v[46:49]
	v_mfma_f32_16x16x32_bf16 v[42:45], v[112:115], v[136:139], v[42:45]
	v_mfma_f32_16x16x32_bf16 v[38:41], v[104:107], v[144:147], v[38:41]
	v_mfma_f32_16x16x32_bf16 v[34:37], v[112:115], v[144:147], v[34:37]
	v_mfma_f32_16x16x32_bf16 v[62:65], v[108:111], v[124:127], v[62:65]
	v_mfma_f32_16x16x32_bf16 v[58:61], v[116:119], v[124:127], v[58:61]
	v_mfma_f32_16x16x32_bf16 v[54:57], v[108:111], v[132:135], v[54:57]
	v_mfma_f32_16x16x32_bf16 v[50:53], v[116:119], v[132:135], v[50:53]
	v_mfma_f32_16x16x32_bf16 v[46:49], v[108:111], v[140:143], v[46:49]
	v_mfma_f32_16x16x32_bf16 v[42:45], v[116:119], v[140:143], v[42:45]
	v_mfma_f32_16x16x32_bf16 v[38:41], v[108:111], v[148:151], v[38:41]
	v_mfma_f32_16x16x32_bf16 v[34:37], v[116:119], v[148:151], v[34:37]
	s_barrier
	s_add_i32 m0, s1, 0x17e80
	s_nop 0
	global_load_lds_dwordx4 v[156:157], off offset:384
	s_add_i32 m0, s1, 0x19e80
	s_nop 0
	global_load_lds_dwordx4 v[158:159], off offset:384
	s_add_i32 m0, s1, 0x7e80
	s_barrier
	s_waitcnt lgkmcnt(0)
	s_barrier
	ds_read_b128 v[120:123], v0 offset:49152
	ds_read_b128 v[124:127], v0 offset:50176
	ds_read_b128 v[128:131], v0 offset:51200
	ds_read_b128 v[132:135], v0 offset:52224
	ds_read_b128 v[136:139], v0 offset:53248
	ds_read_b128 v[140:143], v0 offset:54272
	ds_read_b128 v[144:147], v0 offset:55296
	global_load_lds_dwordx4 v[152:153], off offset:384
	s_add_i32 m0, s1, 0x9e80
	ds_read_b128 v[148:151], v0 offset:56320
	global_load_lds_dwordx4 v[154:155], off offset:384
	s_barrier
	s_waitcnt lgkmcnt(0)
	v_mfma_f32_16x16x32_bf16 v[2:5], v[104:107], v[120:123], v[2:5]
	v_mfma_f32_16x16x32_bf16 v[6:9], v[112:115], v[120:123], v[6:9]
	v_mfma_f32_16x16x32_bf16 v[10:13], v[104:107], v[128:131], v[10:13]
	v_mfma_f32_16x16x32_bf16 v[14:17], v[112:115], v[128:131], v[14:17]
	v_mfma_f32_16x16x32_bf16 v[18:21], v[104:107], v[136:139], v[18:21]
	v_mfma_f32_16x16x32_bf16 v[22:25], v[112:115], v[136:139], v[22:25]
	v_mfma_f32_16x16x32_bf16 v[26:29], v[104:107], v[144:147], v[26:29]
	v_mfma_f32_16x16x32_bf16 v[30:33], v[112:115], v[144:147], v[30:33]
	v_mfma_f32_16x16x32_bf16 v[2:5], v[108:111], v[124:127], v[2:5]
	v_mfma_f32_16x16x32_bf16 v[6:9], v[116:119], v[124:127], v[6:9]
	v_mfma_f32_16x16x32_bf16 v[10:13], v[108:111], v[132:135], v[10:13]
	v_mfma_f32_16x16x32_bf16 v[14:17], v[116:119], v[132:135], v[14:17]
	v_mfma_f32_16x16x32_bf16 v[18:21], v[108:111], v[140:143], v[18:21]
	v_mfma_f32_16x16x32_bf16 v[22:25], v[116:119], v[140:143], v[22:25]
	v_mfma_f32_16x16x32_bf16 v[26:29], v[108:111], v[148:151], v[26:29]
	v_mfma_f32_16x16x32_bf16 v[30:33], v[116:119], v[148:151], v[30:33]
	s_barrier
	s_add_i32 m0, s1, 0x1be80
	s_nop 0
	global_load_lds_dwordx4 v[160:161], off offset:384
	s_add_i32 m0, s1, 0x1de80
	s_add_i32 s0, s0, 2
	global_load_lds_dwordx4 v[162:163], off offset:384
	s_waitcnt vmcnt(6)
	s_add_u32 s10, s10, 0x100
	s_addc_u32 s11, s11, 0
	s_cmp_lt_u32 s0, 28
	s_barrier
	s_barrier
	s_cbranch_scc1 .LBB0_108
	s_add_i32 s1, s1, 0x1e000
	s_mov_b64 s[10:11], 0xf80
	v_readfirstlane_b32 s0, v102
	v_lshl_add_u64 v[68:69], v[68:69], 0, s[10:11]
	s_mov_b32 m0, s0
	v_readfirstlane_b32 s0, v103
	ds_read_b128 v[70:73], v99
	ds_read_b128 v[74:77], v99 offset:1024
	ds_read_b128 v[78:81], v99 offset:2048
	ds_read_b128 v[88:91], v99 offset:3072
	ds_read_b128 v[92:95], v0
	ds_read_b128 v[104:107], v0 offset:1024
	ds_read_b128 v[108:111], v0 offset:2048
	ds_read_b128 v[112:115], v0 offset:3072
	ds_read_b128 v[116:119], v0 offset:4096
	ds_read_b128 v[120:123], v0 offset:5120
	ds_read_b128 v[124:127], v0 offset:6144
	ds_read_b128 v[128:131], v0 offset:7168
	global_load_lds_dwordx4 v[68:69], off
	v_lshl_add_u64 v[66:67], v[66:67], 0, s[10:11]
	s_mov_b32 m0, s0
	s_nop 0
	global_load_lds_dwordx4 v[66:67], off
	s_barrier
	s_waitcnt lgkmcnt(0)
	s_setprio 1
	s_waitcnt lgkmcnt(0)
	v_mfma_f32_16x16x32_bf16 v[62:65], v[70:73], v[92:95], v[62:65]
	v_mfma_f32_16x16x32_bf16 v[58:61], v[78:81], v[92:95], v[58:61]
	v_mfma_f32_16x16x32_bf16 v[54:57], v[70:73], v[108:111], v[54:57]
	v_mfma_f32_16x16x32_bf16 v[50:53], v[78:81], v[108:111], v[50:53]
	v_mfma_f32_16x16x32_bf16 v[46:49], v[70:73], v[116:119], v[46:49]
	v_mfma_f32_16x16x32_bf16 v[42:45], v[78:81], v[116:119], v[42:45]
	v_mfma_f32_16x16x32_bf16 v[38:41], v[70:73], v[124:127], v[38:41]
	v_mfma_f32_16x16x32_bf16 v[34:37], v[78:81], v[124:127], v[34:37]
	v_mfma_f32_16x16x32_bf16 v[62:65], v[74:77], v[104:107], v[62:65]
	v_mfma_f32_16x16x32_bf16 v[58:61], v[88:91], v[104:107], v[58:61]
	v_mfma_f32_16x16x32_bf16 v[54:57], v[74:77], v[112:115], v[54:57]
	v_mfma_f32_16x16x32_bf16 v[50:53], v[88:91], v[112:115], v[50:53]
	v_mfma_f32_16x16x32_bf16 v[46:49], v[74:77], v[120:123], v[46:49]
	v_mfma_f32_16x16x32_bf16 v[42:45], v[88:91], v[120:123], v[42:45]
	v_mfma_f32_16x16x32_bf16 v[38:41], v[74:77], v[128:131], v[38:41]
	v_mfma_f32_16x16x32_bf16 v[34:37], v[88:91], v[128:131], v[34:37]
	s_setprio 0
	s_barrier
	s_barrier
	s_waitcnt lgkmcnt(0)
	s_barrier
	ds_read_b128 v[66:69], v0 offset:16384
	ds_read_b128 v[92:95], v0 offset:17408
	ds_read_b128 v[100:103], v0 offset:18432
	ds_read_b128 v[104:107], v0 offset:19456
	ds_read_b128 v[108:111], v0 offset:20480
	ds_read_b128 v[112:115], v0 offset:21504
	ds_read_b128 v[116:119], v0 offset:22528
	ds_read_b128 v[120:123], v0 offset:23552
	s_waitcnt vmcnt(4)
	s_barrier
	s_waitcnt lgkmcnt(0)
	s_setprio 1
	s_waitcnt lgkmcnt(3)
	v_mfma_f32_16x16x32_bf16 v[18:21], v[70:73], v[108:111], v[18:21]
	v_mfma_f32_16x16x32_bf16 v[2:5], v[70:73], v[66:69], v[2:5]
	v_mfma_f32_16x16x32_bf16 v[6:9], v[78:81], v[66:69], v[6:9]
	s_waitcnt lgkmcnt(2)
	v_mfma_f32_16x16x32_bf16 v[66:69], v[74:77], v[112:115], v[18:21]
	v_mfma_f32_16x16x32_bf16 v[18:21], v[78:81], v[108:111], v[22:25]
	v_mfma_f32_16x16x32_bf16 v[2:5], v[74:77], v[92:95], v[2:5]
	v_mfma_f32_16x16x32_bf16 v[6:9], v[88:91], v[92:95], v[6:9]
	v_mfma_f32_16x16x32_bf16 v[10:13], v[70:73], v[100:103], v[10:13]
	v_mfma_f32_16x16x32_bf16 v[14:17], v[78:81], v[100:103], v[14:17]
	v_mfma_f32_16x16x32_bf16 v[92:95], v[88:91], v[112:115], v[18:21]
	s_waitcnt lgkmcnt(1)
	v_mfma_f32_16x16x32_bf16 v[18:21], v[70:73], v[116:119], v[26:29]
	v_mfma_f32_16x16x32_bf16 v[10:13], v[74:77], v[104:107], v[10:13]
	v_mfma_f32_16x16x32_bf16 v[14:17], v[88:91], v[104:107], v[14:17]
	s_waitcnt lgkmcnt(0)
	v_mfma_f32_16x16x32_bf16 v[70:73], v[74:77], v[120:123], v[18:21]
	v_mfma_f32_16x16x32_bf16 v[18:21], v[78:81], v[116:119], v[30:33]
	v_mfma_f32_16x16x32_bf16 v[74:77], v[88:91], v[120:123], v[18:21]
	s_setprio 0
	s_barrier
	ds_read_b128 v[78:81], v99 offset:32768
	ds_read_b128 v[88:91], v99 offset:33792
	ds_read_b128 v[100:103], v99 offset:34816
	ds_read_b128 v[96:99], v99 offset:35840
	s_nop 0
	ds_read_b128 v[18:21], v0 offset:32768
	ds_read_b128 v[22:25], v0 offset:33792
	ds_read_b128 v[26:29], v0 offset:34816
	ds_read_b128 v[30:33], v0 offset:35840
	ds_read_b128 v[104:107], v0 offset:36864
	ds_read_b128 v[108:111], v0 offset:37888
	ds_read_b128 v[112:115], v0 offset:38912
	ds_read_b128 v[116:119], v0 offset:39936
	s_waitcnt vmcnt(2)
	s_barrier
	s_waitcnt lgkmcnt(0)
	s_setprio 1
	s_waitcnt lgkmcnt(7)
	v_mfma_f32_16x16x32_bf16 v[62:65], v[78:81], v[18:21], v[62:65]
	v_mfma_f32_16x16x32_bf16 v[18:21], v[100:103], v[18:21], v[58:61]
	s_waitcnt lgkmcnt(6)
	v_mfma_f32_16x16x32_bf16 v[58:61], v[96:99], v[22:25], v[18:21]
	s_waitcnt lgkmcnt(5)
	v_mfma_f32_16x16x32_bf16 v[18:21], v[78:81], v[26:29], v[54:57]
	s_waitcnt lgkmcnt(4)
	v_mfma_f32_16x16x32_bf16 v[54:57], v[88:91], v[30:33], v[18:21]
	v_mfma_f32_16x16x32_bf16 v[18:21], v[100:103], v[26:29], v[50:53]
	v_mfma_f32_16x16x32_bf16 v[50:53], v[96:99], v[30:33], v[18:21]
	s_waitcnt lgkmcnt(3)
	v_mfma_f32_16x16x32_bf16 v[18:21], v[78:81], v[104:107], v[46:49]
	s_waitcnt lgkmcnt(2)
	v_mfma_f32_16x16x32_bf16 v[46:49], v[88:91], v[108:111], v[18:21]
	v_mfma_f32_16x16x32_bf16 v[18:21], v[100:103], v[104:107], v[42:45]
	v_mfma_f32_16x16x32_bf16 v[42:45], v[96:99], v[108:111], v[18:21]
	s_waitcnt lgkmcnt(1)
	v_mfma_f32_16x16x32_bf16 v[18:21], v[78:81], v[112:115], v[38:41]
	s_waitcnt lgkmcnt(0)
	v_mfma_f32_16x16x32_bf16 v[38:41], v[88:91], v[116:119], v[18:21]
	v_mfma_f32_16x16x32_bf16 v[18:21], v[100:103], v[112:115], v[34:37]
	v_mfma_f32_16x16x32_bf16 v[62:65], v[88:91], v[22:25], v[62:65]
	v_mfma_f32_16x16x32_bf16 v[34:37], v[96:99], v[116:119], v[18:21]
	s_setprio 0
	s_barrier
	s_waitcnt vmcnt(0)
	s_barrier
	s_waitcnt lgkmcnt(0)
	s_barrier
	s_nop 1
	ds_read_b128 v[18:21], v0 offset:49152
	ds_read_b128 v[22:25], v0 offset:50176
	ds_read_b128 v[104:107], v0 offset:51200
	ds_read_b128 v[108:111], v0 offset:52224
	ds_read_b128 v[112:115], v0 offset:53248
	ds_read_b128 v[116:119], v0 offset:54272
	ds_read_b128 v[120:123], v0 offset:55296
	ds_read_b128 v[124:127], v0 offset:56320
	s_barrier
	s_waitcnt lgkmcnt(0)
	s_setprio 1
	s_waitcnt lgkmcnt(7)
	v_mfma_f32_16x16x32_bf16 v[2:5], v[78:81], v[18:21], v[2:5]
	s_waitcnt lgkmcnt(6)
	v_mfma_f32_16x16x32_bf16 v[30:33], v[88:91], v[22:25], v[2:5]
	v_mfma_f32_16x16x32_bf16 v[2:5], v[100:103], v[18:21], v[6:9]
	v_mfma_f32_16x16x32_bf16 v[26:29], v[96:99], v[22:25], v[2:5]
	s_waitcnt lgkmcnt(5)
	v_mfma_f32_16x16x32_bf16 v[2:5], v[78:81], v[104:107], v[10:13]
	s_waitcnt lgkmcnt(4)
	v_mfma_f32_16x16x32_bf16 v[22:25], v[88:91], v[108:111], v[2:5]
	v_mfma_f32_16x16x32_bf16 v[2:5], v[100:103], v[104:107], v[14:17]
	v_mfma_f32_16x16x32_bf16 v[18:21], v[96:99], v[108:111], v[2:5]
	s_waitcnt lgkmcnt(3)
	v_mfma_f32_16x16x32_bf16 v[2:5], v[78:81], v[112:115], v[66:69]
	s_waitcnt lgkmcnt(2)
	v_mfma_f32_16x16x32_bf16 v[14:17], v[88:91], v[116:119], v[2:5]
	v_mfma_f32_16x16x32_bf16 v[2:5], v[100:103], v[112:115], v[92:95]
	v_mfma_f32_16x16x32_bf16 v[10:13], v[96:99], v[116:119], v[2:5]
	s_waitcnt lgkmcnt(1)
	v_mfma_f32_16x16x32_bf16 v[2:5], v[78:81], v[120:123], v[70:73]
	s_waitcnt lgkmcnt(0)
	v_mfma_f32_16x16x32_bf16 v[6:9], v[88:91], v[124:127], v[2:5]
	v_mfma_f32_16x16x32_bf16 v[2:5], v[100:103], v[120:123], v[74:77]
	v_mfma_f32_16x16x32_bf16 v[2:5], v[96:99], v[124:127], v[2:5]
	s_setprio 0
	s_movk_i32 s0, 0x100
	v_cmp_gt_u32_e32 vcc, s0, v82
	s_barrier
	s_and_saveexec_b64 s[0:1], vcc
	s_cbranch_execz .LBB0_111
	s_barrier

.LBB0_180:
	ds_read_b128 v[164:167], v151
	ds_read_b128 v[168:171], v151 offset:1024
	ds_read_b128 v[172:175], v151 offset:2048
	ds_read_b128 v[176:179], v151 offset:3072
	v_lshl_add_u64 v[204:205], v[138:139], 0, s[12:13]
	v_lshl_add_u64 v[228:229], v[204:205], 0, s[60:61]
	s_add_i32 m0, s1, 0xc000
	ds_read_b128 v[180:183], v0
	ds_read_b128 v[184:187], v0 offset:1024
	ds_read_b128 v[188:191], v0 offset:2048
	ds_read_b128 v[192:195], v0 offset:3072
	ds_read_b128 v[196:199], v0 offset:4096
	ds_read_b128 v[200:203], v0 offset:5120
	ds_read_b128 v[222:225], v0 offset:6144
	ds_read_b128 v[232:235], v0 offset:7168
	global_load_lds_dwordx4 v[228:229], off
	v_lshl_add_u64 v[210:211], v[140:141], 0, s[12:13]
	s_add_i32 m0, s1, 0xe000
	v_lshl_add_u64 v[152:153], v[210:211], 0, s[60:61]
	global_load_lds_dwordx4 v[152:153], off
	s_waitcnt lgkmcnt(8)
	s_barrier
	s_waitcnt lgkmcnt(0)
	v_mfma_f32_16x16x32_bf16 v[126:129], v[164:167], v[180:183], v[126:129]
	v_mfma_f32_16x16x32_bf16 v[122:125], v[172:175], v[180:183], v[122:125]
	v_mfma_f32_16x16x32_bf16 v[118:121], v[164:167], v[188:191], v[118:121]
	v_mfma_f32_16x16x32_bf16 v[114:117], v[172:175], v[188:191], v[114:117]
	v_mfma_f32_16x16x32_bf16 v[110:113], v[164:167], v[196:199], v[110:113]
	v_mfma_f32_16x16x32_bf16 v[106:109], v[172:175], v[196:199], v[106:109]
	v_mfma_f32_16x16x32_bf16 v[102:105], v[164:167], v[222:225], v[102:105]
	v_mfma_f32_16x16x32_bf16 v[98:101], v[172:175], v[222:225], v[98:101]
	v_mfma_f32_16x16x32_bf16 v[126:129], v[168:171], v[184:187], v[126:129]
	v_mfma_f32_16x16x32_bf16 v[122:125], v[176:179], v[184:187], v[122:125]
	v_mfma_f32_16x16x32_bf16 v[118:121], v[168:171], v[192:195], v[118:121]
	v_mfma_f32_16x16x32_bf16 v[114:117], v[176:179], v[192:195], v[114:117]
	v_mfma_f32_16x16x32_bf16 v[110:113], v[168:171], v[200:203], v[110:113]
	v_mfma_f32_16x16x32_bf16 v[106:109], v[176:179], v[200:203], v[106:109]
	v_mfma_f32_16x16x32_bf16 v[102:105], v[168:171], v[232:235], v[102:105]
	v_mfma_f32_16x16x32_bf16 v[98:101], v[176:179], v[232:235], v[98:101]
	s_barrier
	v_lshl_add_u64 v[216:217], v[134:135], 0, s[12:13]
	s_add_i32 m0, s1, 0xff00
	ds_read_b128 v[236:239], v151 offset:16384
	ds_read_b128 v[240:243], v151 offset:17408
	ds_read_b128 v[244:247], v151 offset:18432
	ds_read_b128 v[248:251], v151 offset:19456
	global_load_lds_dwordx4 v[216:217], off offset:256
	s_add_i32 m0, s1, 0x11f00
	v_lshl_add_u64 v[218:219], v[136:137], 0, s[12:13]
	global_load_lds_dwordx4 v[218:219], off offset:256
	s_barrier
	s_waitcnt lgkmcnt(0)
	v_mfma_f32_16x16x32_bf16 v[94:97], v[236:239], v[180:183], v[94:97]
	v_mfma_f32_16x16x32_bf16 v[90:93], v[244:247], v[180:183], v[90:93]
	v_mfma_f32_16x16x32_bf16 v[86:89], v[236:239], v[188:191], v[86:89]
	v_mfma_f32_16x16x32_bf16 v[82:85], v[244:247], v[188:191], v[82:85]
	v_mfma_f32_16x16x32_bf16 v[78:81], v[236:239], v[196:199], v[78:81]
	v_mfma_f32_16x16x32_bf16 v[74:77], v[244:247], v[196:199], v[74:77]
	v_mfma_f32_16x16x32_bf16 v[70:73], v[236:239], v[222:225], v[70:73]
	v_mfma_f32_16x16x32_bf16 v[66:69], v[244:247], v[222:225], v[66:69]
	v_mfma_f32_16x16x32_bf16 v[94:97], v[240:243], v[184:187], v[94:97]
	v_mfma_f32_16x16x32_bf16 v[90:93], v[248:251], v[184:187], v[90:93]
	v_mfma_f32_16x16x32_bf16 v[86:89], v[240:243], v[192:195], v[86:89]
	v_mfma_f32_16x16x32_bf16 v[82:85], v[248:251], v[192:195], v[82:85]
	v_mfma_f32_16x16x32_bf16 v[78:81], v[240:243], v[200:203], v[78:81]
	v_mfma_f32_16x16x32_bf16 v[74:77], v[248:251], v[200:203], v[74:77]
	v_mfma_f32_16x16x32_bf16 v[70:73], v[240:243], v[232:235], v[70:73]
	v_mfma_f32_16x16x32_bf16 v[66:69], v[248:251], v[232:235], v[66:69]
	v_lshl_add_u64 v[158:159], v[204:205], 0, s[74:75]
	s_mov_b32 m0, s1
	s_barrier
	ds_read_b128 v[180:183], v0 offset:16384
	ds_read_b128 v[184:187], v0 offset:17408
	ds_read_b128 v[188:191], v0 offset:18432
	ds_read_b128 v[192:195], v0 offset:19456
	ds_read_b128 v[196:199], v0 offset:20480
	ds_read_b128 v[200:203], v0 offset:21504
	ds_read_b128 v[222:225], v0 offset:22528
	global_load_lds_dwordx4 v[158:159], off
	s_add_i32 m0, s1, 0x1f00
	ds_read_b128 v[232:235], v0 offset:23552
	global_load_lds_dwordx4 v[210:211], off offset:256
	s_barrier
	s_waitcnt lgkmcnt(0)
	v_mfma_f32_16x16x32_bf16 v[62:65], v[164:167], v[180:183], v[62:65]
	v_mfma_f32_16x16x32_bf16 v[58:61], v[172:175], v[180:183], v[58:61]
	v_mfma_f32_16x16x32_bf16 v[54:57], v[164:167], v[188:191], v[54:57]
	v_mfma_f32_16x16x32_bf16 v[50:53], v[172:175], v[188:191], v[50:53]
	v_mfma_f32_16x16x32_bf16 v[46:49], v[164:167], v[196:199], v[46:49]
	v_mfma_f32_16x16x32_bf16 v[42:45], v[172:175], v[196:199], v[42:45]
	v_mfma_f32_16x16x32_bf16 v[38:41], v[164:167], v[222:225], v[38:41]
	v_mfma_f32_16x16x32_bf16 v[34:37], v[172:175], v[222:225], v[34:37]
	v_mfma_f32_16x16x32_bf16 v[62:65], v[168:171], v[184:187], v[62:65]
	v_mfma_f32_16x16x32_bf16 v[58:61], v[176:179], v[184:187], v[58:61]
	v_mfma_f32_16x16x32_bf16 v[54:57], v[168:171], v[192:195], v[54:57]
	v_mfma_f32_16x16x32_bf16 v[50:53], v[176:179], v[192:195], v[50:53]
	v_mfma_f32_16x16x32_bf16 v[46:49], v[168:171], v[200:203], v[46:49]
	v_mfma_f32_16x16x32_bf16 v[42:45], v[176:179], v[200:203], v[42:45]
	v_mfma_f32_16x16x32_bf16 v[38:41], v[168:171], v[232:235], v[38:41]
	v_mfma_f32_16x16x32_bf16 v[34:37], v[176:179], v[232:235], v[34:37]
	s_barrier
	s_add_i32 m0, s1, 0x14000
	v_lshl_add_u64 v[154:155], v[216:217], 0, s[18:19]
	global_load_lds_dwordx4 v[154:155], off
	s_add_i32 m0, s1, 0x16000
	v_lshl_add_u64 v[156:157], v[218:219], 0, s[18:19]
	global_load_lds_dwordx4 v[156:157], off
	s_waitcnt vmcnt(6)
	s_barrier
	v_mfma_f32_16x16x32_bf16 v[30:33], v[236:239], v[180:183], v[30:33]
	v_mfma_f32_16x16x32_bf16 v[26:29], v[244:247], v[180:183], v[26:29]
	v_mfma_f32_16x16x32_bf16 v[22:25], v[236:239], v[188:191], v[22:25]
	v_mfma_f32_16x16x32_bf16 v[18:21], v[244:247], v[188:191], v[18:21]
	v_mfma_f32_16x16x32_bf16 v[14:17], v[236:239], v[196:199], v[14:17]
	v_mfma_f32_16x16x32_bf16 v[10:13], v[244:247], v[196:199], v[10:13]
	v_mfma_f32_16x16x32_bf16 v[6:9], v[236:239], v[222:225], v[6:9]
	v_mfma_f32_16x16x32_bf16 v[2:5], v[244:247], v[222:225], v[2:5]
	v_mfma_f32_16x16x32_bf16 v[30:33], v[240:243], v[184:187], v[30:33]
	v_mfma_f32_16x16x32_bf16 v[26:29], v[248:251], v[184:187], v[26:29]
	v_mfma_f32_16x16x32_bf16 v[22:25], v[240:243], v[192:195], v[22:25]
	v_mfma_f32_16x16x32_bf16 v[18:21], v[248:251], v[192:195], v[18:21]
	v_mfma_f32_16x16x32_bf16 v[14:17], v[240:243], v[200:203], v[14:17]
	v_mfma_f32_16x16x32_bf16 v[10:13], v[248:251], v[200:203], v[10:13]
	v_mfma_f32_16x16x32_bf16 v[6:9], v[240:243], v[232:235], v[6:9]
	v_mfma_f32_16x16x32_bf16 v[2:5], v[248:251], v[232:235], v[2:5]
	s_barrier
	ds_read_b128 v[164:167], v151 offset:32768
	ds_read_b128 v[168:171], v151 offset:33792
	ds_read_b128 v[172:175], v151 offset:34816
	ds_read_b128 v[176:179], v151 offset:35840
	s_add_i32 m0, s1, 0x3f80
	ds_read_b128 v[180:183], v0 offset:32768
	ds_read_b128 v[184:187], v0 offset:33792
	ds_read_b128 v[188:191], v0 offset:34816
	ds_read_b128 v[192:195], v0 offset:35840
	ds_read_b128 v[196:199], v0 offset:36864
	ds_read_b128 v[200:203], v0 offset:37888
	ds_read_b128 v[222:225], v0 offset:38912
	global_load_lds_dwordx4 v[228:229], off offset:128
	s_add_i32 m0, s1, 0x5f80
	ds_read_b128 v[232:235], v0 offset:39936
	global_load_lds_dwordx4 v[152:153], off offset:128
	s_waitcnt lgkmcnt(8)
	s_barrier
	s_waitcnt lgkmcnt(0)
	v_mfma_f32_16x16x32_bf16 v[126:129], v[164:167], v[180:183], v[126:129]
	v_mfma_f32_16x16x32_bf16 v[122:125], v[172:175], v[180:183], v[122:125]
	v_mfma_f32_16x16x32_bf16 v[118:121], v[164:167], v[188:191], v[118:121]
	v_mfma_f32_16x16x32_bf16 v[114:117], v[172:175], v[188:191], v[114:117]
	v_mfma_f32_16x16x32_bf16 v[110:113], v[164:167], v[196:199], v[110:113]
	v_mfma_f32_16x16x32_bf16 v[106:109], v[172:175], v[196:199], v[106:109]
	v_mfma_f32_16x16x32_bf16 v[102:105], v[164:167], v[222:225], v[102:105]
	v_mfma_f32_16x16x32_bf16 v[98:101], v[172:175], v[222:225], v[98:101]
	v_mfma_f32_16x16x32_bf16 v[126:129], v[168:171], v[184:187], v[126:129]
	v_mfma_f32_16x16x32_bf16 v[122:125], v[176:179], v[184:187], v[122:125]
	v_mfma_f32_16x16x32_bf16 v[118:121], v[168:171], v[192:195], v[118:121]
	v_mfma_f32_16x16x32_bf16 v[114:117], v[176:179], v[192:195], v[114:117]
	v_mfma_f32_16x16x32_bf16 v[110:113], v[168:171], v[200:203], v[110:113]
	v_mfma_f32_16x16x32_bf16 v[106:109], v[176:179], v[200:203], v[106:109]
	v_mfma_f32_16x16x32_bf16 v[102:105], v[168:171], v[232:235], v[102:105]
	v_mfma_f32_16x16x32_bf16 v[98:101], v[176:179], v[232:235], v[98:101]
	s_barrier
	s_add_i32 m0, s1, 0x17e80
	ds_read_b128 v[236:239], v151 offset:49152
	ds_read_b128 v[240:243], v151 offset:50176
	ds_read_b128 v[244:247], v151 offset:51200
	global_load_lds_dwordx4 v[216:217], off offset:384
	s_add_i32 m0, s1, 0x19e80
	ds_read_b128 v[248:251], v151 offset:52224
	global_load_lds_dwordx4 v[218:219], off offset:384
	s_barrier
	s_waitcnt lgkmcnt(0)
	v_mfma_f32_16x16x32_bf16 v[94:97], v[236:239], v[180:183], v[94:97]
	v_mfma_f32_16x16x32_bf16 v[90:93], v[244:247], v[180:183], v[90:93]
	v_mfma_f32_16x16x32_bf16 v[86:89], v[236:239], v[188:191], v[86:89]
	v_mfma_f32_16x16x32_bf16 v[82:85], v[244:247], v[188:191], v[82:85]
	v_mfma_f32_16x16x32_bf16 v[78:81], v[236:239], v[196:199], v[78:81]
	v_mfma_f32_16x16x32_bf16 v[74:77], v[244:247], v[196:199], v[74:77]
	v_mfma_f32_16x16x32_bf16 v[70:73], v[236:239], v[222:225], v[70:73]
	v_mfma_f32_16x16x32_bf16 v[66:69], v[244:247], v[222:225], v[66:69]
	v_mfma_f32_16x16x32_bf16 v[94:97], v[240:243], v[184:187], v[94:97]
	v_mfma_f32_16x16x32_bf16 v[90:93], v[248:251], v[184:187], v[90:93]
	v_mfma_f32_16x16x32_bf16 v[86:89], v[240:243], v[192:195], v[86:89]
	v_mfma_f32_16x16x32_bf16 v[82:85], v[248:251], v[192:195], v[82:85]
	v_mfma_f32_16x16x32_bf16 v[78:81], v[240:243], v[200:203], v[78:81]
	v_mfma_f32_16x16x32_bf16 v[74:77], v[248:251], v[200:203], v[74:77]
	v_mfma_f32_16x16x32_bf16 v[70:73], v[240:243], v[232:235], v[70:73]
	v_mfma_f32_16x16x32_bf16 v[66:69], v[248:251], v[232:235], v[66:69]
	s_add_i32 m0, s1, 0x7e80
	s_barrier
	ds_read_b128 v[180:183], v0 offset:49152
	ds_read_b128 v[184:187], v0 offset:50176
	ds_read_b128 v[188:191], v0 offset:51200
	ds_read_b128 v[192:195], v0 offset:52224
	ds_read_b128 v[196:199], v0 offset:53248
	ds_read_b128 v[200:203], v0 offset:54272
	ds_read_b128 v[222:225], v0 offset:55296
	global_load_lds_dwordx4 v[204:205], off offset:384
	s_add_i32 m0, s1, 0x9e80
	ds_read_b128 v[232:235], v0 offset:56320
	global_load_lds_dwordx4 v[210:211], off offset:384
	s_barrier
	s_waitcnt lgkmcnt(0)
	v_mfma_f32_16x16x32_bf16 v[62:65], v[164:167], v[180:183], v[62:65]
	v_mfma_f32_16x16x32_bf16 v[58:61], v[172:175], v[180:183], v[58:61]
	v_mfma_f32_16x16x32_bf16 v[54:57], v[164:167], v[188:191], v[54:57]
	v_mfma_f32_16x16x32_bf16 v[50:53], v[172:175], v[188:191], v[50:53]
	v_mfma_f32_16x16x32_bf16 v[46:49], v[164:167], v[196:199], v[46:49]
	v_mfma_f32_16x16x32_bf16 v[42:45], v[172:175], v[196:199], v[42:45]
	v_mfma_f32_16x16x32_bf16 v[38:41], v[164:167], v[222:225], v[38:41]
	v_mfma_f32_16x16x32_bf16 v[34:37], v[172:175], v[222:225], v[34:37]
	v_mfma_f32_16x16x32_bf16 v[62:65], v[168:171], v[184:187], v[62:65]
	v_mfma_f32_16x16x32_bf16 v[58:61], v[176:179], v[184:187], v[58:61]
	v_mfma_f32_16x16x32_bf16 v[54:57], v[168:171], v[192:195], v[54:57]
	v_mfma_f32_16x16x32_bf16 v[50:53], v[176:179], v[192:195], v[50:53]
	v_mfma_f32_16x16x32_bf16 v[46:49], v[168:171], v[200:203], v[46:49]
	v_mfma_f32_16x16x32_bf16 v[42:45], v[176:179], v[200:203], v[42:45]
	v_mfma_f32_16x16x32_bf16 v[38:41], v[168:171], v[232:235], v[38:41]
	v_mfma_f32_16x16x32_bf16 v[34:37], v[176:179], v[232:235], v[34:37]
	s_barrier
	s_add_i32 m0, s1, 0x1bf80
	s_nop 0
	global_load_lds_dwordx4 v[154:155], off offset:128
	s_add_i32 m0, s1, 0x1df80
	s_nop 0
	global_load_lds_dwordx4 v[156:157], off offset:128
	s_waitcnt vmcnt(6)
	s_barrier
	v_mfma_f32_16x16x32_bf16 v[30:33], v[236:239], v[180:183], v[30:33]
	v_mfma_f32_16x16x32_bf16 v[26:29], v[244:247], v[180:183], v[26:29]
	v_mfma_f32_16x16x32_bf16 v[22:25], v[236:239], v[188:191], v[22:25]
	v_mfma_f32_16x16x32_bf16 v[18:21], v[244:247], v[188:191], v[18:21]
	v_mfma_f32_16x16x32_bf16 v[14:17], v[236:239], v[196:199], v[14:17]
	v_mfma_f32_16x16x32_bf16 v[10:13], v[244:247], v[196:199], v[10:13]
	v_mfma_f32_16x16x32_bf16 v[6:9], v[236:239], v[222:225], v[6:9]
	v_mfma_f32_16x16x32_bf16 v[2:5], v[244:247], v[222:225], v[2:5]
	v_mfma_f32_16x16x32_bf16 v[30:33], v[240:243], v[184:187], v[30:33]
	v_mfma_f32_16x16x32_bf16 v[26:29], v[248:251], v[184:187], v[26:29]
	v_mfma_f32_16x16x32_bf16 v[22:25], v[240:243], v[192:195], v[22:25]
	v_mfma_f32_16x16x32_bf16 v[18:21], v[248:251], v[192:195], v[18:21]
	v_mfma_f32_16x16x32_bf16 v[14:17], v[240:243], v[200:203], v[14:17]
	v_mfma_f32_16x16x32_bf16 v[10:13], v[248:251], v[200:203], v[10:13]
	v_mfma_f32_16x16x32_bf16 v[6:9], v[240:243], v[232:235], v[6:9]
	v_mfma_f32_16x16x32_bf16 v[2:5], v[248:251], v[232:235], v[2:5]
	s_add_i32 s0, s0, 2
	s_add_u32 s12, s12, 0x100
	s_addc_u32 s13, s13, 0
	s_cmp_lt_u32 s0, 28
	s_barrier
	s_cbranch_scc1 .LBB0_180
	s_add_i32 s1, s1, 0x1e000
	s_mov_b64 s[12:13], 0xf80
	v_readfirstlane_b32 s0, v162
	v_lshl_add_u64 v[132:133], v[132:133], 0, s[12:13]
	s_mov_b32 m0, s0
	v_readfirstlane_b32 s0, v163
	ds_read_b128 v[134:137], v151
	ds_read_b128 v[138:141], v151 offset:1024
	ds_read_b128 v[152:155], v151 offset:2048
	ds_read_b128 v[156:159], v151 offset:3072
	ds_read_b128 v[164:167], v0
	ds_read_b128 v[168:171], v0 offset:1024
	ds_read_b128 v[172:175], v0 offset:2048
	ds_read_b128 v[176:179], v0 offset:3072
	ds_read_b128 v[180:183], v0 offset:4096
	ds_read_b128 v[184:187], v0 offset:5120
	ds_read_b128 v[188:191], v0 offset:6144
	ds_read_b128 v[192:195], v0 offset:7168
	global_load_lds_dwordx4 v[132:133], off
	v_lshl_add_u64 v[130:131], v[130:131], 0, s[12:13]
	s_mov_b32 m0, s0
	s_nop 0
	global_load_lds_dwordx4 v[130:131], off
	s_barrier
	s_waitcnt lgkmcnt(0)
	s_setprio 1
	s_waitcnt lgkmcnt(0)
	v_mfma_f32_16x16x32_bf16 v[126:129], v[134:137], v[164:167], v[126:129]
	v_mfma_f32_16x16x32_bf16 v[122:125], v[152:155], v[164:167], v[122:125]
	v_mfma_f32_16x16x32_bf16 v[114:117], v[152:155], v[172:175], v[114:117]
	v_mfma_f32_16x16x32_bf16 v[106:109], v[152:155], v[180:183], v[106:109]
	v_mfma_f32_16x16x32_bf16 v[98:101], v[152:155], v[188:191], v[98:101]
	v_mfma_f32_16x16x32_bf16 v[126:129], v[138:141], v[168:171], v[126:129]
	v_mfma_f32_16x16x32_bf16 v[122:125], v[156:159], v[168:171], v[122:125]
	v_mfma_f32_16x16x32_bf16 v[118:121], v[134:137], v[172:175], v[118:121]
	v_mfma_f32_16x16x32_bf16 v[114:117], v[156:159], v[176:179], v[114:117]
	v_mfma_f32_16x16x32_bf16 v[110:113], v[134:137], v[180:183], v[110:113]
	v_mfma_f32_16x16x32_bf16 v[106:109], v[156:159], v[184:187], v[106:109]
	v_mfma_f32_16x16x32_bf16 v[102:105], v[134:137], v[188:191], v[102:105]
	v_mfma_f32_16x16x32_bf16 v[98:101], v[156:159], v[192:195], v[98:101]
	v_mfma_f32_16x16x32_bf16 v[130:133], v[138:141], v[176:179], v[118:121]
	v_mfma_f32_16x16x32_bf16 v[160:163], v[138:141], v[184:187], v[110:113]
	v_mfma_f32_16x16x32_bf16 v[196:199], v[138:141], v[192:195], v[102:105]
	s_setprio 0
	s_barrier
	s_nop 0
	ds_read_b128 v[102:105], v151 offset:16384
	ds_read_b128 v[110:113], v151 offset:17408
	ds_read_b128 v[118:121], v151 offset:18432
	ds_read_b128 v[200:203], v151 offset:19456
	s_barrier
	s_waitcnt lgkmcnt(0)
	s_setprio 1
	s_waitcnt lgkmcnt(1)
	v_mfma_f32_16x16x32_bf16 v[90:93], v[118:121], v[164:167], v[90:93]
	v_mfma_f32_16x16x32_bf16 v[82:85], v[118:121], v[172:175], v[82:85]
	v_mfma_f32_16x16x32_bf16 v[74:77], v[118:121], v[180:183], v[74:77]
	v_mfma_f32_16x16x32_bf16 v[66:69], v[118:121], v[188:191], v[66:69]
	v_mfma_f32_16x16x32_bf16 v[94:97], v[102:105], v[164:167], v[94:97]
	s_waitcnt lgkmcnt(0)
	v_mfma_f32_16x16x32_bf16 v[90:93], v[200:203], v[168:171], v[90:93]
	v_mfma_f32_16x16x32_bf16 v[86:89], v[102:105], v[172:175], v[86:89]
	v_mfma_f32_16x16x32_bf16 v[82:85], v[200:203], v[176:179], v[82:85]
	v_mfma_f32_16x16x32_bf16 v[78:81], v[102:105], v[180:183], v[78:81]
	v_mfma_f32_16x16x32_bf16 v[74:77], v[200:203], v[184:187], v[74:77]
	v_mfma_f32_16x16x32_bf16 v[70:73], v[102:105], v[188:191], v[70:73]
	v_mfma_f32_16x16x32_bf16 v[66:69], v[200:203], v[192:195], v[66:69]
	v_mfma_f32_16x16x32_bf16 v[222:225], v[110:113], v[168:171], v[94:97]
	v_mfma_f32_16x16x32_bf16 v[164:167], v[110:113], v[176:179], v[86:89]
	v_mfma_f32_16x16x32_bf16 v[168:171], v[110:113], v[184:187], v[78:81]
	v_mfma_f32_16x16x32_bf16 v[172:175], v[110:113], v[192:195], v[70:73]
	s_setprio 0
	s_barrier
	s_nop 0
	ds_read_b128 v[70:73], v0 offset:16384
	ds_read_b128 v[78:81], v0 offset:17408
	ds_read_b128 v[86:89], v0 offset:18432
	ds_read_b128 v[94:97], v0 offset:19456
	ds_read_b128 v[176:179], v0 offset:20480
	ds_read_b128 v[180:183], v0 offset:21504
	ds_read_b128 v[184:187], v0 offset:22528
	ds_read_b128 v[188:191], v0 offset:23552
	s_waitcnt vmcnt(4)
	s_barrier
	s_waitcnt lgkmcnt(0)
	s_setprio 1
	s_waitcnt lgkmcnt(7)
	v_mfma_f32_16x16x32_bf16 v[62:65], v[134:137], v[70:73], v[62:65]
	v_mfma_f32_16x16x32_bf16 v[58:61], v[152:155], v[70:73], v[58:61]
	s_waitcnt lgkmcnt(5)
	v_mfma_f32_16x16x32_bf16 v[50:53], v[152:155], v[86:89], v[50:53]
	s_waitcnt lgkmcnt(3)
	v_mfma_f32_16x16x32_bf16 v[42:45], v[152:155], v[176:179], v[42:45]
	s_waitcnt lgkmcnt(1)
	v_mfma_f32_16x16x32_bf16 v[34:37], v[152:155], v[184:187], v[34:37]
	v_mfma_f32_16x16x32_bf16 v[62:65], v[138:141], v[78:81], v[62:65]
	v_mfma_f32_16x16x32_bf16 v[58:61], v[156:159], v[78:81], v[58:61]
	v_mfma_f32_16x16x32_bf16 v[54:57], v[134:137], v[86:89], v[54:57]
	v_mfma_f32_16x16x32_bf16 v[50:53], v[156:159], v[94:97], v[50:53]
	v_mfma_f32_16x16x32_bf16 v[46:49], v[134:137], v[176:179], v[46:49]
	v_mfma_f32_16x16x32_bf16 v[42:45], v[156:159], v[180:183], v[42:45]
	v_mfma_f32_16x16x32_bf16 v[38:41], v[134:137], v[184:187], v[38:41]
	s_waitcnt lgkmcnt(0)
	v_mfma_f32_16x16x32_bf16 v[34:37], v[156:159], v[188:191], v[34:37]
	v_mfma_f32_16x16x32_bf16 v[192:195], v[138:141], v[94:97], v[54:57]
	v_mfma_f32_16x16x32_bf16 v[232:235], v[138:141], v[180:183], v[46:49]
	v_mfma_f32_16x16x32_bf16 v[134:137], v[138:141], v[188:191], v[38:41]
	s_setprio 0
	s_setprio 1
	v_mfma_f32_16x16x32_bf16 v[26:29], v[118:121], v[70:73], v[26:29]
	v_mfma_f32_16x16x32_bf16 v[18:21], v[118:121], v[86:89], v[18:21]
	v_mfma_f32_16x16x32_bf16 v[10:13], v[118:121], v[176:179], v[10:13]
	v_mfma_f32_16x16x32_bf16 v[2:5], v[118:121], v[184:187], v[2:5]
	v_mfma_f32_16x16x32_bf16 v[30:33], v[102:105], v[70:73], v[30:33]
	v_mfma_f32_16x16x32_bf16 v[26:29], v[200:203], v[78:81], v[26:29]
	v_mfma_f32_16x16x32_bf16 v[22:25], v[102:105], v[86:89], v[22:25]
	v_mfma_f32_16x16x32_bf16 v[18:21], v[200:203], v[94:97], v[18:21]
	v_mfma_f32_16x16x32_bf16 v[14:17], v[102:105], v[176:179], v[14:17]
	v_mfma_f32_16x16x32_bf16 v[10:13], v[200:203], v[180:183], v[10:13]
	v_mfma_f32_16x16x32_bf16 v[6:9], v[102:105], v[184:187], v[6:9]
	v_mfma_f32_16x16x32_bf16 v[2:5], v[200:203], v[188:191], v[2:5]
	v_mfma_f32_16x16x32_bf16 v[138:141], v[110:113], v[78:81], v[30:33]
	v_mfma_f32_16x16x32_bf16 v[152:155], v[110:113], v[94:97], v[22:25]
	v_mfma_f32_16x16x32_bf16 v[156:159], v[110:113], v[180:183], v[14:17]
	v_mfma_f32_16x16x32_bf16 v[176:179], v[110:113], v[188:191], v[6:9]
	s_setprio 0
	s_barrier
	s_nop 0
	ds_read_b128 v[6:9], v151 offset:32768
	ds_read_b128 v[14:17], v151 offset:33792
	ds_read_b128 v[180:183], v151 offset:34816
	ds_read_b128 v[184:187], v151 offset:35840
	ds_read_b128 v[22:25], v0 offset:32768
	ds_read_b128 v[30:33], v0 offset:33792
	ds_read_b128 v[38:41], v0 offset:34816
	ds_read_b128 v[46:49], v0 offset:35840
	ds_read_b128 v[54:57], v0 offset:36864
	ds_read_b128 v[188:191], v0 offset:37888
	ds_read_b128 v[200:203], v0 offset:38912
	ds_read_b128 v[236:239], v0 offset:39936
	s_waitcnt vmcnt(2)
	s_barrier
	s_waitcnt lgkmcnt(0)
	s_setprio 1
	s_waitcnt lgkmcnt(7)
	v_mfma_f32_16x16x32_bf16 v[70:73], v[6:9], v[22:25], v[126:129]
	s_waitcnt lgkmcnt(6)
	v_mfma_f32_16x16x32_bf16 v[126:129], v[14:17], v[30:33], v[70:73]
	v_mfma_f32_16x16x32_bf16 v[70:73], v[180:183], v[22:25], v[122:125]
	v_mfma_f32_16x16x32_bf16 v[118:121], v[184:187], v[30:33], v[70:73]
	s_waitcnt lgkmcnt(5)
	v_mfma_f32_16x16x32_bf16 v[70:73], v[6:9], v[38:41], v[130:133]
	s_waitcnt lgkmcnt(4)
	v_mfma_f32_16x16x32_bf16 v[110:113], v[14:17], v[46:49], v[70:73]
	v_mfma_f32_16x16x32_bf16 v[70:73], v[180:183], v[38:41], v[114:117]
	v_mfma_f32_16x16x32_bf16 v[102:105], v[184:187], v[46:49], v[70:73]
	s_waitcnt lgkmcnt(3)
	v_mfma_f32_16x16x32_bf16 v[70:73], v[6:9], v[54:57], v[160:163]
	s_waitcnt lgkmcnt(2)
	v_mfma_f32_16x16x32_bf16 v[94:97], v[14:17], v[188:191], v[70:73]
	v_mfma_f32_16x16x32_bf16 v[70:73], v[180:183], v[54:57], v[106:109]
	v_mfma_f32_16x16x32_bf16 v[86:89], v[184:187], v[188:191], v[70:73]
	s_waitcnt lgkmcnt(1)
	v_mfma_f32_16x16x32_bf16 v[70:73], v[6:9], v[200:203], v[196:199]
	s_waitcnt lgkmcnt(0)
	v_mfma_f32_16x16x32_bf16 v[78:81], v[14:17], v[236:239], v[70:73]
	v_mfma_f32_16x16x32_bf16 v[70:73], v[180:183], v[200:203], v[98:101]
	v_mfma_f32_16x16x32_bf16 v[70:73], v[184:187], v[236:239], v[70:73]
	s_setprio 0
	s_barrier
	ds_read_b128 v[130:133], v151 offset:49152
	ds_read_b128 v[160:163], v151 offset:50176
	ds_read_b128 v[196:199], v151 offset:51200
	ds_read_b128 v[148:151], v151 offset:52224
	s_waitcnt vmcnt(0)
	s_barrier
	s_waitcnt lgkmcnt(0)
	s_setprio 1
	s_waitcnt lgkmcnt(3)
	v_mfma_f32_16x16x32_bf16 v[98:101], v[130:133], v[22:25], v[222:225]
	s_waitcnt lgkmcnt(1)
	v_mfma_f32_16x16x32_bf16 v[22:25], v[196:199], v[22:25], v[90:93]
	s_waitcnt lgkmcnt(0)
	v_mfma_f32_16x16x32_bf16 v[114:117], v[148:151], v[30:33], v[22:25]
	v_mfma_f32_16x16x32_bf16 v[22:25], v[130:133], v[38:41], v[164:167]
	v_mfma_f32_16x16x32_bf16 v[106:109], v[160:163], v[46:49], v[22:25]
	v_mfma_f32_16x16x32_bf16 v[22:25], v[196:199], v[38:41], v[82:85]
	v_mfma_f32_16x16x32_bf16 v[122:125], v[160:163], v[30:33], v[98:101]
	v_mfma_f32_16x16x32_bf16 v[98:101], v[148:151], v[46:49], v[22:25]
	v_mfma_f32_16x16x32_bf16 v[22:25], v[130:133], v[54:57], v[168:171]
	v_mfma_f32_16x16x32_bf16 v[90:93], v[160:163], v[188:191], v[22:25]
	v_mfma_f32_16x16x32_bf16 v[22:25], v[196:199], v[54:57], v[74:77]
	v_mfma_f32_16x16x32_bf16 v[82:85], v[148:151], v[188:191], v[22:25]
	v_mfma_f32_16x16x32_bf16 v[22:25], v[130:133], v[200:203], v[172:175]
	v_mfma_f32_16x16x32_bf16 v[74:77], v[160:163], v[236:239], v[22:25]
	v_mfma_f32_16x16x32_bf16 v[22:25], v[196:199], v[200:203], v[66:69]
	v_mfma_f32_16x16x32_bf16 v[66:69], v[148:151], v[236:239], v[22:25]
	s_setprio 0
	s_barrier
	ds_read_b128 v[164:167], v0 offset:49152
	ds_read_b128 v[168:171], v0 offset:50176
	ds_read_b128 v[172:175], v0 offset:51200
	ds_read_b128 v[188:191], v0 offset:52224
	ds_read_b128 v[200:203], v0 offset:53248
	ds_read_b128 v[222:225], v0 offset:54272
	ds_read_b128 v[236:239], v0 offset:55296
	ds_read_b128 v[240:243], v0 offset:56320
	s_barrier
	s_waitcnt lgkmcnt(0)
	s_setprio 1
	s_waitcnt lgkmcnt(7)
	v_mfma_f32_16x16x32_bf16 v[22:25], v[6:9], v[164:167], v[62:65]
	s_waitcnt lgkmcnt(6)
	v_mfma_f32_16x16x32_bf16 v[62:65], v[14:17], v[168:171], v[22:25]
	v_mfma_f32_16x16x32_bf16 v[22:25], v[180:183], v[164:167], v[58:61]
	v_mfma_f32_16x16x32_bf16 v[54:57], v[184:187], v[168:171], v[22:25]
	s_waitcnt lgkmcnt(5)
	v_mfma_f32_16x16x32_bf16 v[22:25], v[6:9], v[172:175], v[192:195]
	s_waitcnt lgkmcnt(4)
	v_mfma_f32_16x16x32_bf16 v[46:49], v[14:17], v[188:191], v[22:25]
	v_mfma_f32_16x16x32_bf16 v[22:25], v[180:183], v[172:175], v[50:53]
	v_mfma_f32_16x16x32_bf16 v[38:41], v[184:187], v[188:191], v[22:25]
	s_waitcnt lgkmcnt(3)
	v_mfma_f32_16x16x32_bf16 v[22:25], v[6:9], v[200:203], v[232:235]
	s_waitcnt lgkmcnt(1)
	v_mfma_f32_16x16x32_bf16 v[6:9], v[6:9], v[236:239], v[134:137]
	v_mfma_f32_16x16x32_bf16 v[30:33], v[14:17], v[222:225], v[22:25]
	v_mfma_f32_16x16x32_bf16 v[22:25], v[180:183], v[200:203], v[42:45]
	s_waitcnt lgkmcnt(0)
	v_mfma_f32_16x16x32_bf16 v[14:17], v[14:17], v[240:243], v[6:9]
	v_mfma_f32_16x16x32_bf16 v[6:9], v[180:183], v[236:239], v[34:37]
	v_mfma_f32_16x16x32_bf16 v[22:25], v[184:187], v[222:225], v[22:25]
	v_mfma_f32_16x16x32_bf16 v[6:9], v[184:187], v[240:243], v[6:9]
	s_setprio 0
	s_setprio 1
	v_mfma_f32_16x16x32_bf16 v[34:37], v[130:133], v[164:167], v[138:141]
	v_mfma_f32_16x16x32_bf16 v[26:29], v[196:199], v[164:167], v[26:29]
	v_mfma_f32_16x16x32_bf16 v[18:21], v[196:199], v[172:175], v[18:21]
	v_mfma_f32_16x16x32_bf16 v[58:61], v[160:163], v[168:171], v[34:37]
	v_mfma_f32_16x16x32_bf16 v[50:53], v[148:151], v[168:171], v[26:29]
	v_mfma_f32_16x16x32_bf16 v[26:29], v[130:133], v[172:175], v[152:155]
	v_mfma_f32_16x16x32_bf16 v[34:37], v[148:151], v[188:191], v[18:21]
	v_mfma_f32_16x16x32_bf16 v[18:21], v[130:133], v[200:203], v[156:159]
	v_mfma_f32_16x16x32_bf16 v[10:13], v[196:199], v[200:203], v[10:13]
	v_mfma_f32_16x16x32_bf16 v[42:45], v[160:163], v[188:191], v[26:29]
	v_mfma_f32_16x16x32_bf16 v[26:29], v[160:163], v[222:225], v[18:21]
	v_mfma_f32_16x16x32_bf16 v[18:21], v[148:151], v[222:225], v[10:13]
	v_mfma_f32_16x16x32_bf16 v[10:13], v[130:133], v[236:239], v[176:179]
	v_mfma_f32_16x16x32_bf16 v[2:5], v[196:199], v[236:239], v[2:5]
	v_mfma_f32_16x16x32_bf16 v[10:13], v[160:163], v[240:243], v[10:13]
	v_mfma_f32_16x16x32_bf16 v[2:5], v[148:151], v[240:243], v[2:5]
	s_setprio 0
	s_movk_i32 s0, 0x100
	v_cmp_gt_u32_e32 vcc, s0, v142
	s_barrier
	s_and_saveexec_b64 s[0:1], vcc
	s_cbranch_execz .LBB0_183
	s_barrier

.LBB0_678:
	ds_read_b128 v[164:167], v151
	ds_read_b128 v[168:171], v151 offset:1024
	ds_read_b128 v[172:175], v151 offset:2048
	ds_read_b128 v[176:179], v151 offset:3072
	v_lshl_add_u64 v[204:205], v[138:139], 0, s[8:9]
	v_lshl_add_u64 v[218:219], v[204:205], 0, s[60:61]
	s_add_i32 m0, s1, 0xc000
	ds_read_b128 v[180:183], v0
	ds_read_b128 v[184:187], v0 offset:1024
	ds_read_b128 v[188:191], v0 offset:2048
	ds_read_b128 v[192:195], v0 offset:3072
	ds_read_b128 v[196:199], v0 offset:4096
	ds_read_b128 v[200:203], v0 offset:5120
	ds_read_b128 v[232:235], v0 offset:6144
	ds_read_b128 v[236:239], v0 offset:7168
	global_load_lds_dwordx4 v[218:219], off
	v_lshl_add_u64 v[216:217], v[140:141], 0, s[8:9]
	s_add_i32 m0, s1, 0xe000
	v_lshl_add_u64 v[152:153], v[216:217], 0, s[60:61]
	global_load_lds_dwordx4 v[152:153], off
	s_waitcnt lgkmcnt(8)
	s_barrier
	s_waitcnt lgkmcnt(0)
	v_mfma_f32_16x16x32_bf16 v[126:129], v[164:167], v[180:183], v[126:129]
	v_mfma_f32_16x16x32_bf16 v[122:125], v[172:175], v[180:183], v[122:125]
	v_mfma_f32_16x16x32_bf16 v[118:121], v[164:167], v[188:191], v[118:121]
	v_mfma_f32_16x16x32_bf16 v[114:117], v[172:175], v[188:191], v[114:117]
	v_mfma_f32_16x16x32_bf16 v[110:113], v[164:167], v[196:199], v[110:113]
	v_mfma_f32_16x16x32_bf16 v[106:109], v[172:175], v[196:199], v[106:109]
	v_mfma_f32_16x16x32_bf16 v[102:105], v[164:167], v[232:235], v[102:105]
	v_mfma_f32_16x16x32_bf16 v[98:101], v[172:175], v[232:235], v[98:101]
	v_mfma_f32_16x16x32_bf16 v[126:129], v[168:171], v[184:187], v[126:129]
	v_mfma_f32_16x16x32_bf16 v[122:125], v[176:179], v[184:187], v[122:125]
	v_mfma_f32_16x16x32_bf16 v[118:121], v[168:171], v[192:195], v[118:121]
	v_mfma_f32_16x16x32_bf16 v[114:117], v[176:179], v[192:195], v[114:117]
	v_mfma_f32_16x16x32_bf16 v[110:113], v[168:171], v[200:203], v[110:113]
	v_mfma_f32_16x16x32_bf16 v[106:109], v[176:179], v[200:203], v[106:109]
	v_mfma_f32_16x16x32_bf16 v[102:105], v[168:171], v[236:239], v[102:105]
	v_mfma_f32_16x16x32_bf16 v[98:101], v[176:179], v[236:239], v[98:101]
	s_barrier
	v_lshl_add_u64 v[210:211], v[134:135], 0, s[8:9]
	s_add_i32 m0, s1, 0xff00
	ds_read_b128 v[240:243], v151 offset:16384
	ds_read_b128 v[244:247], v151 offset:17408
	ds_read_b128 v[248:251], v151 offset:18432
	ds_read_b128 v[222:225], v151 offset:19456
	global_load_lds_dwordx4 v[210:211], off offset:256
	s_add_i32 m0, s1, 0x11f00
	v_lshl_add_u64 v[228:229], v[136:137], 0, s[8:9]
	global_load_lds_dwordx4 v[228:229], off offset:256
	s_barrier
	s_waitcnt lgkmcnt(0)
	v_mfma_f32_16x16x32_bf16 v[94:97], v[240:243], v[180:183], v[94:97]
	v_mfma_f32_16x16x32_bf16 v[90:93], v[248:251], v[180:183], v[90:93]
	v_mfma_f32_16x16x32_bf16 v[86:89], v[240:243], v[188:191], v[86:89]
	v_mfma_f32_16x16x32_bf16 v[82:85], v[248:251], v[188:191], v[82:85]
	v_mfma_f32_16x16x32_bf16 v[78:81], v[240:243], v[196:199], v[78:81]
	v_mfma_f32_16x16x32_bf16 v[74:77], v[248:251], v[196:199], v[74:77]
	v_mfma_f32_16x16x32_bf16 v[70:73], v[240:243], v[232:235], v[70:73]
	v_mfma_f32_16x16x32_bf16 v[66:69], v[248:251], v[232:235], v[66:69]
	v_mfma_f32_16x16x32_bf16 v[94:97], v[244:247], v[184:187], v[94:97]
	v_mfma_f32_16x16x32_bf16 v[90:93], v[222:225], v[184:187], v[90:93]
	v_mfma_f32_16x16x32_bf16 v[86:89], v[244:247], v[192:195], v[86:89]
	v_mfma_f32_16x16x32_bf16 v[82:85], v[222:225], v[192:195], v[82:85]
	v_mfma_f32_16x16x32_bf16 v[78:81], v[244:247], v[200:203], v[78:81]
	v_mfma_f32_16x16x32_bf16 v[74:77], v[222:225], v[200:203], v[74:77]
	v_mfma_f32_16x16x32_bf16 v[70:73], v[244:247], v[236:239], v[70:73]
	v_mfma_f32_16x16x32_bf16 v[66:69], v[222:225], v[236:239], v[66:69]
	v_lshl_add_u64 v[158:159], v[204:205], 0, s[74:75]
	s_mov_b32 m0, s1
	s_barrier
	ds_read_b128 v[180:183], v0 offset:16384
	ds_read_b128 v[184:187], v0 offset:17408
	ds_read_b128 v[188:191], v0 offset:18432
	ds_read_b128 v[192:195], v0 offset:19456
	ds_read_b128 v[196:199], v0 offset:20480
	ds_read_b128 v[200:203], v0 offset:21504
	ds_read_b128 v[232:235], v0 offset:22528
	global_load_lds_dwordx4 v[158:159], off
	s_add_i32 m0, s1, 0x1f00
	ds_read_b128 v[236:239], v0 offset:23552
	global_load_lds_dwordx4 v[216:217], off offset:256
	s_barrier
	s_waitcnt lgkmcnt(0)
	v_mfma_f32_16x16x32_bf16 v[62:65], v[164:167], v[180:183], v[62:65]
	v_mfma_f32_16x16x32_bf16 v[58:61], v[172:175], v[180:183], v[58:61]
	v_mfma_f32_16x16x32_bf16 v[54:57], v[164:167], v[188:191], v[54:57]
	v_mfma_f32_16x16x32_bf16 v[50:53], v[172:175], v[188:191], v[50:53]
	v_mfma_f32_16x16x32_bf16 v[46:49], v[164:167], v[196:199], v[46:49]
	v_mfma_f32_16x16x32_bf16 v[42:45], v[172:175], v[196:199], v[42:45]
	v_mfma_f32_16x16x32_bf16 v[38:41], v[164:167], v[232:235], v[38:41]
	v_mfma_f32_16x16x32_bf16 v[34:37], v[172:175], v[232:235], v[34:37]
	v_mfma_f32_16x16x32_bf16 v[62:65], v[168:171], v[184:187], v[62:65]
	v_mfma_f32_16x16x32_bf16 v[58:61], v[176:179], v[184:187], v[58:61]
	v_mfma_f32_16x16x32_bf16 v[54:57], v[168:171], v[192:195], v[54:57]
	v_mfma_f32_16x16x32_bf16 v[50:53], v[176:179], v[192:195], v[50:53]
	v_mfma_f32_16x16x32_bf16 v[46:49], v[168:171], v[200:203], v[46:49]
	v_mfma_f32_16x16x32_bf16 v[42:45], v[176:179], v[200:203], v[42:45]
	v_mfma_f32_16x16x32_bf16 v[38:41], v[168:171], v[236:239], v[38:41]
	v_mfma_f32_16x16x32_bf16 v[34:37], v[176:179], v[236:239], v[34:37]
	s_barrier
	s_add_i32 m0, s1, 0x14000
	v_lshl_add_u64 v[154:155], v[210:211], 0, s[18:19]
	global_load_lds_dwordx4 v[154:155], off
	s_add_i32 m0, s1, 0x16000
	v_lshl_add_u64 v[156:157], v[228:229], 0, s[18:19]
	global_load_lds_dwordx4 v[156:157], off
	s_waitcnt vmcnt(6)
	s_barrier
	v_mfma_f32_16x16x32_bf16 v[30:33], v[240:243], v[180:183], v[30:33]
	v_mfma_f32_16x16x32_bf16 v[26:29], v[248:251], v[180:183], v[26:29]
	v_mfma_f32_16x16x32_bf16 v[22:25], v[240:243], v[188:191], v[22:25]
	v_mfma_f32_16x16x32_bf16 v[18:21], v[248:251], v[188:191], v[18:21]
	v_mfma_f32_16x16x32_bf16 v[14:17], v[240:243], v[196:199], v[14:17]
	v_mfma_f32_16x16x32_bf16 v[10:13], v[248:251], v[196:199], v[10:13]
	v_mfma_f32_16x16x32_bf16 v[6:9], v[240:243], v[232:235], v[6:9]
	v_mfma_f32_16x16x32_bf16 v[2:5], v[248:251], v[232:235], v[2:5]
	v_mfma_f32_16x16x32_bf16 v[30:33], v[244:247], v[184:187], v[30:33]
	v_mfma_f32_16x16x32_bf16 v[26:29], v[222:225], v[184:187], v[26:29]
	v_mfma_f32_16x16x32_bf16 v[22:25], v[244:247], v[192:195], v[22:25]
	v_mfma_f32_16x16x32_bf16 v[18:21], v[222:225], v[192:195], v[18:21]
	v_mfma_f32_16x16x32_bf16 v[14:17], v[244:247], v[200:203], v[14:17]
	v_mfma_f32_16x16x32_bf16 v[10:13], v[222:225], v[200:203], v[10:13]
	v_mfma_f32_16x16x32_bf16 v[6:9], v[244:247], v[236:239], v[6:9]
	v_mfma_f32_16x16x32_bf16 v[2:5], v[222:225], v[236:239], v[2:5]
	s_barrier
	ds_read_b128 v[164:167], v151 offset:32768
	ds_read_b128 v[168:171], v151 offset:33792
	ds_read_b128 v[172:175], v151 offset:34816
	ds_read_b128 v[176:179], v151 offset:35840
	s_add_i32 m0, s1, 0x3f80
	ds_read_b128 v[180:183], v0 offset:32768
	ds_read_b128 v[184:187], v0 offset:33792
	ds_read_b128 v[188:191], v0 offset:34816
	ds_read_b128 v[192:195], v0 offset:35840
	ds_read_b128 v[196:199], v0 offset:36864
	ds_read_b128 v[200:203], v0 offset:37888
	ds_read_b128 v[222:225], v0 offset:38912
	global_load_lds_dwordx4 v[218:219], off offset:128
	s_add_i32 m0, s1, 0x5f80
	ds_read_b128 v[232:235], v0 offset:39936
	global_load_lds_dwordx4 v[152:153], off offset:128
	s_waitcnt lgkmcnt(8)
	s_barrier
	s_waitcnt lgkmcnt(0)
	v_mfma_f32_16x16x32_bf16 v[126:129], v[164:167], v[180:183], v[126:129]
	v_mfma_f32_16x16x32_bf16 v[122:125], v[172:175], v[180:183], v[122:125]
	v_mfma_f32_16x16x32_bf16 v[118:121], v[164:167], v[188:191], v[118:121]
	v_mfma_f32_16x16x32_bf16 v[114:117], v[172:175], v[188:191], v[114:117]
	v_mfma_f32_16x16x32_bf16 v[110:113], v[164:167], v[196:199], v[110:113]
	v_mfma_f32_16x16x32_bf16 v[106:109], v[172:175], v[196:199], v[106:109]
	v_mfma_f32_16x16x32_bf16 v[102:105], v[164:167], v[222:225], v[102:105]
	v_mfma_f32_16x16x32_bf16 v[98:101], v[172:175], v[222:225], v[98:101]
	v_mfma_f32_16x16x32_bf16 v[126:129], v[168:171], v[184:187], v[126:129]
	v_mfma_f32_16x16x32_bf16 v[122:125], v[176:179], v[184:187], v[122:125]
	v_mfma_f32_16x16x32_bf16 v[118:121], v[168:171], v[192:195], v[118:121]
	v_mfma_f32_16x16x32_bf16 v[114:117], v[176:179], v[192:195], v[114:117]
	v_mfma_f32_16x16x32_bf16 v[110:113], v[168:171], v[200:203], v[110:113]
	v_mfma_f32_16x16x32_bf16 v[106:109], v[176:179], v[200:203], v[106:109]
	v_mfma_f32_16x16x32_bf16 v[102:105], v[168:171], v[232:235], v[102:105]
	v_mfma_f32_16x16x32_bf16 v[98:101], v[176:179], v[232:235], v[98:101]
	s_barrier
	s_add_i32 m0, s1, 0x17e80
	ds_read_b128 v[236:239], v151 offset:49152
	ds_read_b128 v[240:243], v151 offset:50176
	ds_read_b128 v[244:247], v151 offset:51200
	global_load_lds_dwordx4 v[210:211], off offset:384
	s_add_i32 m0, s1, 0x19e80
	ds_read_b128 v[248:251], v151 offset:52224
	global_load_lds_dwordx4 v[228:229], off offset:384
	s_barrier
	s_waitcnt lgkmcnt(0)
	v_mfma_f32_16x16x32_bf16 v[94:97], v[236:239], v[180:183], v[94:97]
	v_mfma_f32_16x16x32_bf16 v[90:93], v[244:247], v[180:183], v[90:93]
	v_mfma_f32_16x16x32_bf16 v[86:89], v[236:239], v[188:191], v[86:89]
	v_mfma_f32_16x16x32_bf16 v[82:85], v[244:247], v[188:191], v[82:85]
	v_mfma_f32_16x16x32_bf16 v[78:81], v[236:239], v[196:199], v[78:81]
	v_mfma_f32_16x16x32_bf16 v[74:77], v[244:247], v[196:199], v[74:77]
	v_mfma_f32_16x16x32_bf16 v[70:73], v[236:239], v[222:225], v[70:73]
	v_mfma_f32_16x16x32_bf16 v[66:69], v[244:247], v[222:225], v[66:69]
	v_mfma_f32_16x16x32_bf16 v[94:97], v[240:243], v[184:187], v[94:97]
	v_mfma_f32_16x16x32_bf16 v[90:93], v[248:251], v[184:187], v[90:93]
	v_mfma_f32_16x16x32_bf16 v[86:89], v[240:243], v[192:195], v[86:89]
	v_mfma_f32_16x16x32_bf16 v[82:85], v[248:251], v[192:195], v[82:85]
	v_mfma_f32_16x16x32_bf16 v[78:81], v[240:243], v[200:203], v[78:81]
	v_mfma_f32_16x16x32_bf16 v[74:77], v[248:251], v[200:203], v[74:77]
	v_mfma_f32_16x16x32_bf16 v[70:73], v[240:243], v[232:235], v[70:73]
	v_mfma_f32_16x16x32_bf16 v[66:69], v[248:251], v[232:235], v[66:69]
	s_add_i32 m0, s1, 0x7e80
	s_barrier
	ds_read_b128 v[180:183], v0 offset:49152
	ds_read_b128 v[184:187], v0 offset:50176
	ds_read_b128 v[188:191], v0 offset:51200
	ds_read_b128 v[192:195], v0 offset:52224
	ds_read_b128 v[196:199], v0 offset:53248
	ds_read_b128 v[200:203], v0 offset:54272
	ds_read_b128 v[222:225], v0 offset:55296
	global_load_lds_dwordx4 v[204:205], off offset:384
	s_add_i32 m0, s1, 0x9e80
	ds_read_b128 v[232:235], v0 offset:56320
	global_load_lds_dwordx4 v[216:217], off offset:384
	s_barrier
	s_waitcnt lgkmcnt(0)
	v_mfma_f32_16x16x32_bf16 v[62:65], v[164:167], v[180:183], v[62:65]
	v_mfma_f32_16x16x32_bf16 v[58:61], v[172:175], v[180:183], v[58:61]
	v_mfma_f32_16x16x32_bf16 v[54:57], v[164:167], v[188:191], v[54:57]
	v_mfma_f32_16x16x32_bf16 v[50:53], v[172:175], v[188:191], v[50:53]
	v_mfma_f32_16x16x32_bf16 v[46:49], v[164:167], v[196:199], v[46:49]
	v_mfma_f32_16x16x32_bf16 v[42:45], v[172:175], v[196:199], v[42:45]
	v_mfma_f32_16x16x32_bf16 v[38:41], v[164:167], v[222:225], v[38:41]
	v_mfma_f32_16x16x32_bf16 v[34:37], v[172:175], v[222:225], v[34:37]
	v_mfma_f32_16x16x32_bf16 v[62:65], v[168:171], v[184:187], v[62:65]
	v_mfma_f32_16x16x32_bf16 v[58:61], v[176:179], v[184:187], v[58:61]
	v_mfma_f32_16x16x32_bf16 v[54:57], v[168:171], v[192:195], v[54:57]
	v_mfma_f32_16x16x32_bf16 v[50:53], v[176:179], v[192:195], v[50:53]
	v_mfma_f32_16x16x32_bf16 v[46:49], v[168:171], v[200:203], v[46:49]
	v_mfma_f32_16x16x32_bf16 v[42:45], v[176:179], v[200:203], v[42:45]
	v_mfma_f32_16x16x32_bf16 v[38:41], v[168:171], v[232:235], v[38:41]
	v_mfma_f32_16x16x32_bf16 v[34:37], v[176:179], v[232:235], v[34:37]
	s_barrier
	s_add_i32 m0, s1, 0x1bf80
	s_nop 0
	global_load_lds_dwordx4 v[154:155], off offset:128
	s_add_i32 m0, s1, 0x1df80
	s_nop 0
	global_load_lds_dwordx4 v[156:157], off offset:128
	s_waitcnt vmcnt(6)
	s_barrier
	v_mfma_f32_16x16x32_bf16 v[30:33], v[236:239], v[180:183], v[30:33]
	v_mfma_f32_16x16x32_bf16 v[26:29], v[244:247], v[180:183], v[26:29]
	v_mfma_f32_16x16x32_bf16 v[22:25], v[236:239], v[188:191], v[22:25]
	v_mfma_f32_16x16x32_bf16 v[18:21], v[244:247], v[188:191], v[18:21]
	v_mfma_f32_16x16x32_bf16 v[14:17], v[236:239], v[196:199], v[14:17]
	v_mfma_f32_16x16x32_bf16 v[10:13], v[244:247], v[196:199], v[10:13]
	v_mfma_f32_16x16x32_bf16 v[6:9], v[236:239], v[222:225], v[6:9]
	v_mfma_f32_16x16x32_bf16 v[2:5], v[244:247], v[222:225], v[2:5]
	v_mfma_f32_16x16x32_bf16 v[30:33], v[240:243], v[184:187], v[30:33]
	v_mfma_f32_16x16x32_bf16 v[26:29], v[248:251], v[184:187], v[26:29]
	v_mfma_f32_16x16x32_bf16 v[22:25], v[240:243], v[192:195], v[22:25]
	v_mfma_f32_16x16x32_bf16 v[18:21], v[248:251], v[192:195], v[18:21]
	v_mfma_f32_16x16x32_bf16 v[14:17], v[240:243], v[200:203], v[14:17]
	v_mfma_f32_16x16x32_bf16 v[10:13], v[248:251], v[200:203], v[10:13]
	v_mfma_f32_16x16x32_bf16 v[6:9], v[240:243], v[232:235], v[6:9]
	v_mfma_f32_16x16x32_bf16 v[2:5], v[248:251], v[232:235], v[2:5]
	s_add_i32 s0, s0, 2
	s_add_u32 s8, s8, 0x100
	s_addc_u32 s9, s9, 0
	s_cmp_lt_u32 s0, 28
	s_barrier
	s_cbranch_scc1 .LBB0_678
	s_add_i32 s1, s1, 0x1e000
	s_mov_b64 s[8:9], 0xf80
	v_readfirstlane_b32 s0, v162
	v_lshl_add_u64 v[132:133], v[132:133], 0, s[8:9]
	s_mov_b32 m0, s0
	v_readfirstlane_b32 s0, v163
	ds_read_b128 v[134:137], v151
	ds_read_b128 v[138:141], v151 offset:1024
	ds_read_b128 v[152:155], v151 offset:2048
	ds_read_b128 v[156:159], v151 offset:3072
	ds_read_b128 v[164:167], v0
	ds_read_b128 v[168:171], v0 offset:1024
	ds_read_b128 v[172:175], v0 offset:2048
	ds_read_b128 v[176:179], v0 offset:3072
	ds_read_b128 v[180:183], v0 offset:4096
	ds_read_b128 v[184:187], v0 offset:5120
	ds_read_b128 v[188:191], v0 offset:6144
	ds_read_b128 v[192:195], v0 offset:7168
	global_load_lds_dwordx4 v[132:133], off
	v_lshl_add_u64 v[130:131], v[130:131], 0, s[8:9]
	s_mov_b32 m0, s0
	s_nop 0
	global_load_lds_dwordx4 v[130:131], off
	s_barrier
	s_waitcnt lgkmcnt(0)
	s_setprio 1
	s_waitcnt lgkmcnt(0)
	v_mfma_f32_16x16x32_bf16 v[126:129], v[134:137], v[164:167], v[126:129]
	v_mfma_f32_16x16x32_bf16 v[122:125], v[152:155], v[164:167], v[122:125]
	v_mfma_f32_16x16x32_bf16 v[114:117], v[152:155], v[172:175], v[114:117]
	v_mfma_f32_16x16x32_bf16 v[106:109], v[152:155], v[180:183], v[106:109]
	v_mfma_f32_16x16x32_bf16 v[98:101], v[152:155], v[188:191], v[98:101]
	v_mfma_f32_16x16x32_bf16 v[126:129], v[138:141], v[168:171], v[126:129]
	v_mfma_f32_16x16x32_bf16 v[122:125], v[156:159], v[168:171], v[122:125]
	v_mfma_f32_16x16x32_bf16 v[118:121], v[134:137], v[172:175], v[118:121]
	v_mfma_f32_16x16x32_bf16 v[114:117], v[156:159], v[176:179], v[114:117]
	v_mfma_f32_16x16x32_bf16 v[110:113], v[134:137], v[180:183], v[110:113]
	v_mfma_f32_16x16x32_bf16 v[106:109], v[156:159], v[184:187], v[106:109]
	v_mfma_f32_16x16x32_bf16 v[102:105], v[134:137], v[188:191], v[102:105]
	v_mfma_f32_16x16x32_bf16 v[98:101], v[156:159], v[192:195], v[98:101]
	v_mfma_f32_16x16x32_bf16 v[130:133], v[138:141], v[176:179], v[118:121]
	v_mfma_f32_16x16x32_bf16 v[160:163], v[138:141], v[184:187], v[110:113]
	v_mfma_f32_16x16x32_bf16 v[196:199], v[138:141], v[192:195], v[102:105]
	s_setprio 0
	s_barrier
	s_nop 0
	ds_read_b128 v[102:105], v151 offset:16384
	ds_read_b128 v[110:113], v151 offset:17408
	ds_read_b128 v[118:121], v151 offset:18432
	ds_read_b128 v[200:203], v151 offset:19456
	s_barrier
	s_waitcnt lgkmcnt(0)
	s_setprio 1
	s_waitcnt lgkmcnt(1)
	v_mfma_f32_16x16x32_bf16 v[90:93], v[118:121], v[164:167], v[90:93]
	v_mfma_f32_16x16x32_bf16 v[86:89], v[102:105], v[172:175], v[86:89]
	v_mfma_f32_16x16x32_bf16 v[82:85], v[118:121], v[172:175], v[82:85]
	v_mfma_f32_16x16x32_bf16 v[78:81], v[102:105], v[180:183], v[78:81]
	v_mfma_f32_16x16x32_bf16 v[70:73], v[102:105], v[188:191], v[70:73]
	v_mfma_f32_16x16x32_bf16 v[94:97], v[102:105], v[164:167], v[94:97]
	s_waitcnt lgkmcnt(0)
	v_mfma_f32_16x16x32_bf16 v[90:93], v[200:203], v[168:171], v[90:93]
	v_mfma_f32_16x16x32_bf16 v[86:89], v[110:113], v[176:179], v[86:89]
	v_mfma_f32_16x16x32_bf16 v[82:85], v[200:203], v[176:179], v[82:85]
	v_mfma_f32_16x16x32_bf16 v[78:81], v[110:113], v[184:187], v[78:81]
	v_mfma_f32_16x16x32_bf16 v[74:77], v[118:121], v[180:183], v[74:77]
	v_mfma_f32_16x16x32_bf16 v[70:73], v[110:113], v[192:195], v[70:73]
	v_mfma_f32_16x16x32_bf16 v[66:69], v[118:121], v[188:191], v[66:69]
	v_mfma_f32_16x16x32_bf16 v[222:225], v[110:113], v[168:171], v[94:97]
	v_mfma_f32_16x16x32_bf16 v[164:167], v[200:203], v[184:187], v[74:77]
	v_mfma_f32_16x16x32_bf16 v[168:171], v[200:203], v[192:195], v[66:69]
	s_setprio 0
	s_barrier
	s_nop 2
	ds_read_b128 v[66:69], v0 offset:16384
	ds_read_b128 v[74:77], v0 offset:17408
	ds_read_b128 v[94:97], v0 offset:18432
	ds_read_b128 v[172:175], v0 offset:19456
	ds_read_b128 v[176:179], v0 offset:20480
	ds_read_b128 v[180:183], v0 offset:21504
	ds_read_b128 v[184:187], v0 offset:22528
	ds_read_b128 v[188:191], v0 offset:23552
	s_waitcnt vmcnt(4)
	s_barrier
	s_waitcnt lgkmcnt(0)
	s_setprio 1
	s_waitcnt lgkmcnt(5)
	v_mfma_f32_16x16x32_bf16 v[54:57], v[134:137], v[94:97], v[54:57]
	v_mfma_f32_16x16x32_bf16 v[50:53], v[152:155], v[94:97], v[50:53]
	v_mfma_f32_16x16x32_bf16 v[62:65], v[134:137], v[66:69], v[62:65]
	v_mfma_f32_16x16x32_bf16 v[58:61], v[152:155], v[66:69], v[58:61]
	s_waitcnt lgkmcnt(4)
	v_mfma_f32_16x16x32_bf16 v[54:57], v[138:141], v[172:175], v[54:57]
	v_mfma_f32_16x16x32_bf16 v[50:53], v[156:159], v[172:175], v[50:53]
	s_waitcnt lgkmcnt(3)
	v_mfma_f32_16x16x32_bf16 v[46:49], v[134:137], v[176:179], v[46:49]
	v_mfma_f32_16x16x32_bf16 v[42:45], v[152:155], v[176:179], v[42:45]
	s_waitcnt lgkmcnt(1)
	v_mfma_f32_16x16x32_bf16 v[38:41], v[134:137], v[184:187], v[38:41]
	v_mfma_f32_16x16x32_bf16 v[34:37], v[152:155], v[184:187], v[34:37]
	v_mfma_f32_16x16x32_bf16 v[192:195], v[138:141], v[74:77], v[62:65]
	v_mfma_f32_16x16x32_bf16 v[232:235], v[156:159], v[74:77], v[58:61]
	v_mfma_f32_16x16x32_bf16 v[236:239], v[138:141], v[180:183], v[46:49]
	v_mfma_f32_16x16x32_bf16 v[240:243], v[156:159], v[180:183], v[42:45]
	s_waitcnt lgkmcnt(0)
	v_mfma_f32_16x16x32_bf16 v[134:137], v[138:141], v[188:191], v[38:41]
	v_mfma_f32_16x16x32_bf16 v[138:141], v[156:159], v[188:191], v[34:37]
	s_setprio 0
	s_setprio 1
	v_mfma_f32_16x16x32_bf16 v[30:33], v[102:105], v[66:69], v[30:33]
	v_mfma_f32_16x16x32_bf16 v[26:29], v[118:121], v[66:69], v[26:29]
	v_mfma_f32_16x16x32_bf16 v[14:17], v[102:105], v[176:179], v[14:17]
	v_mfma_f32_16x16x32_bf16 v[10:13], v[118:121], v[176:179], v[10:13]
	v_mfma_f32_16x16x32_bf16 v[30:33], v[110:113], v[74:77], v[30:33]
	v_mfma_f32_16x16x32_bf16 v[26:29], v[200:203], v[74:77], v[26:29]
	v_mfma_f32_16x16x32_bf16 v[22:25], v[102:105], v[94:97], v[22:25]
	v_mfma_f32_16x16x32_bf16 v[18:21], v[118:121], v[94:97], v[18:21]
	v_mfma_f32_16x16x32_bf16 v[14:17], v[110:113], v[180:183], v[14:17]
	v_mfma_f32_16x16x32_bf16 v[10:13], v[200:203], v[180:183], v[10:13]
	v_mfma_f32_16x16x32_bf16 v[6:9], v[102:105], v[184:187], v[6:9]
	v_mfma_f32_16x16x32_bf16 v[2:5], v[118:121], v[184:187], v[2:5]
	v_mfma_f32_16x16x32_bf16 v[152:155], v[110:113], v[172:175], v[22:25]
	v_mfma_f32_16x16x32_bf16 v[156:159], v[200:203], v[172:175], v[18:21]
	v_mfma_f32_16x16x32_bf16 v[172:175], v[110:113], v[188:191], v[6:9]
	v_mfma_f32_16x16x32_bf16 v[176:179], v[200:203], v[188:191], v[2:5]
	s_setprio 0
	s_barrier
	s_nop 1
	ds_read_b128 v[2:5], v151 offset:32768
	ds_read_b128 v[6:9], v151 offset:33792
	ds_read_b128 v[180:183], v151 offset:34816
	ds_read_b128 v[184:187], v151 offset:35840
	ds_read_b128 v[18:21], v0 offset:32768
	ds_read_b128 v[22:25], v0 offset:33792
	ds_read_b128 v[38:41], v0 offset:34816
	ds_read_b128 v[46:49], v0 offset:35840
	ds_read_b128 v[58:61], v0 offset:36864
	ds_read_b128 v[66:69], v0 offset:37888
	ds_read_b128 v[188:191], v0 offset:38912
	ds_read_b128 v[200:203], v0 offset:39936
	s_waitcnt vmcnt(2)
	s_barrier
	s_waitcnt lgkmcnt(0)
	s_setprio 1
	s_waitcnt lgkmcnt(7)
	v_mfma_f32_16x16x32_bf16 v[34:37], v[2:5], v[18:21], v[126:129]
	s_waitcnt lgkmcnt(6)
	v_mfma_f32_16x16x32_bf16 v[118:121], v[6:9], v[22:25], v[34:37]
	v_mfma_f32_16x16x32_bf16 v[34:37], v[180:183], v[18:21], v[122:125]
	v_mfma_f32_16x16x32_bf16 v[110:113], v[184:187], v[22:25], v[34:37]
	s_waitcnt lgkmcnt(5)
	v_mfma_f32_16x16x32_bf16 v[34:37], v[2:5], v[38:41], v[130:133]
	s_waitcnt lgkmcnt(4)
	v_mfma_f32_16x16x32_bf16 v[102:105], v[6:9], v[46:49], v[34:37]
	v_mfma_f32_16x16x32_bf16 v[34:37], v[180:183], v[38:41], v[114:117]
	v_mfma_f32_16x16x32_bf16 v[94:97], v[184:187], v[46:49], v[34:37]
	s_waitcnt lgkmcnt(3)
	v_mfma_f32_16x16x32_bf16 v[34:37], v[2:5], v[58:61], v[160:163]
	s_waitcnt lgkmcnt(2)
	v_mfma_f32_16x16x32_bf16 v[74:77], v[6:9], v[66:69], v[34:37]
	v_mfma_f32_16x16x32_bf16 v[34:37], v[180:183], v[58:61], v[106:109]
	v_mfma_f32_16x16x32_bf16 v[62:65], v[184:187], v[66:69], v[34:37]
	s_waitcnt lgkmcnt(1)
	v_mfma_f32_16x16x32_bf16 v[34:37], v[2:5], v[188:191], v[196:199]
	s_waitcnt lgkmcnt(0)
	v_mfma_f32_16x16x32_bf16 v[42:45], v[6:9], v[200:203], v[34:37]
	v_mfma_f32_16x16x32_bf16 v[34:37], v[180:183], v[188:191], v[98:101]
	v_mfma_f32_16x16x32_bf16 v[34:37], v[184:187], v[200:203], v[34:37]
	s_setprio 0
	s_barrier
	ds_read_b128 v[130:133], v151 offset:49152
	ds_read_b128 v[160:163], v151 offset:50176
	ds_read_b128 v[196:199], v151 offset:51200
	ds_read_b128 v[148:151], v151 offset:52224
	s_waitcnt vmcnt(0)
	s_barrier
	s_waitcnt lgkmcnt(0)
	s_setprio 1
	s_waitcnt lgkmcnt(3)
	v_mfma_f32_16x16x32_bf16 v[98:101], v[130:133], v[18:21], v[222:225]
	s_waitcnt lgkmcnt(1)
	v_mfma_f32_16x16x32_bf16 v[18:21], v[196:199], v[18:21], v[90:93]
	s_waitcnt lgkmcnt(0)
	v_mfma_f32_16x16x32_bf16 v[122:125], v[148:151], v[22:25], v[18:21]
	v_mfma_f32_16x16x32_bf16 v[18:21], v[130:133], v[38:41], v[86:89]
	v_mfma_f32_16x16x32_bf16 v[114:117], v[160:163], v[46:49], v[18:21]
	v_mfma_f32_16x16x32_bf16 v[18:21], v[196:199], v[38:41], v[82:85]
	v_mfma_f32_16x16x32_bf16 v[106:109], v[148:151], v[46:49], v[18:21]
	v_mfma_f32_16x16x32_bf16 v[18:21], v[130:133], v[58:61], v[78:81]
	v_mfma_f32_16x16x32_bf16 v[126:129], v[160:163], v[22:25], v[98:101]
	v_mfma_f32_16x16x32_bf16 v[98:101], v[160:163], v[66:69], v[18:21]
	v_mfma_f32_16x16x32_bf16 v[18:21], v[196:199], v[58:61], v[164:167]
	v_mfma_f32_16x16x32_bf16 v[90:93], v[148:151], v[66:69], v[18:21]
	v_mfma_f32_16x16x32_bf16 v[18:21], v[130:133], v[188:191], v[70:73]
	v_mfma_f32_16x16x32_bf16 v[66:69], v[160:163], v[200:203], v[18:21]
	v_mfma_f32_16x16x32_bf16 v[18:21], v[196:199], v[188:191], v[168:171]
	v_mfma_f32_16x16x32_bf16 v[58:61], v[148:151], v[200:203], v[18:21]
	s_setprio 0
	s_barrier
	ds_read_b128 v[82:85], v0 offset:49152
	ds_read_b128 v[164:167], v0 offset:50176
	ds_read_b128 v[168:171], v0 offset:51200
	ds_read_b128 v[188:191], v0 offset:52224
	ds_read_b128 v[200:203], v0 offset:53248
	ds_read_b128 v[222:225], v0 offset:54272
	ds_read_b128 v[244:247], v0 offset:55296
	ds_read_b128 v[248:251], v0 offset:56320
	s_barrier
	s_waitcnt lgkmcnt(0)
	s_setprio 1
	s_waitcnt lgkmcnt(7)
	v_mfma_f32_16x16x32_bf16 v[18:21], v[2:5], v[82:85], v[192:195]
	s_waitcnt lgkmcnt(6)
	v_mfma_f32_16x16x32_bf16 v[78:81], v[6:9], v[164:167], v[18:21]
	v_mfma_f32_16x16x32_bf16 v[18:21], v[180:183], v[82:85], v[232:235]
	v_mfma_f32_16x16x32_bf16 v[70:73], v[184:187], v[164:167], v[18:21]
	s_waitcnt lgkmcnt(5)
	v_mfma_f32_16x16x32_bf16 v[18:21], v[2:5], v[168:171], v[54:57]
	s_waitcnt lgkmcnt(4)
	v_mfma_f32_16x16x32_bf16 v[46:49], v[6:9], v[188:191], v[18:21]
	v_mfma_f32_16x16x32_bf16 v[18:21], v[180:183], v[168:171], v[50:53]
	v_mfma_f32_16x16x32_bf16 v[38:41], v[184:187], v[188:191], v[18:21]
	s_waitcnt lgkmcnt(3)
	v_mfma_f32_16x16x32_bf16 v[18:21], v[2:5], v[200:203], v[236:239]
	s_waitcnt lgkmcnt(1)
	v_mfma_f32_16x16x32_bf16 v[2:5], v[2:5], v[244:247], v[134:137]
	v_mfma_f32_16x16x32_bf16 v[22:25], v[6:9], v[222:225], v[18:21]
	v_mfma_f32_16x16x32_bf16 v[18:21], v[180:183], v[200:203], v[240:243]
	s_waitcnt lgkmcnt(0)
	v_mfma_f32_16x16x32_bf16 v[6:9], v[6:9], v[248:251], v[2:5]
	v_mfma_f32_16x16x32_bf16 v[2:5], v[180:183], v[244:247], v[138:141]
	v_mfma_f32_16x16x32_bf16 v[18:21], v[184:187], v[222:225], v[18:21]
	v_mfma_f32_16x16x32_bf16 v[2:5], v[184:187], v[248:251], v[2:5]
	s_setprio 0
	s_setprio 1
	v_mfma_f32_16x16x32_bf16 v[26:29], v[196:199], v[82:85], v[26:29]
	v_mfma_f32_16x16x32_bf16 v[30:33], v[130:133], v[82:85], v[30:33]
	v_mfma_f32_16x16x32_bf16 v[82:85], v[148:151], v[164:167], v[26:29]
	v_mfma_f32_16x16x32_bf16 v[26:29], v[130:133], v[168:171], v[152:155]
	v_mfma_f32_16x16x32_bf16 v[54:57], v[160:163], v[188:191], v[26:29]
	v_mfma_f32_16x16x32_bf16 v[26:29], v[196:199], v[168:171], v[156:159]
	v_mfma_f32_16x16x32_bf16 v[10:13], v[196:199], v[200:203], v[10:13]
	v_mfma_f32_16x16x32_bf16 v[50:53], v[148:151], v[188:191], v[26:29]
	v_mfma_f32_16x16x32_bf16 v[14:17], v[130:133], v[200:203], v[14:17]
	v_mfma_f32_16x16x32_bf16 v[26:29], v[148:151], v[222:225], v[10:13]
	v_mfma_f32_16x16x32_bf16 v[10:13], v[130:133], v[244:247], v[172:175]
	v_mfma_f32_16x16x32_bf16 v[86:89], v[160:163], v[164:167], v[30:33]
	v_mfma_f32_16x16x32_bf16 v[30:33], v[160:163], v[222:225], v[14:17]
	v_mfma_f32_16x16x32_bf16 v[14:17], v[160:163], v[248:251], v[10:13]
	v_mfma_f32_16x16x32_bf16 v[10:13], v[196:199], v[244:247], v[176:179]
	v_mfma_f32_16x16x32_bf16 v[10:13], v[148:151], v[248:251], v[10:13]
	s_setprio 0
	s_movk_i32 s0, 0x100
	v_cmp_gt_u32_e32 vcc, s0, v142
	s_barrier
	s_and_saveexec_b64 s[0:1], vcc
	s_cbranch_execz .LBB0_674
	s_barrier
	s_branch .LBB0_674

.LBB0_689:
	ds_read_b128 v[104:107], v95
	ds_read_b128 v[108:111], v95 offset:1024
	ds_read_b128 v[112:115], v95 offset:2048
	ds_read_b128 v[116:119], v95 offset:3072
	v_lshl_add_u64 v[152:153], v[72:73], 0, s[10:11]
	v_lshl_add_u64 v[164:165], v[152:153], 0, s[34:35]
	s_add_i32 m0, s1, 0xc000
	ds_read_b128 v[120:123], v93
	ds_read_b128 v[124:127], v93 offset:1024
	ds_read_b128 v[128:131], v93 offset:2048
	ds_read_b128 v[132:135], v93 offset:3072
	ds_read_b128 v[136:139], v93 offset:4096
	ds_read_b128 v[140:143], v93 offset:5120
	ds_read_b128 v[144:147], v93 offset:6144
	ds_read_b128 v[148:151], v93 offset:7168
	global_load_lds_dwordx4 v[164:165], off
	v_lshl_add_u64 v[154:155], v[74:75], 0, s[10:11]
	s_add_i32 m0, s1, 0xe000
	v_lshl_add_u64 v[86:87], v[154:155], 0, s[34:35]
	global_load_lds_dwordx4 v[86:87], off
	s_waitcnt lgkmcnt(8)
	s_barrier
	s_waitcnt lgkmcnt(0)
	v_mfma_f32_16x16x32_bf16 v[62:65], v[104:107], v[120:123], v[62:65]
	v_mfma_f32_16x16x32_bf16 v[58:61], v[112:115], v[120:123], v[58:61]
	v_mfma_f32_16x16x32_bf16 v[54:57], v[104:107], v[128:131], v[54:57]
	v_mfma_f32_16x16x32_bf16 v[50:53], v[112:115], v[128:131], v[50:53]
	v_mfma_f32_16x16x32_bf16 v[46:49], v[104:107], v[136:139], v[46:49]
	v_mfma_f32_16x16x32_bf16 v[42:45], v[112:115], v[136:139], v[42:45]
	v_mfma_f32_16x16x32_bf16 v[38:41], v[104:107], v[144:147], v[38:41]
	v_mfma_f32_16x16x32_bf16 v[34:37], v[112:115], v[144:147], v[34:37]
	v_mfma_f32_16x16x32_bf16 v[62:65], v[108:111], v[124:127], v[62:65]
	v_mfma_f32_16x16x32_bf16 v[58:61], v[116:119], v[124:127], v[58:61]
	v_mfma_f32_16x16x32_bf16 v[54:57], v[108:111], v[132:135], v[54:57]
	v_mfma_f32_16x16x32_bf16 v[50:53], v[116:119], v[132:135], v[50:53]
	v_mfma_f32_16x16x32_bf16 v[46:49], v[108:111], v[140:143], v[46:49]
	v_mfma_f32_16x16x32_bf16 v[42:45], v[116:119], v[140:143], v[42:45]
	v_mfma_f32_16x16x32_bf16 v[38:41], v[108:111], v[148:151], v[38:41]
	v_mfma_f32_16x16x32_bf16 v[34:37], v[116:119], v[148:151], v[34:37]
	s_barrier
	v_lshl_add_u64 v[156:157], v[68:69], 0, s[10:11]
	s_add_i32 m0, s1, 0xff00
	s_nop 0
	global_load_lds_dwordx4 v[156:157], off offset:256
	s_add_i32 m0, s1, 0x11f00
	v_lshl_add_u64 v[158:159], v[70:71], 0, s[10:11]
	global_load_lds_dwordx4 v[158:159], off offset:256
	v_lshl_add_u64 v[88:89], v[152:153], 0, s[74:75]
	s_mov_b32 m0, s1
	s_barrier
	s_waitcnt lgkmcnt(0)
	s_barrier
	ds_read_b128 v[120:123], v93 offset:16384
	ds_read_b128 v[124:127], v93 offset:17408
	ds_read_b128 v[128:131], v93 offset:18432
	ds_read_b128 v[132:135], v93 offset:19456
	ds_read_b128 v[136:139], v93 offset:20480
	ds_read_b128 v[140:143], v93 offset:21504
	ds_read_b128 v[144:147], v93 offset:22528
	global_load_lds_dwordx4 v[88:89], off
	s_add_i32 m0, s1, 0x1f00
	ds_read_b128 v[148:151], v93 offset:23552
	global_load_lds_dwordx4 v[154:155], off offset:256
	s_barrier
	s_waitcnt lgkmcnt(0)
	v_mfma_f32_16x16x32_bf16 v[2:5], v[104:107], v[120:123], v[2:5]
	v_mfma_f32_16x16x32_bf16 v[6:9], v[112:115], v[120:123], v[6:9]
	v_mfma_f32_16x16x32_bf16 v[10:13], v[104:107], v[128:131], v[10:13]
	v_mfma_f32_16x16x32_bf16 v[14:17], v[112:115], v[128:131], v[14:17]
	v_mfma_f32_16x16x32_bf16 v[18:21], v[104:107], v[136:139], v[18:21]
	v_mfma_f32_16x16x32_bf16 v[22:25], v[112:115], v[136:139], v[22:25]
	v_mfma_f32_16x16x32_bf16 v[26:29], v[104:107], v[144:147], v[26:29]
	v_mfma_f32_16x16x32_bf16 v[30:33], v[112:115], v[144:147], v[30:33]
	v_mfma_f32_16x16x32_bf16 v[2:5], v[108:111], v[124:127], v[2:5]
	v_mfma_f32_16x16x32_bf16 v[6:9], v[116:119], v[124:127], v[6:9]
	v_mfma_f32_16x16x32_bf16 v[10:13], v[108:111], v[132:135], v[10:13]
	v_mfma_f32_16x16x32_bf16 v[14:17], v[116:119], v[132:135], v[14:17]
	v_mfma_f32_16x16x32_bf16 v[18:21], v[108:111], v[140:143], v[18:21]
	v_mfma_f32_16x16x32_bf16 v[22:25], v[116:119], v[140:143], v[22:25]
	v_mfma_f32_16x16x32_bf16 v[26:29], v[108:111], v[148:151], v[26:29]
	v_mfma_f32_16x16x32_bf16 v[30:33], v[116:119], v[148:151], v[30:33]
	s_barrier
	v_lshl_add_u64 v[160:161], v[76:77], 0, s[10:11]
	s_add_i32 m0, s1, 0x13f00
	s_nop 0
	global_load_lds_dwordx4 v[160:161], off offset:256
	s_add_i32 m0, s1, 0x15f00
	v_lshl_add_u64 v[162:163], v[78:79], 0, s[10:11]
	global_load_lds_dwordx4 v[162:163], off offset:256
	s_waitcnt vmcnt(6)
	s_barrier
	s_barrier
	ds_read_b128 v[104:107], v95 offset:32768
	ds_read_b128 v[108:111], v95 offset:33792
	ds_read_b128 v[112:115], v95 offset:34816
	ds_read_b128 v[116:119], v95 offset:35840
	s_add_i32 m0, s1, 0x3f80
	ds_read_b128 v[120:123], v93 offset:32768
	ds_read_b128 v[124:127], v93 offset:33792
	ds_read_b128 v[128:131], v93 offset:34816
	ds_read_b128 v[132:135], v93 offset:35840
	ds_read_b128 v[136:139], v93 offset:36864
	ds_read_b128 v[140:143], v93 offset:37888
	ds_read_b128 v[144:147], v93 offset:38912
	global_load_lds_dwordx4 v[164:165], off offset:128
	s_add_i32 m0, s1, 0x5f80
	ds_read_b128 v[148:151], v93 offset:39936
	global_load_lds_dwordx4 v[86:87], off offset:128
	s_waitcnt lgkmcnt(8)
	s_barrier
	s_waitcnt lgkmcnt(0)
	v_mfma_f32_16x16x32_bf16 v[62:65], v[104:107], v[120:123], v[62:65]
	v_mfma_f32_16x16x32_bf16 v[58:61], v[112:115], v[120:123], v[58:61]
	v_mfma_f32_16x16x32_bf16 v[54:57], v[104:107], v[128:131], v[54:57]
	v_mfma_f32_16x16x32_bf16 v[50:53], v[112:115], v[128:131], v[50:53]
	v_mfma_f32_16x16x32_bf16 v[46:49], v[104:107], v[136:139], v[46:49]
	v_mfma_f32_16x16x32_bf16 v[42:45], v[112:115], v[136:139], v[42:45]
	v_mfma_f32_16x16x32_bf16 v[38:41], v[104:107], v[144:147], v[38:41]
	v_mfma_f32_16x16x32_bf16 v[34:37], v[112:115], v[144:147], v[34:37]
	v_mfma_f32_16x16x32_bf16 v[62:65], v[108:111], v[124:127], v[62:65]
	v_mfma_f32_16x16x32_bf16 v[58:61], v[116:119], v[124:127], v[58:61]
	v_mfma_f32_16x16x32_bf16 v[54:57], v[108:111], v[132:135], v[54:57]
	v_mfma_f32_16x16x32_bf16 v[50:53], v[116:119], v[132:135], v[50:53]
	v_mfma_f32_16x16x32_bf16 v[46:49], v[108:111], v[140:143], v[46:49]
	v_mfma_f32_16x16x32_bf16 v[42:45], v[116:119], v[140:143], v[42:45]
	v_mfma_f32_16x16x32_bf16 v[38:41], v[108:111], v[148:151], v[38:41]
	v_mfma_f32_16x16x32_bf16 v[34:37], v[116:119], v[148:151], v[34:37]
	s_barrier
	s_add_i32 m0, s1, 0x17e80
	s_nop 0
	global_load_lds_dwordx4 v[156:157], off offset:384
	s_add_i32 m0, s1, 0x19e80
	s_nop 0
	global_load_lds_dwordx4 v[158:159], off offset:384
	s_add_i32 m0, s1, 0x7e80
	s_barrier
	s_waitcnt lgkmcnt(0)
	s_barrier
	ds_read_b128 v[120:123], v93 offset:49152
	ds_read_b128 v[124:127], v93 offset:50176
	ds_read_b128 v[128:131], v93 offset:51200
	ds_read_b128 v[132:135], v93 offset:52224
	ds_read_b128 v[136:139], v93 offset:53248
	ds_read_b128 v[140:143], v93 offset:54272
	ds_read_b128 v[144:147], v93 offset:55296
	global_load_lds_dwordx4 v[152:153], off offset:384
	s_add_i32 m0, s1, 0x9e80
	ds_read_b128 v[148:151], v93 offset:56320
	global_load_lds_dwordx4 v[154:155], off offset:384
	s_barrier
	s_waitcnt lgkmcnt(0)
	v_mfma_f32_16x16x32_bf16 v[2:5], v[104:107], v[120:123], v[2:5]
	v_mfma_f32_16x16x32_bf16 v[6:9], v[112:115], v[120:123], v[6:9]
	v_mfma_f32_16x16x32_bf16 v[10:13], v[104:107], v[128:131], v[10:13]
	v_mfma_f32_16x16x32_bf16 v[14:17], v[112:115], v[128:131], v[14:17]
	v_mfma_f32_16x16x32_bf16 v[18:21], v[104:107], v[136:139], v[18:21]
	v_mfma_f32_16x16x32_bf16 v[22:25], v[112:115], v[136:139], v[22:25]
	v_mfma_f32_16x16x32_bf16 v[26:29], v[104:107], v[144:147], v[26:29]
	v_mfma_f32_16x16x32_bf16 v[30:33], v[112:115], v[144:147], v[30:33]
	v_mfma_f32_16x16x32_bf16 v[2:5], v[108:111], v[124:127], v[2:5]
	v_mfma_f32_16x16x32_bf16 v[6:9], v[116:119], v[124:127], v[6:9]
	v_mfma_f32_16x16x32_bf16 v[10:13], v[108:111], v[132:135], v[10:13]
	v_mfma_f32_16x16x32_bf16 v[14:17], v[116:119], v[132:135], v[14:17]
	v_mfma_f32_16x16x32_bf16 v[18:21], v[108:111], v[140:143], v[18:21]
	v_mfma_f32_16x16x32_bf16 v[22:25], v[116:119], v[140:143], v[22:25]
	v_mfma_f32_16x16x32_bf16 v[26:29], v[108:111], v[148:151], v[26:29]
	v_mfma_f32_16x16x32_bf16 v[30:33], v[116:119], v[148:151], v[30:33]
	s_barrier
	s_add_i32 m0, s1, 0x1be80
	s_nop 0
	global_load_lds_dwordx4 v[160:161], off offset:384
	s_add_i32 m0, s1, 0x1de80
	s_add_i32 s0, s0, 2
	global_load_lds_dwordx4 v[162:163], off offset:384
	s_waitcnt vmcnt(6)
	s_add_u32 s10, s10, 0x100
	s_addc_u32 s11, s11, 0
	s_cmpk_lt_u32 s0, 0x54
	s_barrier
	s_barrier
	s_cbranch_scc1 .LBB0_689
	s_add_i32 s1, s1, 0x1e000
	s_add_u32 s0, s8, 0x2b80
	s_addc_u32 s1, s9, 0
	v_readfirstlane_b32 s8, v101
	v_lshl_add_u64 v[90:91], s[0:1], 0, v[0:1]
	s_mov_b32 m0, s8
	v_lshl_add_u64 v[66:67], s[0:1], 0, v[66:67]
	v_readfirstlane_b32 s0, v102
	ds_read_b128 v[68:71], v95
	ds_read_b128 v[72:75], v95 offset:1024
	ds_read_b128 v[76:79], v95 offset:2048
	ds_read_b128 v[86:89], v95 offset:3072
	ds_read_b128 v[96:99], v93
	ds_read_b128 v[104:107], v93 offset:1024
	ds_read_b128 v[108:111], v93 offset:2048
	ds_read_b128 v[112:115], v93 offset:3072
	ds_read_b128 v[116:119], v93 offset:4096
	ds_read_b128 v[120:123], v93 offset:5120
	ds_read_b128 v[124:127], v93 offset:6144
	ds_read_b128 v[128:131], v93 offset:7168
	global_load_lds_dwordx4 v[90:91], off
	s_mov_b32 m0, s0
	s_nop 0
	global_load_lds_dwordx4 v[66:67], off
	s_barrier
	s_waitcnt lgkmcnt(0)
	s_setprio 1
	s_waitcnt lgkmcnt(0)
	v_mfma_f32_16x16x32_bf16 v[62:65], v[68:71], v[96:99], v[62:65]
	v_mfma_f32_16x16x32_bf16 v[58:61], v[76:79], v[96:99], v[58:61]
	v_mfma_f32_16x16x32_bf16 v[54:57], v[68:71], v[108:111], v[54:57]
	v_mfma_f32_16x16x32_bf16 v[50:53], v[76:79], v[108:111], v[50:53]
	v_mfma_f32_16x16x32_bf16 v[46:49], v[68:71], v[116:119], v[46:49]
	v_mfma_f32_16x16x32_bf16 v[42:45], v[76:79], v[116:119], v[42:45]
	v_mfma_f32_16x16x32_bf16 v[38:41], v[68:71], v[124:127], v[38:41]
	v_mfma_f32_16x16x32_bf16 v[34:37], v[76:79], v[124:127], v[34:37]
	v_mfma_f32_16x16x32_bf16 v[62:65], v[72:75], v[104:107], v[62:65]
	v_mfma_f32_16x16x32_bf16 v[58:61], v[86:89], v[104:107], v[58:61]
	v_mfma_f32_16x16x32_bf16 v[54:57], v[72:75], v[112:115], v[54:57]
	v_mfma_f32_16x16x32_bf16 v[50:53], v[86:89], v[112:115], v[50:53]
	v_mfma_f32_16x16x32_bf16 v[46:49], v[72:75], v[120:123], v[46:49]
	v_mfma_f32_16x16x32_bf16 v[42:45], v[86:89], v[120:123], v[42:45]
	v_mfma_f32_16x16x32_bf16 v[38:41], v[72:75], v[128:131], v[38:41]
	v_mfma_f32_16x16x32_bf16 v[34:37], v[86:89], v[128:131], v[34:37]
	s_setprio 0
	s_barrier
	s_barrier
	s_waitcnt lgkmcnt(0)
	s_barrier
	ds_read_b128 v[96:99], v93 offset:16384
	ds_read_b128 v[100:103], v93 offset:17408
	ds_read_b128 v[104:107], v93 offset:18432
	ds_read_b128 v[108:111], v93 offset:19456
	ds_read_b128 v[112:115], v93 offset:20480
	ds_read_b128 v[116:119], v93 offset:21504
	ds_read_b128 v[120:123], v93 offset:22528
	ds_read_b128 v[124:127], v93 offset:23552
	s_waitcnt vmcnt(4)
	s_barrier
	s_waitcnt lgkmcnt(0)
	s_setprio 1
	s_waitcnt lgkmcnt(3)
	v_mfma_f32_16x16x32_bf16 v[18:21], v[68:71], v[112:115], v[18:21]
	v_mfma_f32_16x16x32_bf16 v[2:5], v[68:71], v[96:99], v[2:5]
	v_mfma_f32_16x16x32_bf16 v[6:9], v[76:79], v[96:99], v[6:9]
	s_waitcnt lgkmcnt(2)
	v_mfma_f32_16x16x32_bf16 v[96:99], v[72:75], v[116:119], v[18:21]
	v_mfma_f32_16x16x32_bf16 v[18:21], v[76:79], v[112:115], v[22:25]
	v_mfma_f32_16x16x32_bf16 v[2:5], v[72:75], v[100:103], v[2:5]
	v_mfma_f32_16x16x32_bf16 v[6:9], v[86:89], v[100:103], v[6:9]
	v_mfma_f32_16x16x32_bf16 v[10:13], v[68:71], v[104:107], v[10:13]
	v_mfma_f32_16x16x32_bf16 v[14:17], v[76:79], v[104:107], v[14:17]
	v_mfma_f32_16x16x32_bf16 v[100:103], v[86:89], v[116:119], v[18:21]
	s_waitcnt lgkmcnt(1)
	v_mfma_f32_16x16x32_bf16 v[18:21], v[68:71], v[120:123], v[26:29]
	v_mfma_f32_16x16x32_bf16 v[10:13], v[72:75], v[108:111], v[10:13]
	v_mfma_f32_16x16x32_bf16 v[14:17], v[86:89], v[108:111], v[14:17]
	s_waitcnt lgkmcnt(0)
	v_mfma_f32_16x16x32_bf16 v[66:69], v[72:75], v[124:127], v[18:21]
	v_mfma_f32_16x16x32_bf16 v[18:21], v[76:79], v[120:123], v[30:33]
	v_mfma_f32_16x16x32_bf16 v[70:73], v[86:89], v[124:127], v[18:21]
	s_setprio 0
	s_barrier
	ds_read_b128 v[74:77], v95 offset:32768
	ds_read_b128 v[86:89], v95 offset:33792
	ds_read_b128 v[104:107], v95 offset:34816
	ds_read_b128 v[108:111], v95 offset:35840
	s_nop 0
	ds_read_b128 v[18:21], v93 offset:32768
	ds_read_b128 v[22:25], v93 offset:33792
	ds_read_b128 v[26:29], v93 offset:34816
	ds_read_b128 v[30:33], v93 offset:35840
	ds_read_b128 v[112:115], v93 offset:36864
	ds_read_b128 v[116:119], v93 offset:37888
	ds_read_b128 v[120:123], v93 offset:38912
	ds_read_b128 v[124:127], v93 offset:39936
	s_waitcnt vmcnt(2)
	s_barrier
	s_waitcnt lgkmcnt(0)
	s_setprio 1
	s_waitcnt lgkmcnt(7)
	v_mfma_f32_16x16x32_bf16 v[62:65], v[74:77], v[18:21], v[62:65]
	v_mfma_f32_16x16x32_bf16 v[18:21], v[104:107], v[18:21], v[58:61]
	s_waitcnt lgkmcnt(6)
	v_mfma_f32_16x16x32_bf16 v[58:61], v[108:111], v[22:25], v[18:21]
	s_waitcnt lgkmcnt(5)
	v_mfma_f32_16x16x32_bf16 v[18:21], v[74:77], v[26:29], v[54:57]
	s_waitcnt lgkmcnt(4)
	v_mfma_f32_16x16x32_bf16 v[54:57], v[86:89], v[30:33], v[18:21]
	v_mfma_f32_16x16x32_bf16 v[18:21], v[104:107], v[26:29], v[50:53]
	v_mfma_f32_16x16x32_bf16 v[50:53], v[108:111], v[30:33], v[18:21]
	s_waitcnt lgkmcnt(3)
	v_mfma_f32_16x16x32_bf16 v[18:21], v[74:77], v[112:115], v[46:49]
	s_waitcnt lgkmcnt(2)
	v_mfma_f32_16x16x32_bf16 v[46:49], v[86:89], v[116:119], v[18:21]
	v_mfma_f32_16x16x32_bf16 v[18:21], v[104:107], v[112:115], v[42:45]
	v_mfma_f32_16x16x32_bf16 v[42:45], v[108:111], v[116:119], v[18:21]
	s_waitcnt lgkmcnt(1)
	v_mfma_f32_16x16x32_bf16 v[18:21], v[74:77], v[120:123], v[38:41]
	s_waitcnt lgkmcnt(0)
	v_mfma_f32_16x16x32_bf16 v[38:41], v[86:89], v[124:127], v[18:21]
	v_mfma_f32_16x16x32_bf16 v[18:21], v[104:107], v[120:123], v[34:37]
	v_mfma_f32_16x16x32_bf16 v[62:65], v[86:89], v[22:25], v[62:65]
	v_mfma_f32_16x16x32_bf16 v[34:37], v[108:111], v[124:127], v[18:21]
	s_setprio 0
	s_barrier
	s_waitcnt vmcnt(0)
	s_barrier
	s_waitcnt lgkmcnt(0)
	s_barrier
	s_nop 1
	ds_read_b128 v[18:21], v93 offset:49152
	ds_read_b128 v[22:25], v93 offset:50176
	ds_read_b128 v[112:115], v93 offset:51200
	ds_read_b128 v[116:119], v93 offset:52224
	ds_read_b128 v[120:123], v93 offset:53248
	ds_read_b128 v[124:127], v93 offset:54272
	ds_read_b128 v[128:131], v93 offset:55296
	ds_read_b128 v[90:93], v93 offset:56320
	s_barrier
	s_waitcnt lgkmcnt(0)
	s_setprio 1
	s_waitcnt lgkmcnt(7)
	v_mfma_f32_16x16x32_bf16 v[2:5], v[74:77], v[18:21], v[2:5]
	s_waitcnt lgkmcnt(6)
	v_mfma_f32_16x16x32_bf16 v[30:33], v[86:89], v[22:25], v[2:5]
	v_mfma_f32_16x16x32_bf16 v[2:5], v[104:107], v[18:21], v[6:9]
	v_mfma_f32_16x16x32_bf16 v[26:29], v[108:111], v[22:25], v[2:5]
	s_waitcnt lgkmcnt(5)
	v_mfma_f32_16x16x32_bf16 v[2:5], v[74:77], v[112:115], v[10:13]
	s_waitcnt lgkmcnt(4)
	v_mfma_f32_16x16x32_bf16 v[22:25], v[86:89], v[116:119], v[2:5]
	v_mfma_f32_16x16x32_bf16 v[2:5], v[104:107], v[112:115], v[14:17]
	v_mfma_f32_16x16x32_bf16 v[18:21], v[108:111], v[116:119], v[2:5]
	s_waitcnt lgkmcnt(3)
	v_mfma_f32_16x16x32_bf16 v[2:5], v[74:77], v[120:123], v[96:99]
	s_waitcnt lgkmcnt(2)
	v_mfma_f32_16x16x32_bf16 v[14:17], v[86:89], v[124:127], v[2:5]
	v_mfma_f32_16x16x32_bf16 v[2:5], v[104:107], v[120:123], v[100:103]
	v_mfma_f32_16x16x32_bf16 v[10:13], v[108:111], v[124:127], v[2:5]
	s_waitcnt lgkmcnt(1)
	v_mfma_f32_16x16x32_bf16 v[2:5], v[74:77], v[128:131], v[66:69]
	s_waitcnt lgkmcnt(0)
	v_mfma_f32_16x16x32_bf16 v[6:9], v[86:89], v[90:93], v[2:5]
	v_mfma_f32_16x16x32_bf16 v[2:5], v[104:107], v[128:131], v[70:73]
	v_mfma_f32_16x16x32_bf16 v[2:5], v[108:111], v[90:93], v[2:5]
	s_setprio 0
	s_movk_i32 s0, 0x100
	v_cmp_gt_u32_e32 vcc, s0, v80
	s_barrier
	s_and_saveexec_b64 s[0:1], vcc
	s_cbranch_execz .LBB0_692
	s_barrier

.LBB0_761:
	ds_read_b128 v[164:167], v148
	ds_read_b128 v[168:171], v148 offset:1024
	ds_read_b128 v[172:175], v148 offset:2048
	ds_read_b128 v[176:179], v148 offset:3072
	v_lshl_add_u64 v[204:205], v[136:137], 0, s[10:11]
	v_lshl_add_u64 v[228:229], v[204:205], 0, s[34:35]
	s_add_i32 m0, s1, 0xc000
	ds_read_b128 v[180:183], v147
	ds_read_b128 v[184:187], v147 offset:1024
	ds_read_b128 v[188:191], v147 offset:2048
	ds_read_b128 v[192:195], v147 offset:3072
	ds_read_b128 v[196:199], v147 offset:4096
	ds_read_b128 v[200:203], v147 offset:5120
	ds_read_b128 v[222:225], v147 offset:6144
	ds_read_b128 v[232:235], v147 offset:7168
	global_load_lds_dwordx4 v[228:229], off
	v_lshl_add_u64 v[210:211], v[138:139], 0, s[10:11]
	s_add_i32 m0, s1, 0xe000
	v_lshl_add_u64 v[152:153], v[210:211], 0, s[34:35]
	global_load_lds_dwordx4 v[152:153], off
	s_waitcnt lgkmcnt(8)
	s_barrier
	s_waitcnt lgkmcnt(0)
	v_mfma_f32_16x16x32_bf16 v[126:129], v[164:167], v[180:183], v[126:129]
	v_mfma_f32_16x16x32_bf16 v[122:125], v[172:175], v[180:183], v[122:125]
	v_mfma_f32_16x16x32_bf16 v[118:121], v[164:167], v[188:191], v[118:121]
	v_mfma_f32_16x16x32_bf16 v[114:117], v[172:175], v[188:191], v[114:117]
	v_mfma_f32_16x16x32_bf16 v[110:113], v[164:167], v[196:199], v[110:113]
	v_mfma_f32_16x16x32_bf16 v[106:109], v[172:175], v[196:199], v[106:109]
	v_mfma_f32_16x16x32_bf16 v[102:105], v[164:167], v[222:225], v[102:105]
	v_mfma_f32_16x16x32_bf16 v[98:101], v[172:175], v[222:225], v[98:101]
	v_mfma_f32_16x16x32_bf16 v[126:129], v[168:171], v[184:187], v[126:129]
	v_mfma_f32_16x16x32_bf16 v[122:125], v[176:179], v[184:187], v[122:125]
	v_mfma_f32_16x16x32_bf16 v[118:121], v[168:171], v[192:195], v[118:121]
	v_mfma_f32_16x16x32_bf16 v[114:117], v[176:179], v[192:195], v[114:117]
	v_mfma_f32_16x16x32_bf16 v[110:113], v[168:171], v[200:203], v[110:113]
	v_mfma_f32_16x16x32_bf16 v[106:109], v[176:179], v[200:203], v[106:109]
	v_mfma_f32_16x16x32_bf16 v[102:105], v[168:171], v[232:235], v[102:105]
	v_mfma_f32_16x16x32_bf16 v[98:101], v[176:179], v[232:235], v[98:101]
	s_barrier
	v_lshl_add_u64 v[216:217], v[132:133], 0, s[10:11]
	s_add_i32 m0, s1, 0xff00
	ds_read_b128 v[236:239], v148 offset:16384
	ds_read_b128 v[240:243], v148 offset:17408
	ds_read_b128 v[244:247], v148 offset:18432
	ds_read_b128 v[248:251], v148 offset:19456
	global_load_lds_dwordx4 v[216:217], off offset:256
	s_add_i32 m0, s1, 0x11f00
	v_lshl_add_u64 v[218:219], v[134:135], 0, s[10:11]
	global_load_lds_dwordx4 v[218:219], off offset:256
	s_barrier
	s_waitcnt lgkmcnt(0)
	v_mfma_f32_16x16x32_bf16 v[94:97], v[236:239], v[180:183], v[94:97]
	v_mfma_f32_16x16x32_bf16 v[90:93], v[244:247], v[180:183], v[90:93]
	v_mfma_f32_16x16x32_bf16 v[86:89], v[236:239], v[188:191], v[86:89]
	v_mfma_f32_16x16x32_bf16 v[82:85], v[244:247], v[188:191], v[82:85]
	v_mfma_f32_16x16x32_bf16 v[78:81], v[236:239], v[196:199], v[78:81]
	v_mfma_f32_16x16x32_bf16 v[74:77], v[244:247], v[196:199], v[74:77]
	v_mfma_f32_16x16x32_bf16 v[70:73], v[236:239], v[222:225], v[70:73]
	v_mfma_f32_16x16x32_bf16 v[66:69], v[244:247], v[222:225], v[66:69]
	v_mfma_f32_16x16x32_bf16 v[94:97], v[240:243], v[184:187], v[94:97]
	v_mfma_f32_16x16x32_bf16 v[90:93], v[248:251], v[184:187], v[90:93]
	v_mfma_f32_16x16x32_bf16 v[86:89], v[240:243], v[192:195], v[86:89]
	v_mfma_f32_16x16x32_bf16 v[82:85], v[248:251], v[192:195], v[82:85]
	v_mfma_f32_16x16x32_bf16 v[78:81], v[240:243], v[200:203], v[78:81]
	v_mfma_f32_16x16x32_bf16 v[74:77], v[248:251], v[200:203], v[74:77]
	v_mfma_f32_16x16x32_bf16 v[70:73], v[240:243], v[232:235], v[70:73]
	v_mfma_f32_16x16x32_bf16 v[66:69], v[248:251], v[232:235], v[66:69]
	v_lshl_add_u64 v[158:159], v[204:205], 0, s[74:75]
	s_mov_b32 m0, s1
	s_barrier
	ds_read_b128 v[180:183], v147 offset:16384
	ds_read_b128 v[184:187], v147 offset:17408
	ds_read_b128 v[188:191], v147 offset:18432
	ds_read_b128 v[192:195], v147 offset:19456
	ds_read_b128 v[196:199], v147 offset:20480
	ds_read_b128 v[200:203], v147 offset:21504
	ds_read_b128 v[222:225], v147 offset:22528
	global_load_lds_dwordx4 v[158:159], off
	s_add_i32 m0, s1, 0x1f00
	ds_read_b128 v[232:235], v147 offset:23552
	global_load_lds_dwordx4 v[210:211], off offset:256
	s_barrier
	s_waitcnt lgkmcnt(0)
	v_mfma_f32_16x16x32_bf16 v[62:65], v[164:167], v[180:183], v[62:65]
	v_mfma_f32_16x16x32_bf16 v[58:61], v[172:175], v[180:183], v[58:61]
	v_mfma_f32_16x16x32_bf16 v[54:57], v[164:167], v[188:191], v[54:57]
	v_mfma_f32_16x16x32_bf16 v[50:53], v[172:175], v[188:191], v[50:53]
	v_mfma_f32_16x16x32_bf16 v[46:49], v[164:167], v[196:199], v[46:49]
	v_mfma_f32_16x16x32_bf16 v[42:45], v[172:175], v[196:199], v[42:45]
	v_mfma_f32_16x16x32_bf16 v[38:41], v[164:167], v[222:225], v[38:41]
	v_mfma_f32_16x16x32_bf16 v[34:37], v[172:175], v[222:225], v[34:37]
	v_mfma_f32_16x16x32_bf16 v[62:65], v[168:171], v[184:187], v[62:65]
	v_mfma_f32_16x16x32_bf16 v[58:61], v[176:179], v[184:187], v[58:61]
	v_mfma_f32_16x16x32_bf16 v[54:57], v[168:171], v[192:195], v[54:57]
	v_mfma_f32_16x16x32_bf16 v[50:53], v[176:179], v[192:195], v[50:53]
	v_mfma_f32_16x16x32_bf16 v[46:49], v[168:171], v[200:203], v[46:49]
	v_mfma_f32_16x16x32_bf16 v[42:45], v[176:179], v[200:203], v[42:45]
	v_mfma_f32_16x16x32_bf16 v[38:41], v[168:171], v[232:235], v[38:41]
	v_mfma_f32_16x16x32_bf16 v[34:37], v[176:179], v[232:235], v[34:37]
	s_barrier
	s_add_i32 m0, s1, 0x14000
	v_lshl_add_u64 v[154:155], v[216:217], 0, s[78:79]
	global_load_lds_dwordx4 v[154:155], off
	s_add_i32 m0, s1, 0x16000
	v_lshl_add_u64 v[156:157], v[218:219], 0, s[78:79]
	global_load_lds_dwordx4 v[156:157], off
	s_waitcnt vmcnt(6)
	s_barrier
	v_mfma_f32_16x16x32_bf16 v[30:33], v[236:239], v[180:183], v[30:33]
	v_mfma_f32_16x16x32_bf16 v[26:29], v[244:247], v[180:183], v[26:29]
	v_mfma_f32_16x16x32_bf16 v[22:25], v[236:239], v[188:191], v[22:25]
	v_mfma_f32_16x16x32_bf16 v[18:21], v[244:247], v[188:191], v[18:21]
	v_mfma_f32_16x16x32_bf16 v[14:17], v[236:239], v[196:199], v[14:17]
	v_mfma_f32_16x16x32_bf16 v[10:13], v[244:247], v[196:199], v[10:13]
	v_mfma_f32_16x16x32_bf16 v[6:9], v[236:239], v[222:225], v[6:9]
	v_mfma_f32_16x16x32_bf16 v[2:5], v[244:247], v[222:225], v[2:5]
	v_mfma_f32_16x16x32_bf16 v[30:33], v[240:243], v[184:187], v[30:33]
	v_mfma_f32_16x16x32_bf16 v[26:29], v[248:251], v[184:187], v[26:29]
	v_mfma_f32_16x16x32_bf16 v[22:25], v[240:243], v[192:195], v[22:25]
	v_mfma_f32_16x16x32_bf16 v[18:21], v[248:251], v[192:195], v[18:21]
	v_mfma_f32_16x16x32_bf16 v[14:17], v[240:243], v[200:203], v[14:17]
	v_mfma_f32_16x16x32_bf16 v[10:13], v[248:251], v[200:203], v[10:13]
	v_mfma_f32_16x16x32_bf16 v[6:9], v[240:243], v[232:235], v[6:9]
	v_mfma_f32_16x16x32_bf16 v[2:5], v[248:251], v[232:235], v[2:5]
	s_barrier
	ds_read_b128 v[164:167], v148 offset:32768
	ds_read_b128 v[168:171], v148 offset:33792
	ds_read_b128 v[172:175], v148 offset:34816
	ds_read_b128 v[176:179], v148 offset:35840
	s_add_i32 m0, s1, 0x3f80
	ds_read_b128 v[180:183], v147 offset:32768
	ds_read_b128 v[184:187], v147 offset:33792
	ds_read_b128 v[188:191], v147 offset:34816
	ds_read_b128 v[192:195], v147 offset:35840
	ds_read_b128 v[196:199], v147 offset:36864
	ds_read_b128 v[200:203], v147 offset:37888
	ds_read_b128 v[222:225], v147 offset:38912
	global_load_lds_dwordx4 v[228:229], off offset:128
	s_add_i32 m0, s1, 0x5f80
	ds_read_b128 v[232:235], v147 offset:39936
	global_load_lds_dwordx4 v[152:153], off offset:128
	s_waitcnt lgkmcnt(8)
	s_barrier
	s_waitcnt lgkmcnt(0)
	v_mfma_f32_16x16x32_bf16 v[126:129], v[164:167], v[180:183], v[126:129]
	v_mfma_f32_16x16x32_bf16 v[122:125], v[172:175], v[180:183], v[122:125]
	v_mfma_f32_16x16x32_bf16 v[118:121], v[164:167], v[188:191], v[118:121]
	v_mfma_f32_16x16x32_bf16 v[114:117], v[172:175], v[188:191], v[114:117]
	v_mfma_f32_16x16x32_bf16 v[110:113], v[164:167], v[196:199], v[110:113]
	v_mfma_f32_16x16x32_bf16 v[106:109], v[172:175], v[196:199], v[106:109]
	v_mfma_f32_16x16x32_bf16 v[102:105], v[164:167], v[222:225], v[102:105]
	v_mfma_f32_16x16x32_bf16 v[98:101], v[172:175], v[222:225], v[98:101]
	v_mfma_f32_16x16x32_bf16 v[126:129], v[168:171], v[184:187], v[126:129]
	v_mfma_f32_16x16x32_bf16 v[122:125], v[176:179], v[184:187], v[122:125]
	v_mfma_f32_16x16x32_bf16 v[118:121], v[168:171], v[192:195], v[118:121]
	v_mfma_f32_16x16x32_bf16 v[114:117], v[176:179], v[192:195], v[114:117]
	v_mfma_f32_16x16x32_bf16 v[110:113], v[168:171], v[200:203], v[110:113]
	v_mfma_f32_16x16x32_bf16 v[106:109], v[176:179], v[200:203], v[106:109]
	v_mfma_f32_16x16x32_bf16 v[102:105], v[168:171], v[232:235], v[102:105]
	v_mfma_f32_16x16x32_bf16 v[98:101], v[176:179], v[232:235], v[98:101]
	s_barrier
	s_add_i32 m0, s1, 0x17e80
	ds_read_b128 v[236:239], v148 offset:49152
	ds_read_b128 v[240:243], v148 offset:50176
	ds_read_b128 v[244:247], v148 offset:51200
	global_load_lds_dwordx4 v[216:217], off offset:384
	s_add_i32 m0, s1, 0x19e80
	ds_read_b128 v[248:251], v148 offset:52224
	global_load_lds_dwordx4 v[218:219], off offset:384
	s_barrier
	s_waitcnt lgkmcnt(0)
	v_mfma_f32_16x16x32_bf16 v[94:97], v[236:239], v[180:183], v[94:97]
	v_mfma_f32_16x16x32_bf16 v[90:93], v[244:247], v[180:183], v[90:93]
	v_mfma_f32_16x16x32_bf16 v[86:89], v[236:239], v[188:191], v[86:89]
	v_mfma_f32_16x16x32_bf16 v[82:85], v[244:247], v[188:191], v[82:85]
	v_mfma_f32_16x16x32_bf16 v[78:81], v[236:239], v[196:199], v[78:81]
	v_mfma_f32_16x16x32_bf16 v[74:77], v[244:247], v[196:199], v[74:77]
	v_mfma_f32_16x16x32_bf16 v[70:73], v[236:239], v[222:225], v[70:73]
	v_mfma_f32_16x16x32_bf16 v[66:69], v[244:247], v[222:225], v[66:69]
	v_mfma_f32_16x16x32_bf16 v[94:97], v[240:243], v[184:187], v[94:97]
	v_mfma_f32_16x16x32_bf16 v[90:93], v[248:251], v[184:187], v[90:93]
	v_mfma_f32_16x16x32_bf16 v[86:89], v[240:243], v[192:195], v[86:89]
	v_mfma_f32_16x16x32_bf16 v[82:85], v[248:251], v[192:195], v[82:85]
	v_mfma_f32_16x16x32_bf16 v[78:81], v[240:243], v[200:203], v[78:81]
	v_mfma_f32_16x16x32_bf16 v[74:77], v[248:251], v[200:203], v[74:77]
	v_mfma_f32_16x16x32_bf16 v[70:73], v[240:243], v[232:235], v[70:73]
	v_mfma_f32_16x16x32_bf16 v[66:69], v[248:251], v[232:235], v[66:69]
	s_add_i32 m0, s1, 0x7e80
	s_barrier
	ds_read_b128 v[180:183], v147 offset:49152
	ds_read_b128 v[184:187], v147 offset:50176
	ds_read_b128 v[188:191], v147 offset:51200
	ds_read_b128 v[192:195], v147 offset:52224
	ds_read_b128 v[196:199], v147 offset:53248
	ds_read_b128 v[200:203], v147 offset:54272
	ds_read_b128 v[222:225], v147 offset:55296
	global_load_lds_dwordx4 v[204:205], off offset:384
	s_add_i32 m0, s1, 0x9e80
	ds_read_b128 v[232:235], v147 offset:56320
	global_load_lds_dwordx4 v[210:211], off offset:384
	s_barrier
	s_waitcnt lgkmcnt(0)
	v_mfma_f32_16x16x32_bf16 v[62:65], v[164:167], v[180:183], v[62:65]
	v_mfma_f32_16x16x32_bf16 v[58:61], v[172:175], v[180:183], v[58:61]
	v_mfma_f32_16x16x32_bf16 v[54:57], v[164:167], v[188:191], v[54:57]
	v_mfma_f32_16x16x32_bf16 v[50:53], v[172:175], v[188:191], v[50:53]
	v_mfma_f32_16x16x32_bf16 v[46:49], v[164:167], v[196:199], v[46:49]
	v_mfma_f32_16x16x32_bf16 v[42:45], v[172:175], v[196:199], v[42:45]
	v_mfma_f32_16x16x32_bf16 v[38:41], v[164:167], v[222:225], v[38:41]
	v_mfma_f32_16x16x32_bf16 v[34:37], v[172:175], v[222:225], v[34:37]
	v_mfma_f32_16x16x32_bf16 v[62:65], v[168:171], v[184:187], v[62:65]
	v_mfma_f32_16x16x32_bf16 v[58:61], v[176:179], v[184:187], v[58:61]
	v_mfma_f32_16x16x32_bf16 v[54:57], v[168:171], v[192:195], v[54:57]
	v_mfma_f32_16x16x32_bf16 v[50:53], v[176:179], v[192:195], v[50:53]
	v_mfma_f32_16x16x32_bf16 v[46:49], v[168:171], v[200:203], v[46:49]
	v_mfma_f32_16x16x32_bf16 v[42:45], v[176:179], v[200:203], v[42:45]
	v_mfma_f32_16x16x32_bf16 v[38:41], v[168:171], v[232:235], v[38:41]
	v_mfma_f32_16x16x32_bf16 v[34:37], v[176:179], v[232:235], v[34:37]
	s_barrier
	s_add_i32 m0, s1, 0x1bf80
	s_nop 0
	global_load_lds_dwordx4 v[154:155], off offset:128
	s_add_i32 m0, s1, 0x1df80
	s_nop 0
	global_load_lds_dwordx4 v[156:157], off offset:128
	s_waitcnt vmcnt(6)
	s_barrier
	v_mfma_f32_16x16x32_bf16 v[30:33], v[236:239], v[180:183], v[30:33]
	v_mfma_f32_16x16x32_bf16 v[26:29], v[244:247], v[180:183], v[26:29]
	v_mfma_f32_16x16x32_bf16 v[22:25], v[236:239], v[188:191], v[22:25]
	v_mfma_f32_16x16x32_bf16 v[18:21], v[244:247], v[188:191], v[18:21]
	v_mfma_f32_16x16x32_bf16 v[14:17], v[236:239], v[196:199], v[14:17]
	v_mfma_f32_16x16x32_bf16 v[10:13], v[244:247], v[196:199], v[10:13]
	v_mfma_f32_16x16x32_bf16 v[6:9], v[236:239], v[222:225], v[6:9]
	v_mfma_f32_16x16x32_bf16 v[2:5], v[244:247], v[222:225], v[2:5]
	v_mfma_f32_16x16x32_bf16 v[30:33], v[240:243], v[184:187], v[30:33]
	v_mfma_f32_16x16x32_bf16 v[26:29], v[248:251], v[184:187], v[26:29]
	v_mfma_f32_16x16x32_bf16 v[22:25], v[240:243], v[192:195], v[22:25]
	v_mfma_f32_16x16x32_bf16 v[18:21], v[248:251], v[192:195], v[18:21]
	v_mfma_f32_16x16x32_bf16 v[14:17], v[240:243], v[200:203], v[14:17]
	v_mfma_f32_16x16x32_bf16 v[10:13], v[248:251], v[200:203], v[10:13]
	v_mfma_f32_16x16x32_bf16 v[6:9], v[240:243], v[232:235], v[6:9]
	v_mfma_f32_16x16x32_bf16 v[2:5], v[248:251], v[232:235], v[2:5]
	s_add_i32 s0, s0, 2
	s_add_u32 s10, s10, 0x100
	s_addc_u32 s11, s11, 0
	s_cmpk_lt_u32 s0, 0x54
	s_barrier
	s_cbranch_scc1 .LBB0_761
	s_add_i32 s1, s1, 0x1e000
	s_add_u32 s0, s8, 0x162b80
	s_addc_u32 s1, s9, 0
	v_readfirstlane_b32 s8, v161
	v_lshl_add_u64 v[158:159], s[0:1], 0, v[0:1]
	s_mov_b32 m0, s8
	v_lshl_add_u64 v[130:131], s[0:1], 0, v[130:131]
	v_readfirstlane_b32 s0, v162
	ds_read_b128 v[132:135], v148
	ds_read_b128 v[136:139], v148 offset:1024
	ds_read_b128 v[150:153], v148 offset:2048
	ds_read_b128 v[154:157], v148 offset:3072
	ds_read_b128 v[164:167], v147
	ds_read_b128 v[168:171], v147 offset:1024
	ds_read_b128 v[172:175], v147 offset:2048
	ds_read_b128 v[176:179], v147 offset:3072
	ds_read_b128 v[180:183], v147 offset:4096
	ds_read_b128 v[184:187], v147 offset:5120
	ds_read_b128 v[188:191], v147 offset:6144
	ds_read_b128 v[192:195], v147 offset:7168
	global_load_lds_dwordx4 v[158:159], off
	s_mov_b32 m0, s0
	s_nop 0
	global_load_lds_dwordx4 v[130:131], off
	s_barrier
	s_waitcnt lgkmcnt(0)
	s_setprio 1
	s_waitcnt lgkmcnt(0)
	v_mfma_f32_16x16x32_bf16 v[122:125], v[150:153], v[164:167], v[122:125]
	v_mfma_f32_16x16x32_bf16 v[118:121], v[132:135], v[172:175], v[118:121]
	v_mfma_f32_16x16x32_bf16 v[114:117], v[150:153], v[172:175], v[114:117]
	v_mfma_f32_16x16x32_bf16 v[102:105], v[132:135], v[188:191], v[102:105]
	v_mfma_f32_16x16x32_bf16 v[98:101], v[150:153], v[188:191], v[98:101]
	v_mfma_f32_16x16x32_bf16 v[126:129], v[132:135], v[164:167], v[126:129]
	v_mfma_f32_16x16x32_bf16 v[122:125], v[154:157], v[168:171], v[122:125]
	v_mfma_f32_16x16x32_bf16 v[118:121], v[136:139], v[176:179], v[118:121]
	v_mfma_f32_16x16x32_bf16 v[114:117], v[154:157], v[176:179], v[114:117]
	v_mfma_f32_16x16x32_bf16 v[110:113], v[132:135], v[180:183], v[110:113]
	v_mfma_f32_16x16x32_bf16 v[106:109], v[150:153], v[180:183], v[106:109]
	v_mfma_f32_16x16x32_bf16 v[102:105], v[136:139], v[192:195], v[102:105]
	v_mfma_f32_16x16x32_bf16 v[98:101], v[154:157], v[192:195], v[98:101]
	v_mfma_f32_16x16x32_bf16 v[126:129], v[136:139], v[168:171], v[126:129]
	v_mfma_f32_16x16x32_bf16 v[158:161], v[136:139], v[184:187], v[110:113]
	v_mfma_f32_16x16x32_bf16 v[196:199], v[154:157], v[184:187], v[106:109]
	s_setprio 0
	s_barrier
	ds_read_b128 v[106:109], v148 offset:16384
	ds_read_b128 v[110:113], v148 offset:17408
	ds_read_b128 v[200:203], v148 offset:18432
	ds_read_b128 v[222:225], v148 offset:19456
	s_barrier
	s_waitcnt lgkmcnt(0)
	s_setprio 1
	s_waitcnt lgkmcnt(3)
	v_mfma_f32_16x16x32_bf16 v[86:89], v[106:109], v[172:175], v[86:89]
	s_waitcnt lgkmcnt(1)
	v_mfma_f32_16x16x32_bf16 v[82:85], v[200:203], v[172:175], v[82:85]
	v_mfma_f32_16x16x32_bf16 v[70:73], v[106:109], v[188:191], v[70:73]
	v_mfma_f32_16x16x32_bf16 v[66:69], v[200:203], v[188:191], v[66:69]
	v_mfma_f32_16x16x32_bf16 v[94:97], v[106:109], v[164:167], v[94:97]
	v_mfma_f32_16x16x32_bf16 v[90:93], v[200:203], v[164:167], v[90:93]
	v_mfma_f32_16x16x32_bf16 v[86:89], v[110:113], v[176:179], v[86:89]
	s_waitcnt lgkmcnt(0)
	v_mfma_f32_16x16x32_bf16 v[82:85], v[222:225], v[176:179], v[82:85]
	v_mfma_f32_16x16x32_bf16 v[78:81], v[106:109], v[180:183], v[78:81]
	v_mfma_f32_16x16x32_bf16 v[74:77], v[200:203], v[180:183], v[74:77]
	v_mfma_f32_16x16x32_bf16 v[70:73], v[110:113], v[192:195], v[70:73]
	v_mfma_f32_16x16x32_bf16 v[66:69], v[222:225], v[192:195], v[66:69]
	v_mfma_f32_16x16x32_bf16 v[232:235], v[110:113], v[168:171], v[94:97]
	v_mfma_f32_16x16x32_bf16 v[162:165], v[222:225], v[168:171], v[90:93]
	v_mfma_f32_16x16x32_bf16 v[166:169], v[110:113], v[184:187], v[78:81]
	v_mfma_f32_16x16x32_bf16 v[170:173], v[222:225], v[184:187], v[74:77]
	s_setprio 0
	s_barrier
	s_nop 0
	ds_read_b128 v[74:77], v147 offset:16384
	ds_read_b128 v[78:81], v147 offset:17408
	ds_read_b128 v[90:93], v147 offset:18432
	ds_read_b128 v[94:97], v147 offset:19456
	ds_read_b128 v[174:177], v147 offset:20480
	ds_read_b128 v[178:181], v147 offset:21504
	ds_read_b128 v[182:185], v147 offset:22528
	ds_read_b128 v[186:189], v147 offset:23552
	s_waitcnt vmcnt(4)
	s_barrier
	s_waitcnt lgkmcnt(0)
	s_setprio 1
	s_waitcnt lgkmcnt(7)
	v_mfma_f32_16x16x32_bf16 v[62:65], v[132:135], v[74:77], v[62:65]
	v_mfma_f32_16x16x32_bf16 v[58:61], v[150:153], v[74:77], v[58:61]
	s_waitcnt lgkmcnt(5)
	v_mfma_f32_16x16x32_bf16 v[54:57], v[132:135], v[90:93], v[54:57]
	v_mfma_f32_16x16x32_bf16 v[50:53], v[150:153], v[90:93], v[50:53]
	s_waitcnt lgkmcnt(1)
	v_mfma_f32_16x16x32_bf16 v[38:41], v[132:135], v[182:185], v[38:41]
	v_mfma_f32_16x16x32_bf16 v[34:37], v[150:153], v[182:185], v[34:37]
	v_mfma_f32_16x16x32_bf16 v[62:65], v[136:139], v[78:81], v[62:65]
	v_mfma_f32_16x16x32_bf16 v[58:61], v[154:157], v[78:81], v[58:61]
	v_mfma_f32_16x16x32_bf16 v[54:57], v[136:139], v[94:97], v[54:57]
	v_mfma_f32_16x16x32_bf16 v[50:53], v[154:157], v[94:97], v[50:53]
	v_mfma_f32_16x16x32_bf16 v[46:49], v[132:135], v[174:177], v[46:49]
	v_mfma_f32_16x16x32_bf16 v[42:45], v[150:153], v[174:177], v[42:45]
	s_waitcnt lgkmcnt(0)
	v_mfma_f32_16x16x32_bf16 v[38:41], v[136:139], v[186:189], v[38:41]
	v_mfma_f32_16x16x32_bf16 v[34:37], v[154:157], v[186:189], v[34:37]
	v_mfma_f32_16x16x32_bf16 v[190:193], v[136:139], v[178:181], v[46:49]
	v_mfma_f32_16x16x32_bf16 v[236:239], v[154:157], v[178:181], v[42:45]
	s_setprio 0
	s_setprio 1
	v_mfma_f32_16x16x32_bf16 v[22:25], v[106:109], v[90:93], v[22:25]
	v_mfma_f32_16x16x32_bf16 v[18:21], v[200:203], v[90:93], v[18:21]
	v_mfma_f32_16x16x32_bf16 v[6:9], v[106:109], v[182:185], v[6:9]
	v_mfma_f32_16x16x32_bf16 v[2:5], v[200:203], v[182:185], v[2:5]
	v_mfma_f32_16x16x32_bf16 v[30:33], v[106:109], v[74:77], v[30:33]
	v_mfma_f32_16x16x32_bf16 v[26:29], v[200:203], v[74:77], v[26:29]
	v_mfma_f32_16x16x32_bf16 v[22:25], v[110:113], v[94:97], v[22:25]
	v_mfma_f32_16x16x32_bf16 v[18:21], v[222:225], v[94:97], v[18:21]
	v_mfma_f32_16x16x32_bf16 v[14:17], v[106:109], v[174:177], v[14:17]
	v_mfma_f32_16x16x32_bf16 v[10:13], v[200:203], v[174:177], v[10:13]
	v_mfma_f32_16x16x32_bf16 v[6:9], v[110:113], v[186:189], v[6:9]
	v_mfma_f32_16x16x32_bf16 v[2:5], v[222:225], v[186:189], v[2:5]
	v_mfma_f32_16x16x32_bf16 v[134:137], v[110:113], v[78:81], v[30:33]
	v_mfma_f32_16x16x32_bf16 v[150:153], v[222:225], v[78:81], v[26:29]
	v_mfma_f32_16x16x32_bf16 v[154:157], v[110:113], v[178:181], v[14:17]
	v_mfma_f32_16x16x32_bf16 v[174:177], v[222:225], v[178:181], v[10:13]
	s_setprio 0
	s_barrier
	s_nop 0
	ds_read_b128 v[10:13], v148 offset:32768
	ds_read_b128 v[14:17], v148 offset:33792
	ds_read_b128 v[178:181], v148 offset:34816
	ds_read_b128 v[182:185], v148 offset:35840
	ds_read_b128 v[26:29], v147 offset:32768
	ds_read_b128 v[30:33], v147 offset:33792
	ds_read_b128 v[42:45], v147 offset:34816
	ds_read_b128 v[46:49], v147 offset:35840
	ds_read_b128 v[186:189], v147 offset:36864
	ds_read_b128 v[200:203], v147 offset:37888
	ds_read_b128 v[222:225], v147 offset:38912
	ds_read_b128 v[240:243], v147 offset:39936
	s_waitcnt vmcnt(2)
	s_barrier
	s_waitcnt lgkmcnt(0)
	s_setprio 1
	s_waitcnt lgkmcnt(7)
	v_mfma_f32_16x16x32_bf16 v[74:77], v[10:13], v[26:29], v[126:129]
	s_waitcnt lgkmcnt(6)
	v_mfma_f32_16x16x32_bf16 v[130:133], v[14:17], v[30:33], v[74:77]
	v_mfma_f32_16x16x32_bf16 v[74:77], v[178:181], v[26:29], v[122:125]
	v_mfma_f32_16x16x32_bf16 v[122:125], v[182:185], v[30:33], v[74:77]
	s_waitcnt lgkmcnt(5)
	v_mfma_f32_16x16x32_bf16 v[74:77], v[10:13], v[42:45], v[118:121]
	s_waitcnt lgkmcnt(4)
	v_mfma_f32_16x16x32_bf16 v[110:113], v[14:17], v[46:49], v[74:77]
	v_mfma_f32_16x16x32_bf16 v[74:77], v[178:181], v[42:45], v[114:117]
	v_mfma_f32_16x16x32_bf16 v[106:109], v[182:185], v[46:49], v[74:77]
	s_waitcnt lgkmcnt(3)
	v_mfma_f32_16x16x32_bf16 v[74:77], v[10:13], v[186:189], v[158:161]
	s_waitcnt lgkmcnt(2)
	v_mfma_f32_16x16x32_bf16 v[94:97], v[14:17], v[200:203], v[74:77]
	v_mfma_f32_16x16x32_bf16 v[74:77], v[178:181], v[186:189], v[196:199]
	v_mfma_f32_16x16x32_bf16 v[90:93], v[182:185], v[200:203], v[74:77]
	s_waitcnt lgkmcnt(1)
	v_mfma_f32_16x16x32_bf16 v[74:77], v[10:13], v[222:225], v[102:105]
	s_waitcnt lgkmcnt(0)
	v_mfma_f32_16x16x32_bf16 v[78:81], v[14:17], v[240:243], v[74:77]
	v_mfma_f32_16x16x32_bf16 v[74:77], v[178:181], v[222:225], v[98:101]
	v_mfma_f32_16x16x32_bf16 v[74:77], v[182:185], v[240:243], v[74:77]
	s_setprio 0
	s_barrier
	ds_read_b128 v[126:129], v148 offset:49152
	ds_read_b128 v[158:161], v148 offset:50176
	ds_read_b128 v[194:197], v148 offset:51200
	ds_read_b128 v[244:247], v148 offset:52224
	s_waitcnt vmcnt(0)
	s_barrier
	s_waitcnt lgkmcnt(0)
	s_setprio 1
	s_waitcnt lgkmcnt(3)
	v_mfma_f32_16x16x32_bf16 v[98:101], v[126:129], v[26:29], v[232:235]
	s_waitcnt lgkmcnt(1)
	v_mfma_f32_16x16x32_bf16 v[26:29], v[194:197], v[26:29], v[162:165]
	s_waitcnt lgkmcnt(0)
	v_mfma_f32_16x16x32_bf16 v[114:117], v[244:247], v[30:33], v[26:29]
	v_mfma_f32_16x16x32_bf16 v[26:29], v[126:129], v[42:45], v[86:89]
	v_mfma_f32_16x16x32_bf16 v[102:105], v[158:161], v[46:49], v[26:29]
	v_mfma_f32_16x16x32_bf16 v[26:29], v[194:197], v[42:45], v[82:85]
	v_mfma_f32_16x16x32_bf16 v[118:121], v[158:161], v[30:33], v[98:101]
	v_mfma_f32_16x16x32_bf16 v[98:101], v[244:247], v[46:49], v[26:29]
	v_mfma_f32_16x16x32_bf16 v[26:29], v[126:129], v[186:189], v[166:169]
	v_mfma_f32_16x16x32_bf16 v[86:89], v[158:161], v[200:203], v[26:29]
	v_mfma_f32_16x16x32_bf16 v[26:29], v[194:197], v[186:189], v[170:173]
	v_mfma_f32_16x16x32_bf16 v[82:85], v[244:247], v[200:203], v[26:29]
	v_mfma_f32_16x16x32_bf16 v[26:29], v[126:129], v[222:225], v[70:73]
	v_mfma_f32_16x16x32_bf16 v[70:73], v[158:161], v[240:243], v[26:29]
	v_mfma_f32_16x16x32_bf16 v[26:29], v[194:197], v[222:225], v[66:69]
	v_mfma_f32_16x16x32_bf16 v[66:69], v[244:247], v[240:243], v[26:29]
	s_setprio 0
	s_barrier
	ds_read_b128 v[162:165], v147 offset:49152
	ds_read_b128 v[166:169], v147 offset:50176
	ds_read_b128 v[170:173], v147 offset:51200
	ds_read_b128 v[186:189], v147 offset:52224
	ds_read_b128 v[198:201], v147 offset:53248
	ds_read_b128 v[202:205], v147 offset:54272
	ds_read_b128 v[222:225], v147 offset:55296
	ds_read_b128 v[146:149], v147 offset:56320
	s_barrier
	s_waitcnt lgkmcnt(0)
	s_setprio 1
	s_waitcnt lgkmcnt(7)
	v_mfma_f32_16x16x32_bf16 v[26:29], v[10:13], v[162:165], v[62:65]
	s_waitcnt lgkmcnt(6)
	v_mfma_f32_16x16x32_bf16 v[62:65], v[14:17], v[166:169], v[26:29]
	v_mfma_f32_16x16x32_bf16 v[26:29], v[178:181], v[162:165], v[58:61]
	v_mfma_f32_16x16x32_bf16 v[58:61], v[182:185], v[166:169], v[26:29]
	s_waitcnt lgkmcnt(5)
	v_mfma_f32_16x16x32_bf16 v[26:29], v[10:13], v[170:173], v[54:57]
	s_waitcnt lgkmcnt(4)
	v_mfma_f32_16x16x32_bf16 v[46:49], v[14:17], v[186:189], v[26:29]
	v_mfma_f32_16x16x32_bf16 v[26:29], v[178:181], v[170:173], v[50:53]
	v_mfma_f32_16x16x32_bf16 v[42:45], v[182:185], v[186:189], v[26:29]
	s_waitcnt lgkmcnt(3)
	v_mfma_f32_16x16x32_bf16 v[26:29], v[10:13], v[198:201], v[190:193]
	s_waitcnt lgkmcnt(1)
	v_mfma_f32_16x16x32_bf16 v[10:13], v[10:13], v[222:225], v[38:41]
	v_mfma_f32_16x16x32_bf16 v[30:33], v[14:17], v[202:205], v[26:29]
	v_mfma_f32_16x16x32_bf16 v[26:29], v[178:181], v[198:201], v[236:239]
	s_waitcnt lgkmcnt(0)
	v_mfma_f32_16x16x32_bf16 v[14:17], v[14:17], v[146:149], v[10:13]
	v_mfma_f32_16x16x32_bf16 v[10:13], v[178:181], v[222:225], v[34:37]
	v_mfma_f32_16x16x32_bf16 v[26:29], v[182:185], v[202:205], v[26:29]
	v_mfma_f32_16x16x32_bf16 v[10:13], v[182:185], v[146:149], v[10:13]
	s_setprio 0
	s_setprio 1
	v_mfma_f32_16x16x32_bf16 v[34:37], v[126:129], v[162:165], v[134:137]
	v_mfma_f32_16x16x32_bf16 v[54:57], v[158:161], v[166:169], v[34:37]
	v_mfma_f32_16x16x32_bf16 v[34:37], v[194:197], v[162:165], v[150:153]
	v_mfma_f32_16x16x32_bf16 v[18:21], v[194:197], v[170:173], v[18:21]
	v_mfma_f32_16x16x32_bf16 v[50:53], v[244:247], v[166:169], v[34:37]
	v_mfma_f32_16x16x32_bf16 v[22:25], v[126:129], v[170:173], v[22:25]
	v_mfma_f32_16x16x32_bf16 v[34:37], v[244:247], v[186:189], v[18:21]
	v_mfma_f32_16x16x32_bf16 v[18:21], v[126:129], v[198:201], v[154:157]
	v_mfma_f32_16x16x32_bf16 v[38:41], v[158:161], v[186:189], v[22:25]
	v_mfma_f32_16x16x32_bf16 v[22:25], v[158:161], v[202:205], v[18:21]
	v_mfma_f32_16x16x32_bf16 v[18:21], v[194:197], v[198:201], v[174:177]
	v_mfma_f32_16x16x32_bf16 v[6:9], v[126:129], v[222:225], v[6:9]
	v_mfma_f32_16x16x32_bf16 v[2:5], v[194:197], v[222:225], v[2:5]
	v_mfma_f32_16x16x32_bf16 v[18:21], v[244:247], v[202:205], v[18:21]
	v_mfma_f32_16x16x32_bf16 v[6:9], v[158:161], v[146:149], v[6:9]
	v_mfma_f32_16x16x32_bf16 v[2:5], v[244:247], v[146:149], v[2:5]
	s_setprio 0
	s_movk_i32 s0, 0x100
	v_cmp_gt_u32_e32 vcc, s0, v140
	s_barrier
	s_and_saveexec_b64 s[0:1], vcc
	s_cbranch_execz .LBB0_764
	s_barrier
